# adds: outproj K-loop rewritten the same way; residual epilogue of out-proj and down-proj de-serialised (all x/g loads issued up front, counted vmcnt, instead of 16 load-wait-store round trips)
# speedup vs baseline: 1.0533x; 1.0055x over previous
.LBB0_20:
	s_mov_b32 s18, 0x10000
	s_mov_b32 s19, 0
	v_lshl_add_u64 v[138:139], s[18:19], 0, v[132:133]
	s_mov_b32 s18, 0x20000
	s_mov_b32 s19, 0
	v_lshl_add_u64 v[172:173], s[18:19], 0, v[132:133]
	s_mov_b32 s18, 0x30000
	s_mov_b32 s19, 0
	v_lshl_add_u64 v[174:175], s[18:19], 0, v[132:133]
	s_mov_b32 s18, 0x10000
	s_mov_b32 s19, 0
	v_lshl_add_u64 v[176:177], s[18:19], 0, v[134:135]
	s_mov_b32 s18, 0x580000
	s_mov_b32 s19, 0
	v_lshl_add_u64 v[178:179], s[18:19], 0, v[134:135]
	s_mov_b32 s18, 0x590000
	s_mov_b32 s19, 0
	v_lshl_add_u64 v[180:181], s[18:19], 0, v[134:135]
	v_lshrrev_b32_e32 v168, 3, v0
	v_lshlrev_b32_e32 v169, 4, v0
	v_mul_u32_u24_e32 v168, 0x90, v168
	v_and_b32_e32 v169, 0x70, v169
	v_add_u32_e32 v182, v168, v169
	v_add_u32_e32 v183, 0x9000, v182
	v_lshrrev_b32_e32 v168, 1, v0
	v_and_b32_e32 v169, 31, v0
	v_and_b32_e32 v170, 16, v168
	v_and_b32_e32 v168, 64, v168
	v_add_u32_e32 v168, v168, v169
	v_mul_u32_u24_e32 v168, 0x90, v168
	v_add_u32_e32 v184, v168, v170
	v_and_b32_e32 v168, 64, v0
	v_add_u32_e32 v168, v168, v169
	v_mul_u32_u24_e32 v168, 0x90, v168
	v_add_u32_e32 v185, v168, v170
	s_barrier
	s_waitcnt vmcnt(15)
	ds_write_b128 v182, v[68:71]
	s_waitcnt vmcnt(13)
	ds_write_b128 v182, v[72:75] offset:4608
	s_waitcnt vmcnt(11)
	ds_write_b128 v182, v[76:79] offset:9216
	s_waitcnt vmcnt(9)
	ds_write_b128 v182, v[80:83] offset:13824
	s_waitcnt vmcnt(7)
	ds_write_b128 v182, v[84:87] offset:18432
	s_waitcnt vmcnt(5)
	ds_write_b128 v182, v[88:91] offset:23040
	s_waitcnt vmcnt(3)
	ds_write_b128 v182, v[92:95] offset:27648
	s_waitcnt vmcnt(1)
	ds_write_b128 v182, v[96:99] offset:32256
	global_load_dwordx4 v[68:71], v[132:133], off offset:256
	global_load_dwordx4 v[72:75], v[138:139], off offset:256
	global_load_dwordx4 v[76:79], v[172:173], off offset:256
	global_load_dwordx4 v[80:83], v[174:175], off offset:256
	global_load_dwordx4 v[84:87], v[134:135], off offset:256
	global_load_dwordx4 v[88:91], v[176:177], off offset:256
	global_load_dwordx4 v[92:95], v[178:179], off offset:256
	global_load_dwordx4 v[96:99], v[180:181], off offset:256
	s_waitcnt lgkmcnt(0)
	s_barrier
	ds_read_b128 v[140:143], v184
	ds_read_b128 v[144:147], v185 offset:18432
	ds_read_b128 v[148:151], v185 offset:23040
	ds_read_b128 v[152:155], v184 offset:4608
	ds_read_b128 v[156:159], v184 offset:32
	ds_read_b128 v[160:163], v185 offset:18464
	ds_read_b128 v[164:167], v185 offset:23072
	ds_read_b128 v[168:171], v184 offset:4640
	s_setprio 1
	s_waitcnt lgkmcnt(6)
	v_mfma_f32_32x32x16_bf16 v[52:67], v[144:147], v[140:143], 0
	ds_write_b128 v183, v[100:103]
	s_waitcnt lgkmcnt(6)
	v_mfma_f32_32x32x16_bf16 v[36:51], v[148:151], v[140:143], 0
	ds_write_b128 v183, v[104:107] offset:4608
	s_waitcnt lgkmcnt(6)
	v_mfma_f32_32x32x16_bf16 v[20:35], v[144:147], v[152:155], 0
	ds_write_b128 v183, v[108:111] offset:9216
	global_load_dwordx4 v[100:103], v[132:133], off offset:384
	v_mfma_f32_32x32x16_bf16 v[4:19], v[148:151], v[152:155], 0
	ds_read_b128 v[140:143], v184 offset:64
	ds_read_b128 v[144:147], v185 offset:18496
	s_waitcnt lgkmcnt(7)
	v_mfma_f32_32x32x16_bf16 v[52:67], v[160:163], v[156:159], v[52:67]
	ds_read_b128 v[148:151], v185 offset:23104
	ds_read_b128 v[152:155], v184 offset:4672
	s_waitcnt lgkmcnt(8)
	v_mfma_f32_32x32x16_bf16 v[36:51], v[164:167], v[156:159], v[36:51]
	ds_write_b128 v183, v[112:115] offset:13824
	global_load_dwordx4 v[104:107], v[138:139], off offset:384
	s_waitcnt lgkmcnt(8)
	v_mfma_f32_32x32x16_bf16 v[20:35], v[160:163], v[168:171], v[20:35]
	ds_write_b128 v183, v[116:119] offset:18432
	global_load_dwordx4 v[108:111], v[172:173], off offset:384
	v_mfma_f32_32x32x16_bf16 v[4:19], v[164:167], v[168:171], v[4:19]
	ds_read_b128 v[156:159], v184 offset:96
	ds_read_b128 v[160:163], v185 offset:18528
	s_waitcnt lgkmcnt(6)
	v_mfma_f32_32x32x16_bf16 v[52:67], v[144:147], v[140:143], v[52:67]
	ds_read_b128 v[164:167], v185 offset:23136
	ds_read_b128 v[168:171], v184 offset:4704
	s_waitcnt lgkmcnt(7)
	v_mfma_f32_32x32x16_bf16 v[36:51], v[148:151], v[140:143], v[36:51]
	ds_write_b128 v183, v[120:123] offset:23040
	global_load_dwordx4 v[112:115], v[174:175], off offset:384
	s_waitcnt lgkmcnt(7)
	v_mfma_f32_32x32x16_bf16 v[20:35], v[144:147], v[152:155], v[20:35]
	ds_write_b128 v183, v[124:127] offset:27648
	global_load_dwordx4 v[116:119], v[134:135], off offset:384
	v_mfma_f32_32x32x16_bf16 v[4:19], v[148:151], v[152:155], v[4:19]
	s_waitcnt vmcnt(13)
	ds_write_b128 v183, v[128:131] offset:32256
	global_load_dwordx4 v[120:123], v[176:177], off offset:384
	s_waitcnt lgkmcnt(5)
	v_mfma_f32_32x32x16_bf16 v[52:67], v[160:163], v[156:159], v[52:67]
	global_load_dwordx4 v[124:127], v[178:179], off offset:384
	s_waitcnt lgkmcnt(4)
	v_mfma_f32_32x32x16_bf16 v[36:51], v[164:167], v[156:159], v[36:51]
	global_load_dwordx4 v[128:131], v[180:181], off offset:384
	s_waitcnt lgkmcnt(3)
	v_mfma_f32_32x32x16_bf16 v[20:35], v[160:163], v[168:171], v[20:35]
	v_mfma_f32_32x32x16_bf16 v[4:19], v[164:167], v[168:171], v[4:19]
	s_setprio 0
	s_waitcnt lgkmcnt(0)
	s_barrier
	ds_read_b128 v[140:143], v184 offset:36864
	ds_read_b128 v[144:147], v185 offset:55296
	ds_read_b128 v[148:151], v185 offset:59904
	ds_read_b128 v[152:155], v184 offset:41472
	ds_read_b128 v[156:159], v184 offset:36896
	ds_read_b128 v[160:163], v185 offset:55328
	ds_read_b128 v[164:167], v185 offset:59936
	ds_read_b128 v[168:171], v184 offset:41504
	s_setprio 1
	s_waitcnt lgkmcnt(6)
	v_mfma_f32_32x32x16_bf16 v[52:67], v[144:147], v[140:143], v[52:67]
	s_waitcnt vmcnt(15)
	ds_write_b128 v182, v[68:71]
	s_waitcnt lgkmcnt(6)
	v_mfma_f32_32x32x16_bf16 v[36:51], v[148:151], v[140:143], v[36:51]
	s_waitcnt vmcnt(14)
	ds_write_b128 v182, v[72:75] offset:4608
	s_waitcnt lgkmcnt(6)
	v_mfma_f32_32x32x16_bf16 v[20:35], v[144:147], v[152:155], v[20:35]
	s_waitcnt vmcnt(13)
	ds_write_b128 v182, v[76:79] offset:9216
	global_load_dwordx4 v[68:71], v[132:133], off offset:512
	v_mfma_f32_32x32x16_bf16 v[4:19], v[148:151], v[152:155], v[4:19]
	ds_read_b128 v[140:143], v184 offset:36928
	ds_read_b128 v[144:147], v185 offset:55360
	s_waitcnt lgkmcnt(7)
	v_mfma_f32_32x32x16_bf16 v[52:67], v[160:163], v[156:159], v[52:67]
	ds_read_b128 v[148:151], v185 offset:59968
	ds_read_b128 v[152:155], v184 offset:41536
	s_waitcnt lgkmcnt(8)
	v_mfma_f32_32x32x16_bf16 v[36:51], v[164:167], v[156:159], v[36:51]
	s_waitcnt vmcnt(13)
	ds_write_b128 v182, v[80:83] offset:13824
	global_load_dwordx4 v[72:75], v[138:139], off offset:512
	s_waitcnt lgkmcnt(8)
	v_mfma_f32_32x32x16_bf16 v[20:35], v[160:163], v[168:171], v[20:35]
	s_waitcnt vmcnt(13)
	ds_write_b128 v182, v[84:87] offset:18432
	global_load_dwordx4 v[76:79], v[172:173], off offset:512
	v_mfma_f32_32x32x16_bf16 v[4:19], v[164:167], v[168:171], v[4:19]
	ds_read_b128 v[156:159], v184 offset:36960
	ds_read_b128 v[160:163], v185 offset:55392
	s_waitcnt lgkmcnt(6)
	v_mfma_f32_32x32x16_bf16 v[52:67], v[144:147], v[140:143], v[52:67]
	ds_read_b128 v[164:167], v185 offset:60000
	ds_read_b128 v[168:171], v184 offset:41568
	s_waitcnt lgkmcnt(7)
	v_mfma_f32_32x32x16_bf16 v[36:51], v[148:151], v[140:143], v[36:51]
	s_waitcnt vmcnt(13)
	ds_write_b128 v182, v[88:91] offset:23040
	global_load_dwordx4 v[80:83], v[174:175], off offset:512
	s_waitcnt lgkmcnt(7)
	v_mfma_f32_32x32x16_bf16 v[20:35], v[144:147], v[152:155], v[20:35]
	s_waitcnt vmcnt(13)
	ds_write_b128 v182, v[92:95] offset:27648
	global_load_dwordx4 v[84:87], v[134:135], off offset:512
	v_mfma_f32_32x32x16_bf16 v[4:19], v[148:151], v[152:155], v[4:19]
	s_waitcnt vmcnt(13)
	ds_write_b128 v182, v[96:99] offset:32256
	global_load_dwordx4 v[88:91], v[176:177], off offset:512
	s_waitcnt lgkmcnt(5)
	v_mfma_f32_32x32x16_bf16 v[52:67], v[160:163], v[156:159], v[52:67]
	global_load_dwordx4 v[92:95], v[178:179], off offset:512
	s_waitcnt lgkmcnt(4)
	v_mfma_f32_32x32x16_bf16 v[36:51], v[164:167], v[156:159], v[36:51]
	global_load_dwordx4 v[96:99], v[180:181], off offset:512
	s_waitcnt lgkmcnt(3)
	v_mfma_f32_32x32x16_bf16 v[20:35], v[160:163], v[168:171], v[20:35]
	v_mfma_f32_32x32x16_bf16 v[4:19], v[164:167], v[168:171], v[4:19]
	s_setprio 0
	s_waitcnt lgkmcnt(0)
	s_barrier
	ds_read_b128 v[140:143], v184
	ds_read_b128 v[144:147], v185 offset:18432
	ds_read_b128 v[148:151], v185 offset:23040
	ds_read_b128 v[152:155], v184 offset:4608
	ds_read_b128 v[156:159], v184 offset:32
	ds_read_b128 v[160:163], v185 offset:18464
	ds_read_b128 v[164:167], v185 offset:23072
	ds_read_b128 v[168:171], v184 offset:4640
	s_setprio 1
	s_waitcnt lgkmcnt(6)
	v_mfma_f32_32x32x16_bf16 v[52:67], v[144:147], v[140:143], v[52:67]
	s_waitcnt vmcnt(15)
	ds_write_b128 v183, v[100:103]
	s_waitcnt lgkmcnt(6)
	v_mfma_f32_32x32x16_bf16 v[36:51], v[148:151], v[140:143], v[36:51]
	s_waitcnt vmcnt(14)
	ds_write_b128 v183, v[104:107] offset:4608
	s_waitcnt lgkmcnt(6)
	v_mfma_f32_32x32x16_bf16 v[20:35], v[144:147], v[152:155], v[20:35]
	s_waitcnt vmcnt(13)
	ds_write_b128 v183, v[108:111] offset:9216
	global_load_dwordx4 v[100:103], v[132:133], off offset:640
	v_mfma_f32_32x32x16_bf16 v[4:19], v[148:151], v[152:155], v[4:19]
	ds_read_b128 v[140:143], v184 offset:64
	ds_read_b128 v[144:147], v185 offset:18496
	s_waitcnt lgkmcnt(7)
	v_mfma_f32_32x32x16_bf16 v[52:67], v[160:163], v[156:159], v[52:67]
	ds_read_b128 v[148:151], v185 offset:23104
	ds_read_b128 v[152:155], v184 offset:4672
	s_waitcnt lgkmcnt(8)
	v_mfma_f32_32x32x16_bf16 v[36:51], v[164:167], v[156:159], v[36:51]
	s_waitcnt vmcnt(13)
	ds_write_b128 v183, v[112:115] offset:13824
	global_load_dwordx4 v[104:107], v[138:139], off offset:640
	s_waitcnt lgkmcnt(8)
	v_mfma_f32_32x32x16_bf16 v[20:35], v[160:163], v[168:171], v[20:35]
	s_waitcnt vmcnt(13)
	ds_write_b128 v183, v[116:119] offset:18432
	global_load_dwordx4 v[108:111], v[172:173], off offset:640
	v_mfma_f32_32x32x16_bf16 v[4:19], v[164:167], v[168:171], v[4:19]
	ds_read_b128 v[156:159], v184 offset:96
	ds_read_b128 v[160:163], v185 offset:18528
	s_waitcnt lgkmcnt(6)
	v_mfma_f32_32x32x16_bf16 v[52:67], v[144:147], v[140:143], v[52:67]
	ds_read_b128 v[164:167], v185 offset:23136
	ds_read_b128 v[168:171], v184 offset:4704
	s_waitcnt lgkmcnt(7)
	v_mfma_f32_32x32x16_bf16 v[36:51], v[148:151], v[140:143], v[36:51]
	s_waitcnt vmcnt(13)
	ds_write_b128 v183, v[120:123] offset:23040
	global_load_dwordx4 v[112:115], v[174:175], off offset:640
	s_waitcnt lgkmcnt(7)
	v_mfma_f32_32x32x16_bf16 v[20:35], v[144:147], v[152:155], v[20:35]
	s_waitcnt vmcnt(13)
	ds_write_b128 v183, v[124:127] offset:27648
	global_load_dwordx4 v[116:119], v[134:135], off offset:640
	v_mfma_f32_32x32x16_bf16 v[4:19], v[148:151], v[152:155], v[4:19]
	s_waitcnt vmcnt(13)
	ds_write_b128 v183, v[128:131] offset:32256
	global_load_dwordx4 v[120:123], v[176:177], off offset:640
	s_waitcnt lgkmcnt(5)
	v_mfma_f32_32x32x16_bf16 v[52:67], v[160:163], v[156:159], v[52:67]
	global_load_dwordx4 v[124:127], v[178:179], off offset:640
	s_waitcnt lgkmcnt(4)
	v_mfma_f32_32x32x16_bf16 v[36:51], v[164:167], v[156:159], v[36:51]
	global_load_dwordx4 v[128:131], v[180:181], off offset:640
	s_waitcnt lgkmcnt(3)
	v_mfma_f32_32x32x16_bf16 v[20:35], v[160:163], v[168:171], v[20:35]
	v_mfma_f32_32x32x16_bf16 v[4:19], v[164:167], v[168:171], v[4:19]
	s_setprio 0
	s_waitcnt lgkmcnt(0)
	s_barrier
	ds_read_b128 v[140:143], v184 offset:36864
	ds_read_b128 v[144:147], v185 offset:55296
	ds_read_b128 v[148:151], v185 offset:59904
	ds_read_b128 v[152:155], v184 offset:41472
	ds_read_b128 v[156:159], v184 offset:36896
	ds_read_b128 v[160:163], v185 offset:55328
	ds_read_b128 v[164:167], v185 offset:59936
	ds_read_b128 v[168:171], v184 offset:41504
	s_setprio 1
	s_waitcnt lgkmcnt(6)
	v_mfma_f32_32x32x16_bf16 v[52:67], v[144:147], v[140:143], v[52:67]
	s_waitcnt vmcnt(15)
	ds_write_b128 v182, v[68:71]
	s_waitcnt lgkmcnt(6)
	v_mfma_f32_32x32x16_bf16 v[36:51], v[148:151], v[140:143], v[36:51]
	s_waitcnt vmcnt(14)
	ds_write_b128 v182, v[72:75] offset:4608
	s_waitcnt lgkmcnt(6)
	v_mfma_f32_32x32x16_bf16 v[20:35], v[144:147], v[152:155], v[20:35]
	s_waitcnt vmcnt(13)
	ds_write_b128 v182, v[76:79] offset:9216
	global_load_dwordx4 v[68:71], v[132:133], off offset:768
	v_mfma_f32_32x32x16_bf16 v[4:19], v[148:151], v[152:155], v[4:19]
	ds_read_b128 v[140:143], v184 offset:36928
	ds_read_b128 v[144:147], v185 offset:55360
	s_waitcnt lgkmcnt(7)
	v_mfma_f32_32x32x16_bf16 v[52:67], v[160:163], v[156:159], v[52:67]
	ds_read_b128 v[148:151], v185 offset:59968
	ds_read_b128 v[152:155], v184 offset:41536
	s_waitcnt lgkmcnt(8)
	v_mfma_f32_32x32x16_bf16 v[36:51], v[164:167], v[156:159], v[36:51]
	s_waitcnt vmcnt(13)
	ds_write_b128 v182, v[80:83] offset:13824
	global_load_dwordx4 v[72:75], v[138:139], off offset:768
	s_waitcnt lgkmcnt(8)
	v_mfma_f32_32x32x16_bf16 v[20:35], v[160:163], v[168:171], v[20:35]
	s_waitcnt vmcnt(13)
	ds_write_b128 v182, v[84:87] offset:18432
	global_load_dwordx4 v[76:79], v[172:173], off offset:768
	v_mfma_f32_32x32x16_bf16 v[4:19], v[164:167], v[168:171], v[4:19]
	ds_read_b128 v[156:159], v184 offset:36960
	ds_read_b128 v[160:163], v185 offset:55392
	s_waitcnt lgkmcnt(6)
	v_mfma_f32_32x32x16_bf16 v[52:67], v[144:147], v[140:143], v[52:67]
	ds_read_b128 v[164:167], v185 offset:60000
	ds_read_b128 v[168:171], v184 offset:41568
	s_waitcnt lgkmcnt(7)
	v_mfma_f32_32x32x16_bf16 v[36:51], v[148:151], v[140:143], v[36:51]
	s_waitcnt vmcnt(13)
	ds_write_b128 v182, v[88:91] offset:23040
	global_load_dwordx4 v[80:83], v[174:175], off offset:768
	s_waitcnt lgkmcnt(7)
	v_mfma_f32_32x32x16_bf16 v[20:35], v[144:147], v[152:155], v[20:35]
	s_waitcnt vmcnt(13)
	ds_write_b128 v182, v[92:95] offset:27648
	global_load_dwordx4 v[84:87], v[134:135], off offset:768
	v_mfma_f32_32x32x16_bf16 v[4:19], v[148:151], v[152:155], v[4:19]
	s_waitcnt vmcnt(13)
	ds_write_b128 v182, v[96:99] offset:32256
	global_load_dwordx4 v[88:91], v[176:177], off offset:768
	s_waitcnt lgkmcnt(5)
	v_mfma_f32_32x32x16_bf16 v[52:67], v[160:163], v[156:159], v[52:67]
	global_load_dwordx4 v[92:95], v[178:179], off offset:768
	s_waitcnt lgkmcnt(4)
	v_mfma_f32_32x32x16_bf16 v[36:51], v[164:167], v[156:159], v[36:51]
	global_load_dwordx4 v[96:99], v[180:181], off offset:768
	s_waitcnt lgkmcnt(3)
	v_mfma_f32_32x32x16_bf16 v[20:35], v[160:163], v[168:171], v[20:35]
	v_mfma_f32_32x32x16_bf16 v[4:19], v[164:167], v[168:171], v[4:19]
	s_setprio 0
	s_waitcnt lgkmcnt(0)
	s_barrier
	ds_read_b128 v[140:143], v184
	ds_read_b128 v[144:147], v185 offset:18432
	ds_read_b128 v[148:151], v185 offset:23040
	ds_read_b128 v[152:155], v184 offset:4608
	ds_read_b128 v[156:159], v184 offset:32
	ds_read_b128 v[160:163], v185 offset:18464
	ds_read_b128 v[164:167], v185 offset:23072
	ds_read_b128 v[168:171], v184 offset:4640
	s_setprio 1
	s_waitcnt lgkmcnt(6)
	v_mfma_f32_32x32x16_bf16 v[52:67], v[144:147], v[140:143], v[52:67]
	s_waitcnt vmcnt(15)
	ds_write_b128 v183, v[100:103]
	s_waitcnt lgkmcnt(6)
	v_mfma_f32_32x32x16_bf16 v[36:51], v[148:151], v[140:143], v[36:51]
	s_waitcnt vmcnt(14)
	ds_write_b128 v183, v[104:107] offset:4608
	s_waitcnt lgkmcnt(6)
	v_mfma_f32_32x32x16_bf16 v[20:35], v[144:147], v[152:155], v[20:35]
	s_waitcnt vmcnt(13)
	ds_write_b128 v183, v[108:111] offset:9216
	global_load_dwordx4 v[100:103], v[132:133], off offset:896
	v_mfma_f32_32x32x16_bf16 v[4:19], v[148:151], v[152:155], v[4:19]
	ds_read_b128 v[140:143], v184 offset:64
	ds_read_b128 v[144:147], v185 offset:18496
	s_waitcnt lgkmcnt(7)
	v_mfma_f32_32x32x16_bf16 v[52:67], v[160:163], v[156:159], v[52:67]
	ds_read_b128 v[148:151], v185 offset:23104
	ds_read_b128 v[152:155], v184 offset:4672
	s_waitcnt lgkmcnt(8)
	v_mfma_f32_32x32x16_bf16 v[36:51], v[164:167], v[156:159], v[36:51]
	s_waitcnt vmcnt(13)
	ds_write_b128 v183, v[112:115] offset:13824
	global_load_dwordx4 v[104:107], v[138:139], off offset:896
	s_waitcnt lgkmcnt(8)
	v_mfma_f32_32x32x16_bf16 v[20:35], v[160:163], v[168:171], v[20:35]
	s_waitcnt vmcnt(13)
	ds_write_b128 v183, v[116:119] offset:18432
	global_load_dwordx4 v[108:111], v[172:173], off offset:896
	v_mfma_f32_32x32x16_bf16 v[4:19], v[164:167], v[168:171], v[4:19]
	ds_read_b128 v[156:159], v184 offset:96
	ds_read_b128 v[160:163], v185 offset:18528
	s_waitcnt lgkmcnt(6)
	v_mfma_f32_32x32x16_bf16 v[52:67], v[144:147], v[140:143], v[52:67]
	ds_read_b128 v[164:167], v185 offset:23136
	ds_read_b128 v[168:171], v184 offset:4704
	s_waitcnt lgkmcnt(7)
	v_mfma_f32_32x32x16_bf16 v[36:51], v[148:151], v[140:143], v[36:51]
	s_waitcnt vmcnt(13)
	ds_write_b128 v183, v[120:123] offset:23040
	global_load_dwordx4 v[112:115], v[174:175], off offset:896
	s_waitcnt lgkmcnt(7)
	v_mfma_f32_32x32x16_bf16 v[20:35], v[144:147], v[152:155], v[20:35]
	s_waitcnt vmcnt(13)
	ds_write_b128 v183, v[124:127] offset:27648
	global_load_dwordx4 v[116:119], v[134:135], off offset:896
	v_mfma_f32_32x32x16_bf16 v[4:19], v[148:151], v[152:155], v[4:19]
	s_waitcnt vmcnt(13)
	ds_write_b128 v183, v[128:131] offset:32256
	global_load_dwordx4 v[120:123], v[176:177], off offset:896
	s_waitcnt lgkmcnt(5)
	v_mfma_f32_32x32x16_bf16 v[52:67], v[160:163], v[156:159], v[52:67]
	global_load_dwordx4 v[124:127], v[178:179], off offset:896
	s_waitcnt lgkmcnt(4)
	v_mfma_f32_32x32x16_bf16 v[36:51], v[164:167], v[156:159], v[36:51]
	global_load_dwordx4 v[128:131], v[180:181], off offset:896
	s_waitcnt lgkmcnt(3)
	v_mfma_f32_32x32x16_bf16 v[20:35], v[160:163], v[168:171], v[20:35]
	v_mfma_f32_32x32x16_bf16 v[4:19], v[164:167], v[168:171], v[4:19]
	s_setprio 0
	s_waitcnt lgkmcnt(0)
	s_barrier
	ds_read_b128 v[140:143], v184 offset:36864
	ds_read_b128 v[144:147], v185 offset:55296
	ds_read_b128 v[148:151], v185 offset:59904
	ds_read_b128 v[152:155], v184 offset:41472
	ds_read_b128 v[156:159], v184 offset:36896
	ds_read_b128 v[160:163], v185 offset:55328
	ds_read_b128 v[164:167], v185 offset:59936
	ds_read_b128 v[168:171], v184 offset:41504
	s_setprio 1
	s_waitcnt lgkmcnt(6)
	v_mfma_f32_32x32x16_bf16 v[52:67], v[144:147], v[140:143], v[52:67]
	s_waitcnt vmcnt(15)
	ds_write_b128 v182, v[68:71]
	s_waitcnt lgkmcnt(6)
	v_mfma_f32_32x32x16_bf16 v[36:51], v[148:151], v[140:143], v[36:51]
	s_waitcnt vmcnt(14)
	ds_write_b128 v182, v[72:75] offset:4608
	s_waitcnt lgkmcnt(6)
	v_mfma_f32_32x32x16_bf16 v[20:35], v[144:147], v[152:155], v[20:35]
	s_waitcnt vmcnt(13)
	ds_write_b128 v182, v[76:79] offset:9216
	global_load_dwordx4 v[68:71], v[132:133], off offset:1024
	v_mfma_f32_32x32x16_bf16 v[4:19], v[148:151], v[152:155], v[4:19]
	ds_read_b128 v[140:143], v184 offset:36928
	ds_read_b128 v[144:147], v185 offset:55360
	s_waitcnt lgkmcnt(7)
	v_mfma_f32_32x32x16_bf16 v[52:67], v[160:163], v[156:159], v[52:67]
	ds_read_b128 v[148:151], v185 offset:59968
	ds_read_b128 v[152:155], v184 offset:41536
	s_waitcnt lgkmcnt(8)
	v_mfma_f32_32x32x16_bf16 v[36:51], v[164:167], v[156:159], v[36:51]
	s_waitcnt vmcnt(13)
	ds_write_b128 v182, v[80:83] offset:13824
	global_load_dwordx4 v[72:75], v[138:139], off offset:1024
	s_waitcnt lgkmcnt(8)
	v_mfma_f32_32x32x16_bf16 v[20:35], v[160:163], v[168:171], v[20:35]
	s_waitcnt vmcnt(13)
	ds_write_b128 v182, v[84:87] offset:18432
	global_load_dwordx4 v[76:79], v[172:173], off offset:1024
	v_mfma_f32_32x32x16_bf16 v[4:19], v[164:167], v[168:171], v[4:19]
	ds_read_b128 v[156:159], v184 offset:36960
	ds_read_b128 v[160:163], v185 offset:55392
	s_waitcnt lgkmcnt(6)
	v_mfma_f32_32x32x16_bf16 v[52:67], v[144:147], v[140:143], v[52:67]
	ds_read_b128 v[164:167], v185 offset:60000
	ds_read_b128 v[168:171], v184 offset:41568
	s_waitcnt lgkmcnt(7)
	v_mfma_f32_32x32x16_bf16 v[36:51], v[148:151], v[140:143], v[36:51]
	s_waitcnt vmcnt(13)
	ds_write_b128 v182, v[88:91] offset:23040
	global_load_dwordx4 v[80:83], v[174:175], off offset:1024
	s_waitcnt lgkmcnt(7)
	v_mfma_f32_32x32x16_bf16 v[20:35], v[144:147], v[152:155], v[20:35]
	s_waitcnt vmcnt(13)
	ds_write_b128 v182, v[92:95] offset:27648
	global_load_dwordx4 v[84:87], v[134:135], off offset:1024
	v_mfma_f32_32x32x16_bf16 v[4:19], v[148:151], v[152:155], v[4:19]
	s_waitcnt vmcnt(13)
	ds_write_b128 v182, v[96:99] offset:32256
	global_load_dwordx4 v[88:91], v[176:177], off offset:1024
	s_waitcnt lgkmcnt(5)
	v_mfma_f32_32x32x16_bf16 v[52:67], v[160:163], v[156:159], v[52:67]
	global_load_dwordx4 v[92:95], v[178:179], off offset:1024
	s_waitcnt lgkmcnt(4)
	v_mfma_f32_32x32x16_bf16 v[36:51], v[164:167], v[156:159], v[36:51]
	global_load_dwordx4 v[96:99], v[180:181], off offset:1024
	s_waitcnt lgkmcnt(3)
	v_mfma_f32_32x32x16_bf16 v[20:35], v[160:163], v[168:171], v[20:35]
	v_mfma_f32_32x32x16_bf16 v[4:19], v[164:167], v[168:171], v[4:19]
	s_setprio 0
	s_waitcnt lgkmcnt(0)
	s_barrier
	ds_read_b128 v[140:143], v184
	ds_read_b128 v[144:147], v185 offset:18432
	ds_read_b128 v[148:151], v185 offset:23040
	ds_read_b128 v[152:155], v184 offset:4608
	ds_read_b128 v[156:159], v184 offset:32
	ds_read_b128 v[160:163], v185 offset:18464
	ds_read_b128 v[164:167], v185 offset:23072
	ds_read_b128 v[168:171], v184 offset:4640
	s_setprio 1
	s_waitcnt lgkmcnt(6)
	v_mfma_f32_32x32x16_bf16 v[52:67], v[144:147], v[140:143], v[52:67]
	s_waitcnt vmcnt(15)
	ds_write_b128 v183, v[100:103]
	s_waitcnt lgkmcnt(6)
	v_mfma_f32_32x32x16_bf16 v[36:51], v[148:151], v[140:143], v[36:51]
	s_waitcnt vmcnt(14)
	ds_write_b128 v183, v[104:107] offset:4608
	s_waitcnt lgkmcnt(6)
	v_mfma_f32_32x32x16_bf16 v[20:35], v[144:147], v[152:155], v[20:35]
	s_waitcnt vmcnt(13)
	ds_write_b128 v183, v[108:111] offset:9216
	global_load_dwordx4 v[100:103], v[132:133], off offset:1152
	v_mfma_f32_32x32x16_bf16 v[4:19], v[148:151], v[152:155], v[4:19]
	ds_read_b128 v[140:143], v184 offset:64
	ds_read_b128 v[144:147], v185 offset:18496
	s_waitcnt lgkmcnt(7)
	v_mfma_f32_32x32x16_bf16 v[52:67], v[160:163], v[156:159], v[52:67]
	ds_read_b128 v[148:151], v185 offset:23104
	ds_read_b128 v[152:155], v184 offset:4672
	s_waitcnt lgkmcnt(8)
	v_mfma_f32_32x32x16_bf16 v[36:51], v[164:167], v[156:159], v[36:51]
	s_waitcnt vmcnt(13)
	ds_write_b128 v183, v[112:115] offset:13824
	global_load_dwordx4 v[104:107], v[138:139], off offset:1152
	s_waitcnt lgkmcnt(8)
	v_mfma_f32_32x32x16_bf16 v[20:35], v[160:163], v[168:171], v[20:35]
	s_waitcnt vmcnt(13)
	ds_write_b128 v183, v[116:119] offset:18432
	global_load_dwordx4 v[108:111], v[172:173], off offset:1152
	v_mfma_f32_32x32x16_bf16 v[4:19], v[164:167], v[168:171], v[4:19]
	ds_read_b128 v[156:159], v184 offset:96
	ds_read_b128 v[160:163], v185 offset:18528
	s_waitcnt lgkmcnt(6)
	v_mfma_f32_32x32x16_bf16 v[52:67], v[144:147], v[140:143], v[52:67]
	ds_read_b128 v[164:167], v185 offset:23136
	ds_read_b128 v[168:171], v184 offset:4704
	s_waitcnt lgkmcnt(7)
	v_mfma_f32_32x32x16_bf16 v[36:51], v[148:151], v[140:143], v[36:51]
	s_waitcnt vmcnt(13)
	ds_write_b128 v183, v[120:123] offset:23040
	global_load_dwordx4 v[112:115], v[174:175], off offset:1152
	s_waitcnt lgkmcnt(7)
	v_mfma_f32_32x32x16_bf16 v[20:35], v[144:147], v[152:155], v[20:35]
	s_waitcnt vmcnt(13)
	ds_write_b128 v183, v[124:127] offset:27648
	global_load_dwordx4 v[116:119], v[134:135], off offset:1152
	v_mfma_f32_32x32x16_bf16 v[4:19], v[148:151], v[152:155], v[4:19]
	s_waitcnt vmcnt(13)
	ds_write_b128 v183, v[128:131] offset:32256
	global_load_dwordx4 v[120:123], v[176:177], off offset:1152
	s_waitcnt lgkmcnt(5)
	v_mfma_f32_32x32x16_bf16 v[52:67], v[160:163], v[156:159], v[52:67]
	global_load_dwordx4 v[124:127], v[178:179], off offset:1152
	s_waitcnt lgkmcnt(4)
	v_mfma_f32_32x32x16_bf16 v[36:51], v[164:167], v[156:159], v[36:51]
	global_load_dwordx4 v[128:131], v[180:181], off offset:1152
	s_waitcnt lgkmcnt(3)
	v_mfma_f32_32x32x16_bf16 v[20:35], v[160:163], v[168:171], v[20:35]
	v_mfma_f32_32x32x16_bf16 v[4:19], v[164:167], v[168:171], v[4:19]
	s_setprio 0
	s_waitcnt lgkmcnt(0)
	s_barrier
	ds_read_b128 v[140:143], v184 offset:36864
	ds_read_b128 v[144:147], v185 offset:55296
	ds_read_b128 v[148:151], v185 offset:59904
	ds_read_b128 v[152:155], v184 offset:41472
	ds_read_b128 v[156:159], v184 offset:36896
	ds_read_b128 v[160:163], v185 offset:55328
	ds_read_b128 v[164:167], v185 offset:59936
	ds_read_b128 v[168:171], v184 offset:41504
	s_setprio 1
	s_waitcnt lgkmcnt(6)
	v_mfma_f32_32x32x16_bf16 v[52:67], v[144:147], v[140:143], v[52:67]
	s_waitcnt vmcnt(15)
	ds_write_b128 v182, v[68:71]
	s_waitcnt lgkmcnt(6)
	v_mfma_f32_32x32x16_bf16 v[36:51], v[148:151], v[140:143], v[36:51]
	s_waitcnt vmcnt(14)
	ds_write_b128 v182, v[72:75] offset:4608
	s_waitcnt lgkmcnt(6)
	v_mfma_f32_32x32x16_bf16 v[20:35], v[144:147], v[152:155], v[20:35]
	s_waitcnt vmcnt(13)
	ds_write_b128 v182, v[76:79] offset:9216
	global_load_dwordx4 v[68:71], v[132:133], off offset:1280
	v_mfma_f32_32x32x16_bf16 v[4:19], v[148:151], v[152:155], v[4:19]
	ds_read_b128 v[140:143], v184 offset:36928
	ds_read_b128 v[144:147], v185 offset:55360
	s_waitcnt lgkmcnt(7)
	v_mfma_f32_32x32x16_bf16 v[52:67], v[160:163], v[156:159], v[52:67]
	ds_read_b128 v[148:151], v185 offset:59968
	ds_read_b128 v[152:155], v184 offset:41536
	s_waitcnt lgkmcnt(8)
	v_mfma_f32_32x32x16_bf16 v[36:51], v[164:167], v[156:159], v[36:51]
	s_waitcnt vmcnt(13)
	ds_write_b128 v182, v[80:83] offset:13824
	global_load_dwordx4 v[72:75], v[138:139], off offset:1280
	s_waitcnt lgkmcnt(8)
	v_mfma_f32_32x32x16_bf16 v[20:35], v[160:163], v[168:171], v[20:35]
	s_waitcnt vmcnt(13)
	ds_write_b128 v182, v[84:87] offset:18432
	global_load_dwordx4 v[76:79], v[172:173], off offset:1280
	v_mfma_f32_32x32x16_bf16 v[4:19], v[164:167], v[168:171], v[4:19]
	ds_read_b128 v[156:159], v184 offset:36960
	ds_read_b128 v[160:163], v185 offset:55392
	s_waitcnt lgkmcnt(6)
	v_mfma_f32_32x32x16_bf16 v[52:67], v[144:147], v[140:143], v[52:67]
	ds_read_b128 v[164:167], v185 offset:60000
	ds_read_b128 v[168:171], v184 offset:41568
	s_waitcnt lgkmcnt(7)
	v_mfma_f32_32x32x16_bf16 v[36:51], v[148:151], v[140:143], v[36:51]
	s_waitcnt vmcnt(13)
	ds_write_b128 v182, v[88:91] offset:23040
	global_load_dwordx4 v[80:83], v[174:175], off offset:1280
	s_waitcnt lgkmcnt(7)
	v_mfma_f32_32x32x16_bf16 v[20:35], v[144:147], v[152:155], v[20:35]
	s_waitcnt vmcnt(13)
	ds_write_b128 v182, v[92:95] offset:27648
	global_load_dwordx4 v[84:87], v[134:135], off offset:1280
	v_mfma_f32_32x32x16_bf16 v[4:19], v[148:151], v[152:155], v[4:19]
	s_waitcnt vmcnt(13)
	ds_write_b128 v182, v[96:99] offset:32256
	global_load_dwordx4 v[88:91], v[176:177], off offset:1280
	s_waitcnt lgkmcnt(5)
	v_mfma_f32_32x32x16_bf16 v[52:67], v[160:163], v[156:159], v[52:67]
	global_load_dwordx4 v[92:95], v[178:179], off offset:1280
	s_waitcnt lgkmcnt(4)
	v_mfma_f32_32x32x16_bf16 v[36:51], v[164:167], v[156:159], v[36:51]
	global_load_dwordx4 v[96:99], v[180:181], off offset:1280
	s_waitcnt lgkmcnt(3)
	v_mfma_f32_32x32x16_bf16 v[20:35], v[160:163], v[168:171], v[20:35]
	v_mfma_f32_32x32x16_bf16 v[4:19], v[164:167], v[168:171], v[4:19]
	s_setprio 0
	s_waitcnt lgkmcnt(0)
	s_barrier
	ds_read_b128 v[140:143], v184
	ds_read_b128 v[144:147], v185 offset:18432
	ds_read_b128 v[148:151], v185 offset:23040
	ds_read_b128 v[152:155], v184 offset:4608
	ds_read_b128 v[156:159], v184 offset:32
	ds_read_b128 v[160:163], v185 offset:18464
	ds_read_b128 v[164:167], v185 offset:23072
	ds_read_b128 v[168:171], v184 offset:4640
	s_setprio 1
	s_waitcnt lgkmcnt(6)
	v_mfma_f32_32x32x16_bf16 v[52:67], v[144:147], v[140:143], v[52:67]
	s_waitcnt vmcnt(15)
	ds_write_b128 v183, v[100:103]
	s_waitcnt lgkmcnt(6)
	v_mfma_f32_32x32x16_bf16 v[36:51], v[148:151], v[140:143], v[36:51]
	s_waitcnt vmcnt(14)
	ds_write_b128 v183, v[104:107] offset:4608
	s_waitcnt lgkmcnt(6)
	v_mfma_f32_32x32x16_bf16 v[20:35], v[144:147], v[152:155], v[20:35]
	s_waitcnt vmcnt(13)
	ds_write_b128 v183, v[108:111] offset:9216
	global_load_dwordx4 v[100:103], v[132:133], off offset:1408
	v_mfma_f32_32x32x16_bf16 v[4:19], v[148:151], v[152:155], v[4:19]
	ds_read_b128 v[140:143], v184 offset:64
	ds_read_b128 v[144:147], v185 offset:18496
	s_waitcnt lgkmcnt(7)
	v_mfma_f32_32x32x16_bf16 v[52:67], v[160:163], v[156:159], v[52:67]
	ds_read_b128 v[148:151], v185 offset:23104
	ds_read_b128 v[152:155], v184 offset:4672
	s_waitcnt lgkmcnt(8)
	v_mfma_f32_32x32x16_bf16 v[36:51], v[164:167], v[156:159], v[36:51]
	s_waitcnt vmcnt(13)
	ds_write_b128 v183, v[112:115] offset:13824
	global_load_dwordx4 v[104:107], v[138:139], off offset:1408
	s_waitcnt lgkmcnt(8)
	v_mfma_f32_32x32x16_bf16 v[20:35], v[160:163], v[168:171], v[20:35]
	s_waitcnt vmcnt(13)
	ds_write_b128 v183, v[116:119] offset:18432
	global_load_dwordx4 v[108:111], v[172:173], off offset:1408
	v_mfma_f32_32x32x16_bf16 v[4:19], v[164:167], v[168:171], v[4:19]
	ds_read_b128 v[156:159], v184 offset:96
	ds_read_b128 v[160:163], v185 offset:18528
	s_waitcnt lgkmcnt(6)
	v_mfma_f32_32x32x16_bf16 v[52:67], v[144:147], v[140:143], v[52:67]
	ds_read_b128 v[164:167], v185 offset:23136
	ds_read_b128 v[168:171], v184 offset:4704
	s_waitcnt lgkmcnt(7)
	v_mfma_f32_32x32x16_bf16 v[36:51], v[148:151], v[140:143], v[36:51]
	s_waitcnt vmcnt(13)
	ds_write_b128 v183, v[120:123] offset:23040
	global_load_dwordx4 v[112:115], v[174:175], off offset:1408
	s_waitcnt lgkmcnt(7)
	v_mfma_f32_32x32x16_bf16 v[20:35], v[144:147], v[152:155], v[20:35]
	s_waitcnt vmcnt(13)
	ds_write_b128 v183, v[124:127] offset:27648
	global_load_dwordx4 v[116:119], v[134:135], off offset:1408
	v_mfma_f32_32x32x16_bf16 v[4:19], v[148:151], v[152:155], v[4:19]
	s_waitcnt vmcnt(13)
	ds_write_b128 v183, v[128:131] offset:32256
	global_load_dwordx4 v[120:123], v[176:177], off offset:1408
	s_waitcnt lgkmcnt(5)
	v_mfma_f32_32x32x16_bf16 v[52:67], v[160:163], v[156:159], v[52:67]
	global_load_dwordx4 v[124:127], v[178:179], off offset:1408
	s_waitcnt lgkmcnt(4)
	v_mfma_f32_32x32x16_bf16 v[36:51], v[164:167], v[156:159], v[36:51]
	global_load_dwordx4 v[128:131], v[180:181], off offset:1408
	s_waitcnt lgkmcnt(3)
	v_mfma_f32_32x32x16_bf16 v[20:35], v[160:163], v[168:171], v[20:35]
	v_mfma_f32_32x32x16_bf16 v[4:19], v[164:167], v[168:171], v[4:19]
	s_setprio 0
	s_waitcnt lgkmcnt(0)
	s_barrier
	ds_read_b128 v[140:143], v184 offset:36864
	ds_read_b128 v[144:147], v185 offset:55296
	ds_read_b128 v[148:151], v185 offset:59904
	ds_read_b128 v[152:155], v184 offset:41472
	ds_read_b128 v[156:159], v184 offset:36896
	ds_read_b128 v[160:163], v185 offset:55328
	ds_read_b128 v[164:167], v185 offset:59936
	ds_read_b128 v[168:171], v184 offset:41504
	s_setprio 1
	s_waitcnt lgkmcnt(6)
	v_mfma_f32_32x32x16_bf16 v[52:67], v[144:147], v[140:143], v[52:67]
	s_waitcnt vmcnt(15)
	ds_write_b128 v182, v[68:71]
	s_waitcnt lgkmcnt(6)
	v_mfma_f32_32x32x16_bf16 v[36:51], v[148:151], v[140:143], v[36:51]
	s_waitcnt vmcnt(14)
	ds_write_b128 v182, v[72:75] offset:4608
	s_waitcnt lgkmcnt(6)
	v_mfma_f32_32x32x16_bf16 v[20:35], v[144:147], v[152:155], v[20:35]
	s_waitcnt vmcnt(13)
	ds_write_b128 v182, v[76:79] offset:9216
	global_load_dwordx4 v[68:71], v[132:133], off offset:1536
	v_mfma_f32_32x32x16_bf16 v[4:19], v[148:151], v[152:155], v[4:19]
	ds_read_b128 v[140:143], v184 offset:36928
	ds_read_b128 v[144:147], v185 offset:55360
	s_waitcnt lgkmcnt(7)
	v_mfma_f32_32x32x16_bf16 v[52:67], v[160:163], v[156:159], v[52:67]
	ds_read_b128 v[148:151], v185 offset:59968
	ds_read_b128 v[152:155], v184 offset:41536
	s_waitcnt lgkmcnt(8)
	v_mfma_f32_32x32x16_bf16 v[36:51], v[164:167], v[156:159], v[36:51]
	s_waitcnt vmcnt(13)
	ds_write_b128 v182, v[80:83] offset:13824
	global_load_dwordx4 v[72:75], v[138:139], off offset:1536
	s_waitcnt lgkmcnt(8)
	v_mfma_f32_32x32x16_bf16 v[20:35], v[160:163], v[168:171], v[20:35]
	s_waitcnt vmcnt(13)
	ds_write_b128 v182, v[84:87] offset:18432
	global_load_dwordx4 v[76:79], v[172:173], off offset:1536
	v_mfma_f32_32x32x16_bf16 v[4:19], v[164:167], v[168:171], v[4:19]
	ds_read_b128 v[156:159], v184 offset:36960
	ds_read_b128 v[160:163], v185 offset:55392
	s_waitcnt lgkmcnt(6)
	v_mfma_f32_32x32x16_bf16 v[52:67], v[144:147], v[140:143], v[52:67]
	ds_read_b128 v[164:167], v185 offset:60000
	ds_read_b128 v[168:171], v184 offset:41568
	s_waitcnt lgkmcnt(7)
	v_mfma_f32_32x32x16_bf16 v[36:51], v[148:151], v[140:143], v[36:51]
	s_waitcnt vmcnt(13)
	ds_write_b128 v182, v[88:91] offset:23040
	global_load_dwordx4 v[80:83], v[174:175], off offset:1536
	s_waitcnt lgkmcnt(7)
	v_mfma_f32_32x32x16_bf16 v[20:35], v[144:147], v[152:155], v[20:35]
	s_waitcnt vmcnt(13)
	ds_write_b128 v182, v[92:95] offset:27648
	global_load_dwordx4 v[84:87], v[134:135], off offset:1536
	v_mfma_f32_32x32x16_bf16 v[4:19], v[148:151], v[152:155], v[4:19]
	s_waitcnt vmcnt(13)
	ds_write_b128 v182, v[96:99] offset:32256
	global_load_dwordx4 v[88:91], v[176:177], off offset:1536
	s_waitcnt lgkmcnt(5)
	v_mfma_f32_32x32x16_bf16 v[52:67], v[160:163], v[156:159], v[52:67]
	global_load_dwordx4 v[92:95], v[178:179], off offset:1536
	s_waitcnt lgkmcnt(4)
	v_mfma_f32_32x32x16_bf16 v[36:51], v[164:167], v[156:159], v[36:51]
	global_load_dwordx4 v[96:99], v[180:181], off offset:1536
	s_waitcnt lgkmcnt(3)
	v_mfma_f32_32x32x16_bf16 v[20:35], v[160:163], v[168:171], v[20:35]
	v_mfma_f32_32x32x16_bf16 v[4:19], v[164:167], v[168:171], v[4:19]
	s_setprio 0
	s_waitcnt lgkmcnt(0)
	s_barrier
	ds_read_b128 v[140:143], v184
	ds_read_b128 v[144:147], v185 offset:18432
	ds_read_b128 v[148:151], v185 offset:23040
	ds_read_b128 v[152:155], v184 offset:4608
	ds_read_b128 v[156:159], v184 offset:32
	ds_read_b128 v[160:163], v185 offset:18464
	ds_read_b128 v[164:167], v185 offset:23072
	ds_read_b128 v[168:171], v184 offset:4640
	s_setprio 1
	s_waitcnt lgkmcnt(6)
	v_mfma_f32_32x32x16_bf16 v[52:67], v[144:147], v[140:143], v[52:67]
	s_waitcnt vmcnt(15)
	ds_write_b128 v183, v[100:103]
	s_waitcnt lgkmcnt(6)
	v_mfma_f32_32x32x16_bf16 v[36:51], v[148:151], v[140:143], v[36:51]
	s_waitcnt vmcnt(14)
	ds_write_b128 v183, v[104:107] offset:4608
	s_waitcnt lgkmcnt(6)
	v_mfma_f32_32x32x16_bf16 v[20:35], v[144:147], v[152:155], v[20:35]
	s_waitcnt vmcnt(13)
	ds_write_b128 v183, v[108:111] offset:9216
	global_load_dwordx4 v[100:103], v[132:133], off offset:1664
	v_mfma_f32_32x32x16_bf16 v[4:19], v[148:151], v[152:155], v[4:19]
	ds_read_b128 v[140:143], v184 offset:64
	ds_read_b128 v[144:147], v185 offset:18496
	s_waitcnt lgkmcnt(7)
	v_mfma_f32_32x32x16_bf16 v[52:67], v[160:163], v[156:159], v[52:67]
	ds_read_b128 v[148:151], v185 offset:23104
	ds_read_b128 v[152:155], v184 offset:4672
	s_waitcnt lgkmcnt(8)
	v_mfma_f32_32x32x16_bf16 v[36:51], v[164:167], v[156:159], v[36:51]
	s_waitcnt vmcnt(13)
	ds_write_b128 v183, v[112:115] offset:13824
	global_load_dwordx4 v[104:107], v[138:139], off offset:1664
	s_waitcnt lgkmcnt(8)
	v_mfma_f32_32x32x16_bf16 v[20:35], v[160:163], v[168:171], v[20:35]
	s_waitcnt vmcnt(13)
	ds_write_b128 v183, v[116:119] offset:18432
	global_load_dwordx4 v[108:111], v[172:173], off offset:1664
	v_mfma_f32_32x32x16_bf16 v[4:19], v[164:167], v[168:171], v[4:19]
	ds_read_b128 v[156:159], v184 offset:96
	ds_read_b128 v[160:163], v185 offset:18528
	s_waitcnt lgkmcnt(6)
	v_mfma_f32_32x32x16_bf16 v[52:67], v[144:147], v[140:143], v[52:67]
	ds_read_b128 v[164:167], v185 offset:23136
	ds_read_b128 v[168:171], v184 offset:4704
	s_waitcnt lgkmcnt(7)
	v_mfma_f32_32x32x16_bf16 v[36:51], v[148:151], v[140:143], v[36:51]
	s_waitcnt vmcnt(13)
	ds_write_b128 v183, v[120:123] offset:23040
	global_load_dwordx4 v[112:115], v[174:175], off offset:1664
	s_waitcnt lgkmcnt(7)
	v_mfma_f32_32x32x16_bf16 v[20:35], v[144:147], v[152:155], v[20:35]
	s_waitcnt vmcnt(13)
	ds_write_b128 v183, v[124:127] offset:27648
	global_load_dwordx4 v[116:119], v[134:135], off offset:1664
	v_mfma_f32_32x32x16_bf16 v[4:19], v[148:151], v[152:155], v[4:19]
	s_waitcnt vmcnt(13)
	ds_write_b128 v183, v[128:131] offset:32256
	global_load_dwordx4 v[120:123], v[176:177], off offset:1664
	s_waitcnt lgkmcnt(5)
	v_mfma_f32_32x32x16_bf16 v[52:67], v[160:163], v[156:159], v[52:67]
	global_load_dwordx4 v[124:127], v[178:179], off offset:1664
	s_waitcnt lgkmcnt(4)
	v_mfma_f32_32x32x16_bf16 v[36:51], v[164:167], v[156:159], v[36:51]
	global_load_dwordx4 v[128:131], v[180:181], off offset:1664
	s_waitcnt lgkmcnt(3)
	v_mfma_f32_32x32x16_bf16 v[20:35], v[160:163], v[168:171], v[20:35]
	v_mfma_f32_32x32x16_bf16 v[4:19], v[164:167], v[168:171], v[4:19]
	s_setprio 0
	s_waitcnt lgkmcnt(0)
	s_barrier
	ds_read_b128 v[140:143], v184 offset:36864
	ds_read_b128 v[144:147], v185 offset:55296
	ds_read_b128 v[148:151], v185 offset:59904
	ds_read_b128 v[152:155], v184 offset:41472
	ds_read_b128 v[156:159], v184 offset:36896
	ds_read_b128 v[160:163], v185 offset:55328
	ds_read_b128 v[164:167], v185 offset:59936
	ds_read_b128 v[168:171], v184 offset:41504
	s_setprio 1
	s_waitcnt lgkmcnt(6)
	v_mfma_f32_32x32x16_bf16 v[52:67], v[144:147], v[140:143], v[52:67]
	s_waitcnt vmcnt(15)
	ds_write_b128 v182, v[68:71]
	s_waitcnt lgkmcnt(6)
	v_mfma_f32_32x32x16_bf16 v[36:51], v[148:151], v[140:143], v[36:51]
	s_waitcnt vmcnt(14)
	ds_write_b128 v182, v[72:75] offset:4608
	s_waitcnt lgkmcnt(6)
	v_mfma_f32_32x32x16_bf16 v[20:35], v[144:147], v[152:155], v[20:35]
	s_waitcnt vmcnt(13)
	ds_write_b128 v182, v[76:79] offset:9216
	global_load_dwordx4 v[68:71], v[132:133], off offset:1792
	v_mfma_f32_32x32x16_bf16 v[4:19], v[148:151], v[152:155], v[4:19]
	ds_read_b128 v[140:143], v184 offset:36928
	ds_read_b128 v[144:147], v185 offset:55360
	s_waitcnt lgkmcnt(7)
	v_mfma_f32_32x32x16_bf16 v[52:67], v[160:163], v[156:159], v[52:67]
	ds_read_b128 v[148:151], v185 offset:59968
	ds_read_b128 v[152:155], v184 offset:41536
	s_waitcnt lgkmcnt(8)
	v_mfma_f32_32x32x16_bf16 v[36:51], v[164:167], v[156:159], v[36:51]
	s_waitcnt vmcnt(13)
	ds_write_b128 v182, v[80:83] offset:13824
	global_load_dwordx4 v[72:75], v[138:139], off offset:1792
	s_waitcnt lgkmcnt(8)
	v_mfma_f32_32x32x16_bf16 v[20:35], v[160:163], v[168:171], v[20:35]
	s_waitcnt vmcnt(13)
	ds_write_b128 v182, v[84:87] offset:18432
	global_load_dwordx4 v[76:79], v[172:173], off offset:1792
	v_mfma_f32_32x32x16_bf16 v[4:19], v[164:167], v[168:171], v[4:19]
	ds_read_b128 v[156:159], v184 offset:36960
	ds_read_b128 v[160:163], v185 offset:55392
	s_waitcnt lgkmcnt(6)
	v_mfma_f32_32x32x16_bf16 v[52:67], v[144:147], v[140:143], v[52:67]
	ds_read_b128 v[164:167], v185 offset:60000
	ds_read_b128 v[168:171], v184 offset:41568
	s_waitcnt lgkmcnt(7)
	v_mfma_f32_32x32x16_bf16 v[36:51], v[148:151], v[140:143], v[36:51]
	s_waitcnt vmcnt(13)
	ds_write_b128 v182, v[88:91] offset:23040
	global_load_dwordx4 v[80:83], v[174:175], off offset:1792
	s_waitcnt lgkmcnt(7)
	v_mfma_f32_32x32x16_bf16 v[20:35], v[144:147], v[152:155], v[20:35]
	s_waitcnt vmcnt(13)
	ds_write_b128 v182, v[92:95] offset:27648
	global_load_dwordx4 v[84:87], v[134:135], off offset:1792
	v_mfma_f32_32x32x16_bf16 v[4:19], v[148:151], v[152:155], v[4:19]
	s_waitcnt vmcnt(13)
	ds_write_b128 v182, v[96:99] offset:32256
	global_load_dwordx4 v[88:91], v[176:177], off offset:1792
	s_waitcnt lgkmcnt(5)
	v_mfma_f32_32x32x16_bf16 v[52:67], v[160:163], v[156:159], v[52:67]
	global_load_dwordx4 v[92:95], v[178:179], off offset:1792
	s_waitcnt lgkmcnt(4)
	v_mfma_f32_32x32x16_bf16 v[36:51], v[164:167], v[156:159], v[36:51]
	global_load_dwordx4 v[96:99], v[180:181], off offset:1792
	s_waitcnt lgkmcnt(3)
	v_mfma_f32_32x32x16_bf16 v[20:35], v[160:163], v[168:171], v[20:35]
	v_mfma_f32_32x32x16_bf16 v[4:19], v[164:167], v[168:171], v[4:19]
	s_setprio 0
	s_waitcnt lgkmcnt(0)
	s_barrier
	ds_read_b128 v[140:143], v184
	ds_read_b128 v[144:147], v185 offset:18432
	ds_read_b128 v[148:151], v185 offset:23040
	ds_read_b128 v[152:155], v184 offset:4608
	ds_read_b128 v[156:159], v184 offset:32
	ds_read_b128 v[160:163], v185 offset:18464
	ds_read_b128 v[164:167], v185 offset:23072
	ds_read_b128 v[168:171], v184 offset:4640
	s_setprio 1
	s_waitcnt lgkmcnt(6)
	v_mfma_f32_32x32x16_bf16 v[52:67], v[144:147], v[140:143], v[52:67]
	s_waitcnt vmcnt(15)
	ds_write_b128 v183, v[100:103]
	s_waitcnt lgkmcnt(6)
	v_mfma_f32_32x32x16_bf16 v[36:51], v[148:151], v[140:143], v[36:51]
	s_waitcnt vmcnt(14)
	ds_write_b128 v183, v[104:107] offset:4608
	s_waitcnt lgkmcnt(6)
	v_mfma_f32_32x32x16_bf16 v[20:35], v[144:147], v[152:155], v[20:35]
	s_waitcnt vmcnt(13)
	ds_write_b128 v183, v[108:111] offset:9216
	global_load_dwordx4 v[100:103], v[132:133], off offset:1920
	v_mfma_f32_32x32x16_bf16 v[4:19], v[148:151], v[152:155], v[4:19]
	ds_read_b128 v[140:143], v184 offset:64
	ds_read_b128 v[144:147], v185 offset:18496
	s_waitcnt lgkmcnt(7)
	v_mfma_f32_32x32x16_bf16 v[52:67], v[160:163], v[156:159], v[52:67]
	ds_read_b128 v[148:151], v185 offset:23104
	ds_read_b128 v[152:155], v184 offset:4672
	s_waitcnt lgkmcnt(8)
	v_mfma_f32_32x32x16_bf16 v[36:51], v[164:167], v[156:159], v[36:51]
	s_waitcnt vmcnt(13)
	ds_write_b128 v183, v[112:115] offset:13824
	global_load_dwordx4 v[104:107], v[138:139], off offset:1920
	s_waitcnt lgkmcnt(8)
	v_mfma_f32_32x32x16_bf16 v[20:35], v[160:163], v[168:171], v[20:35]
	s_waitcnt vmcnt(13)
	ds_write_b128 v183, v[116:119] offset:18432
	global_load_dwordx4 v[108:111], v[172:173], off offset:1920
	v_mfma_f32_32x32x16_bf16 v[4:19], v[164:167], v[168:171], v[4:19]
	ds_read_b128 v[156:159], v184 offset:96
	ds_read_b128 v[160:163], v185 offset:18528
	s_waitcnt lgkmcnt(6)
	v_mfma_f32_32x32x16_bf16 v[52:67], v[144:147], v[140:143], v[52:67]
	ds_read_b128 v[164:167], v185 offset:23136
	ds_read_b128 v[168:171], v184 offset:4704
	s_waitcnt lgkmcnt(7)
	v_mfma_f32_32x32x16_bf16 v[36:51], v[148:151], v[140:143], v[36:51]
	s_waitcnt vmcnt(13)
	ds_write_b128 v183, v[120:123] offset:23040
	global_load_dwordx4 v[112:115], v[174:175], off offset:1920
	s_waitcnt lgkmcnt(7)
	v_mfma_f32_32x32x16_bf16 v[20:35], v[144:147], v[152:155], v[20:35]
	s_waitcnt vmcnt(13)
	ds_write_b128 v183, v[124:127] offset:27648
	global_load_dwordx4 v[116:119], v[134:135], off offset:1920
	v_mfma_f32_32x32x16_bf16 v[4:19], v[148:151], v[152:155], v[4:19]
	s_waitcnt vmcnt(13)
	ds_write_b128 v183, v[128:131] offset:32256
	global_load_dwordx4 v[120:123], v[176:177], off offset:1920
	s_waitcnt lgkmcnt(5)
	v_mfma_f32_32x32x16_bf16 v[52:67], v[160:163], v[156:159], v[52:67]
	global_load_dwordx4 v[124:127], v[178:179], off offset:1920
	s_waitcnt lgkmcnt(4)
	v_mfma_f32_32x32x16_bf16 v[36:51], v[164:167], v[156:159], v[36:51]
	global_load_dwordx4 v[128:131], v[180:181], off offset:1920
	s_waitcnt lgkmcnt(3)
	v_mfma_f32_32x32x16_bf16 v[20:35], v[160:163], v[168:171], v[20:35]
	v_mfma_f32_32x32x16_bf16 v[4:19], v[164:167], v[168:171], v[4:19]
	s_setprio 0
	s_waitcnt lgkmcnt(0)
	s_barrier
	ds_read_b128 v[140:143], v184 offset:36864
	ds_read_b128 v[144:147], v185 offset:55296
	ds_read_b128 v[148:151], v185 offset:59904
	ds_read_b128 v[152:155], v184 offset:41472
	ds_read_b128 v[156:159], v184 offset:36896
	ds_read_b128 v[160:163], v185 offset:55328
	ds_read_b128 v[164:167], v185 offset:59936
	ds_read_b128 v[168:171], v184 offset:41504
	s_setprio 1
	s_waitcnt lgkmcnt(6)
	v_mfma_f32_32x32x16_bf16 v[52:67], v[144:147], v[140:143], v[52:67]
	s_waitcnt vmcnt(15)
	ds_write_b128 v182, v[68:71]
	s_waitcnt lgkmcnt(6)
	v_mfma_f32_32x32x16_bf16 v[36:51], v[148:151], v[140:143], v[36:51]
	s_waitcnt vmcnt(14)
	ds_write_b128 v182, v[72:75] offset:4608
	s_waitcnt lgkmcnt(6)
	v_mfma_f32_32x32x16_bf16 v[20:35], v[144:147], v[152:155], v[20:35]
	s_waitcnt vmcnt(13)
	ds_write_b128 v182, v[76:79] offset:9216
	v_mfma_f32_32x32x16_bf16 v[4:19], v[148:151], v[152:155], v[4:19]
	ds_read_b128 v[140:143], v184 offset:36928
	ds_read_b128 v[144:147], v185 offset:55360
	s_waitcnt lgkmcnt(7)
	v_mfma_f32_32x32x16_bf16 v[52:67], v[160:163], v[156:159], v[52:67]
	ds_read_b128 v[148:151], v185 offset:59968
	ds_read_b128 v[152:155], v184 offset:41536
	s_waitcnt lgkmcnt(8)
	v_mfma_f32_32x32x16_bf16 v[36:51], v[164:167], v[156:159], v[36:51]
	s_waitcnt vmcnt(12)
	ds_write_b128 v182, v[80:83] offset:13824
	s_waitcnt lgkmcnt(8)
	v_mfma_f32_32x32x16_bf16 v[20:35], v[160:163], v[168:171], v[20:35]
	s_waitcnt vmcnt(11)
	ds_write_b128 v182, v[84:87] offset:18432
	v_mfma_f32_32x32x16_bf16 v[4:19], v[164:167], v[168:171], v[4:19]
	ds_read_b128 v[156:159], v184 offset:36960
	ds_read_b128 v[160:163], v185 offset:55392
	s_waitcnt lgkmcnt(6)
	v_mfma_f32_32x32x16_bf16 v[52:67], v[144:147], v[140:143], v[52:67]
	ds_read_b128 v[164:167], v185 offset:60000
	ds_read_b128 v[168:171], v184 offset:41568
	s_waitcnt lgkmcnt(7)
	v_mfma_f32_32x32x16_bf16 v[36:51], v[148:151], v[140:143], v[36:51]
	s_waitcnt vmcnt(10)
	ds_write_b128 v182, v[88:91] offset:23040
	s_waitcnt lgkmcnt(7)
	v_mfma_f32_32x32x16_bf16 v[20:35], v[144:147], v[152:155], v[20:35]
	s_waitcnt vmcnt(9)
	ds_write_b128 v182, v[92:95] offset:27648
	v_mfma_f32_32x32x16_bf16 v[4:19], v[148:151], v[152:155], v[4:19]
	s_waitcnt vmcnt(8)
	ds_write_b128 v182, v[96:99] offset:32256
	s_waitcnt lgkmcnt(5)
	v_mfma_f32_32x32x16_bf16 v[52:67], v[160:163], v[156:159], v[52:67]
	s_waitcnt lgkmcnt(4)
	v_mfma_f32_32x32x16_bf16 v[36:51], v[164:167], v[156:159], v[36:51]
	s_waitcnt lgkmcnt(3)
	v_mfma_f32_32x32x16_bf16 v[20:35], v[160:163], v[168:171], v[20:35]
	v_mfma_f32_32x32x16_bf16 v[4:19], v[164:167], v[168:171], v[4:19]
	s_setprio 0
	s_waitcnt lgkmcnt(0)
	s_barrier
	ds_read_b128 v[140:143], v184
	ds_read_b128 v[144:147], v185 offset:18432
	ds_read_b128 v[148:151], v185 offset:23040
	ds_read_b128 v[152:155], v184 offset:4608
	ds_read_b128 v[156:159], v184 offset:32
	ds_read_b128 v[160:163], v185 offset:18464
	ds_read_b128 v[164:167], v185 offset:23072
	ds_read_b128 v[168:171], v184 offset:4640
	s_setprio 1
	s_waitcnt lgkmcnt(6)
	v_mfma_f32_32x32x16_bf16 v[52:67], v[144:147], v[140:143], v[52:67]
	s_waitcnt vmcnt(7)
	ds_write_b128 v183, v[100:103]
	s_waitcnt lgkmcnt(6)
	v_mfma_f32_32x32x16_bf16 v[36:51], v[148:151], v[140:143], v[36:51]
	s_waitcnt vmcnt(6)
	ds_write_b128 v183, v[104:107] offset:4608
	s_waitcnt lgkmcnt(6)
	v_mfma_f32_32x32x16_bf16 v[20:35], v[144:147], v[152:155], v[20:35]
	s_waitcnt vmcnt(5)
	ds_write_b128 v183, v[108:111] offset:9216
	v_mfma_f32_32x32x16_bf16 v[4:19], v[148:151], v[152:155], v[4:19]
	ds_read_b128 v[140:143], v184 offset:64
	ds_read_b128 v[144:147], v185 offset:18496
	s_waitcnt lgkmcnt(7)
	v_mfma_f32_32x32x16_bf16 v[52:67], v[160:163], v[156:159], v[52:67]
	ds_read_b128 v[148:151], v185 offset:23104
	ds_read_b128 v[152:155], v184 offset:4672
	s_waitcnt lgkmcnt(8)
	v_mfma_f32_32x32x16_bf16 v[36:51], v[164:167], v[156:159], v[36:51]
	s_waitcnt vmcnt(4)
	ds_write_b128 v183, v[112:115] offset:13824
	s_waitcnt lgkmcnt(8)
	v_mfma_f32_32x32x16_bf16 v[20:35], v[160:163], v[168:171], v[20:35]
	s_waitcnt vmcnt(3)
	ds_write_b128 v183, v[116:119] offset:18432
	v_mfma_f32_32x32x16_bf16 v[4:19], v[164:167], v[168:171], v[4:19]
	ds_read_b128 v[156:159], v184 offset:96
	ds_read_b128 v[160:163], v185 offset:18528
	s_waitcnt lgkmcnt(6)
	v_mfma_f32_32x32x16_bf16 v[52:67], v[144:147], v[140:143], v[52:67]
	ds_read_b128 v[164:167], v185 offset:23136
	ds_read_b128 v[168:171], v184 offset:4704
	s_waitcnt lgkmcnt(7)
	v_mfma_f32_32x32x16_bf16 v[36:51], v[148:151], v[140:143], v[36:51]
	s_waitcnt vmcnt(2)
	ds_write_b128 v183, v[120:123] offset:23040
	s_waitcnt lgkmcnt(7)
	v_mfma_f32_32x32x16_bf16 v[20:35], v[144:147], v[152:155], v[20:35]
	s_waitcnt vmcnt(1)
	ds_write_b128 v183, v[124:127] offset:27648
	v_mfma_f32_32x32x16_bf16 v[4:19], v[148:151], v[152:155], v[4:19]
	s_waitcnt vmcnt(0)
	ds_write_b128 v183, v[128:131] offset:32256
	s_waitcnt lgkmcnt(5)
	v_mfma_f32_32x32x16_bf16 v[52:67], v[160:163], v[156:159], v[52:67]
	s_waitcnt lgkmcnt(4)
	v_mfma_f32_32x32x16_bf16 v[36:51], v[164:167], v[156:159], v[36:51]
	s_waitcnt lgkmcnt(3)
	v_mfma_f32_32x32x16_bf16 v[20:35], v[160:163], v[168:171], v[20:35]
	v_mfma_f32_32x32x16_bf16 v[4:19], v[164:167], v[168:171], v[4:19]
	s_setprio 0
	s_waitcnt lgkmcnt(0)
	s_barrier
	ds_read_b128 v[140:143], v184 offset:36864
	ds_read_b128 v[144:147], v185 offset:55296
	ds_read_b128 v[148:151], v185 offset:59904
	ds_read_b128 v[152:155], v184 offset:41472
	ds_read_b128 v[156:159], v184 offset:36896
	ds_read_b128 v[160:163], v185 offset:55328
	ds_read_b128 v[164:167], v185 offset:59936
	ds_read_b128 v[168:171], v184 offset:41504
	s_setprio 1
	s_waitcnt lgkmcnt(6)
	v_mfma_f32_32x32x16_bf16 v[52:67], v[144:147], v[140:143], v[52:67]
	s_waitcnt lgkmcnt(5)
	v_mfma_f32_32x32x16_bf16 v[36:51], v[148:151], v[140:143], v[36:51]
	s_waitcnt lgkmcnt(4)
	v_mfma_f32_32x32x16_bf16 v[20:35], v[144:147], v[152:155], v[20:35]
	v_mfma_f32_32x32x16_bf16 v[4:19], v[148:151], v[152:155], v[4:19]
	ds_read_b128 v[140:143], v184 offset:36928
	ds_read_b128 v[144:147], v185 offset:55360
	s_waitcnt lgkmcnt(4)
	v_mfma_f32_32x32x16_bf16 v[52:67], v[160:163], v[156:159], v[52:67]
	ds_read_b128 v[148:151], v185 offset:59968
	ds_read_b128 v[152:155], v184 offset:41536
	s_waitcnt lgkmcnt(5)
	v_mfma_f32_32x32x16_bf16 v[36:51], v[164:167], v[156:159], v[36:51]
	s_waitcnt lgkmcnt(4)
	v_mfma_f32_32x32x16_bf16 v[20:35], v[160:163], v[168:171], v[20:35]
	v_mfma_f32_32x32x16_bf16 v[4:19], v[164:167], v[168:171], v[4:19]
	ds_read_b128 v[156:159], v184 offset:36960
	ds_read_b128 v[160:163], v185 offset:55392
	s_waitcnt lgkmcnt(4)
	v_mfma_f32_32x32x16_bf16 v[52:67], v[144:147], v[140:143], v[52:67]
	ds_read_b128 v[164:167], v185 offset:60000
	ds_read_b128 v[168:171], v184 offset:41568
	s_waitcnt lgkmcnt(5)
	v_mfma_f32_32x32x16_bf16 v[36:51], v[148:151], v[140:143], v[36:51]
	s_waitcnt lgkmcnt(4)
	v_mfma_f32_32x32x16_bf16 v[20:35], v[144:147], v[152:155], v[20:35]
	v_mfma_f32_32x32x16_bf16 v[4:19], v[148:151], v[152:155], v[4:19]
	s_waitcnt lgkmcnt(2)
	v_mfma_f32_32x32x16_bf16 v[52:67], v[160:163], v[156:159], v[52:67]
	s_waitcnt lgkmcnt(1)
	v_mfma_f32_32x32x16_bf16 v[36:51], v[164:167], v[156:159], v[36:51]
	s_waitcnt lgkmcnt(0)
	v_mfma_f32_32x32x16_bf16 v[20:35], v[160:163], v[168:171], v[20:35]
	v_mfma_f32_32x32x16_bf16 v[4:19], v[164:167], v[168:171], v[4:19]
	s_setprio 0
	s_nop 7
	s_nop 4
	s_barrier
	s_load_dword s34, s[62:63], 0x0
	s_waitcnt lgkmcnt(0)
	s_add_i32 s34, s34, s21
	s_cmpk_gt_i32 s34, 0xaff
	s_cselect_b64 s[18:19], -1, 0
	s_and_b64 vcc, exec, s[18:19]
	s_cbranch_vccnz .LBB0_22
	s_lshl_b32 s20, s34, 18
	v_readlane_b32 s24, v252, 47
	v_mov_b32_e32 v2, v0
	s_and_b32 s20, s20, 0xfc0000
	v_readlane_b32 s30, v252, 53
	v_readlane_b32 s31, v252, 54
	v_ashrrev_i32_e32 v68, 3, v2
	s_add_u32 s22, s30, s20
	v_ashrrev_i32_e32 v69, 31, v68
	s_addc_u32 s23, s31, 0
	v_lshlrev_b64 v[68:69], 11, v[68:69]
	v_lshlrev_b32_e32 v2, 4, v2
	v_lshl_add_u64 v[70:71], s[22:23], 0, v[68:69]
	v_and_b32_e32 v2, 0x70, v2
	v_readlane_b32 s25, v252, 48
	s_ashr_i32 s24, s34, 6
	v_lshl_add_u64 v[132:133], v[70:71], 0, v[2:3]
	s_ashr_i32 s25, s24, 31
	v_add_co_u32_e32 v76, vcc, s33, v132
	s_lshl_b64 s[24:25], s[24:25], 17
	s_nop 0
	v_addc_co_u32_e32 v77, vcc, 0, v133, vcc
	s_add_u32 s24, s37, s24
	v_add_co_u32_e32 v80, vcc, s78, v132
	s_addc_u32 s25, s40, s25
	s_nop 0
	v_addc_co_u32_e32 v81, vcc, 0, v133, vcc
	v_lshl_add_u64 v[68:69], s[24:25], 0, v[68:69]
	v_add_co_u32_e32 v84, vcc, s79, v132
	v_lshl_add_u64 v[134:135], v[68:69], 0, v[2:3]
	s_nop 0
	v_addc_co_u32_e32 v85, vcc, 0, v133, vcc
	v_add_co_u32_e32 v92, vcc, s33, v134
	v_readlane_b32 s26, v252, 49
	s_nop 0
	v_addc_co_u32_e32 v93, vcc, 0, v135, vcc
	v_add_co_u32_e32 v96, vcc, 0x580000, v134
	v_readlane_b32 s27, v252, 50
	s_nop 0
	v_addc_co_u32_e32 v97, vcc, 0, v135, vcc
	v_add_co_u32_e32 v128, vcc, 0x590000, v134
	v_readlane_b32 s28, v252, 51
	s_nop 0
	v_addc_co_u32_e32 v129, vcc, 0, v135, vcc
	global_load_dwordx4 v[68:71], v[132:133], off
	global_load_dwordx4 v[100:103], v[132:133], off offset:128
	global_load_dwordx4 v[72:75], v[76:77], off
	global_load_dwordx4 v[104:107], v[76:77], off offset:128
	s_nop 0
	global_load_dwordx4 v[76:79], v[80:81], off
	global_load_dwordx4 v[108:111], v[80:81], off offset:128
	s_nop 0
	global_load_dwordx4 v[80:83], v[84:85], off
	global_load_dwordx4 v[112:115], v[84:85], off offset:128
	s_nop 0
	global_load_dwordx4 v[84:87], v[134:135], off
	global_load_dwordx4 v[116:119], v[134:135], off offset:128
	global_load_dwordx4 v[88:91], v[92:93], off
	global_load_dwordx4 v[120:123], v[92:93], off offset:128
	s_nop 0
	global_load_dwordx4 v[92:95], v[96:97], off
	global_load_dwordx4 v[124:127], v[96:97], off offset:128
	s_nop 0
	global_load_dwordx4 v[96:99], v[128:129], off
	s_nop 0
	global_load_dwordx4 v[128:131], v[128:129], off offset:128
	v_readlane_b32 s29, v252, 52

.LBB0_50:
	s_lshr_b32 s7, s42, 11
	s_add_i32 s7, s7, 1
	s_and_b64 s[0:1], s[0:1], exec
	s_cselect_b32 s0, 0, s7
	s_mul_i32 s1, s94, 3
	v_mov_b32_e32 v2, v0
	s_add_u32 s0, s1, s0
	s_mul_hi_i32 s1, s94, 3
	s_addc_u32 s1, s1, 0
	v_and_b32_e32 v86, 31, v2
	v_and_b32_e32 v68, 64, v2
	v_lshrrev_b32_e32 v69, 3, v2
	v_ashrrev_i32_e32 v2, 1, v2
	s_mulk_i32 s1, 0x6000
	s_mul_hi_u32 s7, s0, 0x6000
	v_readlane_b32 s16, v251, 7
	v_and_b32_e32 v2, 0xffffffc0, v2
	s_add_i32 s7, s7, s1
	s_mulk_i32 s0, 0x6000
	v_readlane_b32 s18, v251, 9
	v_and_b32_e32 v69, 4, v69
	v_or_b32_e32 v78, v2, v86
	v_readlane_b32 s19, v251, 10
	s_add_u32 s0, s18, s0
	v_or3_b32 v76, v68, v69, s6
	v_ashrrev_i32_e32 v79, 31, v78
	s_addc_u32 s1, s19, s7
	v_lshlrev_b64 v[68:69], 12, v[78:79]
	v_ashrrev_i32_e32 v77, 31, v76
	s_add_u32 s0, s0, 0x2000
	v_lshl_add_u64 v[68:69], s[8:9], 0, v[68:69]
	v_lshlrev_b64 v[80:81], 2, v[76:77]
	s_addc_u32 s1, s1, 0
	v_lshl_add_u64 v[82:83], v[68:69], 0, v[80:81]
	v_lshl_add_u64 v[84:85], s[0:1], 0, v[80:81]
	v_or_b32_e32 v77, s15, v86
	v_add_u32_e32 v86, v77, v2
	v_ashrrev_i32_e32 v87, 31, v86
	v_lshlrev_b64 v[88:89], 12, v[86:87]
	v_lshl_add_u64 v[88:89], s[70:71], 0, v[88:89]
	v_lshl_add_u64 v[88:89], v[88:89], 0, v[80:81]
	v_readlane_b32 s17, v251, 8
	v_add_co_u32_e32 v70, vcc, 0x20000, v82
	s_nop 1
	v_addc_co_u32_e32 v71, vcc, 0, v83, vcc
	v_add_co_u32_e32 v90, vcc, 0x20000, v88
	s_nop 1
	v_addc_co_u32_e32 v91, vcc, 0, v89, vcc
	global_load_dwordx4 v[136:139], v[82:83], off
	global_load_dwordx4 v[140:143], v[82:83], off offset:32
	global_load_dwordx4 v[144:147], v[82:83], off offset:64
	global_load_dwordx4 v[148:151], v[82:83], off offset:96
	global_load_dwordx4 v[152:155], v[82:83], off offset:128
	global_load_dwordx4 v[156:159], v[82:83], off offset:160
	global_load_dwordx4 v[160:163], v[82:83], off offset:192
	global_load_dwordx4 v[164:167], v[82:83], off offset:224
	global_load_dwordx4 v[72:75], v[84:85], off
	global_load_dwordx4 v[92:95], v[84:85], off offset:32
	global_load_dwordx4 v[96:99], v[84:85], off offset:64
	global_load_dwordx4 v[100:103], v[84:85], off offset:96
	global_load_dwordx4 v[120:123], v[84:85], off offset:128
	global_load_dwordx4 v[124:127], v[84:85], off offset:160
	global_load_dwordx4 v[128:131], v[84:85], off offset:192
	global_load_dwordx4 v[132:135], v[84:85], off offset:224
	global_load_dwordx4 v[168:171], v[70:71], off
	global_load_dwordx4 v[172:175], v[70:71], off offset:32
	global_load_dwordx4 v[176:179], v[70:71], off offset:64
	global_load_dwordx4 v[180:183], v[70:71], off offset:96
	s_waitcnt vmcnt(11)
	v_pk_fma_f32 v[136:137], v[52:53], v[72:73], v[136:137]
	v_pk_fma_f32 v[138:139], v[54:55], v[74:75], v[138:139]
	global_store_dwordx4 v[88:89], v[136:139], off
	s_waitcnt vmcnt(11)
	v_pk_fma_f32 v[140:141], v[56:57], v[92:93], v[140:141]
	v_pk_fma_f32 v[142:143], v[58:59], v[94:95], v[142:143]
	global_store_dwordx4 v[88:89], v[140:143], off offset:32
	s_waitcnt vmcnt(11)
	v_pk_fma_f32 v[144:145], v[60:61], v[96:97], v[144:145]
	v_pk_fma_f32 v[146:147], v[62:63], v[98:99], v[146:147]
	global_store_dwordx4 v[88:89], v[144:147], off offset:64
	s_waitcnt vmcnt(11)
	v_pk_fma_f32 v[148:149], v[64:65], v[100:101], v[148:149]
	v_pk_fma_f32 v[150:151], v[66:67], v[102:103], v[150:151]
	global_store_dwordx4 v[88:89], v[148:151], off offset:96
	s_nop 1
	global_load_dwordx4 v[136:139], v[70:71], off offset:128
	global_load_dwordx4 v[140:143], v[70:71], off offset:160
	global_load_dwordx4 v[144:147], v[70:71], off offset:192
	global_load_dwordx4 v[148:151], v[70:71], off offset:224
	s_waitcnt vmcnt(15)
	v_pk_fma_f32 v[152:153], v[36:37], v[120:121], v[152:153]
	v_pk_fma_f32 v[154:155], v[38:39], v[122:123], v[154:155]
	global_store_dwordx4 v[88:89], v[152:155], off offset:128
	s_waitcnt vmcnt(15)
	v_pk_fma_f32 v[156:157], v[40:41], v[124:125], v[156:157]
	v_pk_fma_f32 v[158:159], v[42:43], v[126:127], v[158:159]
	global_store_dwordx4 v[88:89], v[156:159], off offset:160
	s_waitcnt vmcnt(15)
	v_pk_fma_f32 v[160:161], v[44:45], v[128:129], v[160:161]
	v_pk_fma_f32 v[162:163], v[46:47], v[130:131], v[162:163]
	global_store_dwordx4 v[88:89], v[160:163], off offset:192
	s_waitcnt vmcnt(15)
	v_pk_fma_f32 v[164:165], v[48:49], v[132:133], v[164:165]
	v_pk_fma_f32 v[166:167], v[50:51], v[134:135], v[166:167]
	global_store_dwordx4 v[88:89], v[164:167], off offset:224
	s_waitcnt vmcnt(15)
	v_pk_fma_f32 v[168:169], v[20:21], v[72:73], v[168:169]
	v_pk_fma_f32 v[170:171], v[22:23], v[74:75], v[170:171]
	global_store_dwordx4 v[90:91], v[168:171], off
	s_waitcnt vmcnt(15)
	v_pk_fma_f32 v[172:173], v[24:25], v[92:93], v[172:173]
	v_pk_fma_f32 v[174:175], v[26:27], v[94:95], v[174:175]
	global_store_dwordx4 v[90:91], v[172:175], off offset:32
	s_waitcnt vmcnt(15)
	v_pk_fma_f32 v[176:177], v[28:29], v[96:97], v[176:177]
	v_pk_fma_f32 v[178:179], v[30:31], v[98:99], v[178:179]
	global_store_dwordx4 v[90:91], v[176:179], off offset:64
	s_waitcnt vmcnt(15)
	v_pk_fma_f32 v[180:181], v[32:33], v[100:101], v[180:181]
	v_pk_fma_f32 v[182:183], v[34:35], v[102:103], v[182:183]
	global_store_dwordx4 v[90:91], v[180:183], off offset:96
	s_waitcnt vmcnt(11)
	v_pk_fma_f32 v[136:137], v[4:5], v[120:121], v[136:137]
	v_pk_fma_f32 v[138:139], v[6:7], v[122:123], v[138:139]
	global_store_dwordx4 v[90:91], v[136:139], off offset:128
	s_waitcnt vmcnt(11)
	v_pk_fma_f32 v[140:141], v[8:9], v[124:125], v[140:141]
	v_pk_fma_f32 v[142:143], v[10:11], v[126:127], v[142:143]
	global_store_dwordx4 v[90:91], v[140:143], off offset:160
	s_waitcnt vmcnt(11)
	v_pk_fma_f32 v[144:145], v[12:13], v[128:129], v[144:145]
	v_pk_fma_f32 v[146:147], v[14:15], v[130:131], v[146:147]
	global_store_dwordx4 v[90:91], v[144:147], off offset:192
	s_waitcnt vmcnt(11)
	v_pk_fma_f32 v[148:149], v[16:17], v[132:133], v[148:149]
	v_pk_fma_f32 v[150:151], v[18:19], v[134:135], v[150:151]
	global_store_dwordx4 v[90:91], v[148:151], off offset:224
	s_load_dword s0, s[62:63], 0x0
	s_waitcnt lgkmcnt(0)
	s_add_i32 s14, s0, s14
	s_cmpk_gt_i32 s14, 0x1ff
	s_cbranch_scc1 .LBB0_58
.LBB0_51:
	s_lshl_b32 s0, s14, 7
	s_and_b32 s15, s0, 0x1f80
	s_lshl_b32 s0, s14, 1
	v_readlane_b32 s8, v252, 62
	v_mov_b32_e32 v2, v0
	s_and_b32 s6, s0, 0xffffff80
	s_lshl_b32 s16, s15, 10
	s_lshl_b32 s0, s15, 11
	v_readlane_b32 s10, v253, 0
	v_readlane_b32 s11, v253, 1
	v_ashrrev_i32_e32 v4, 3, v2
	s_add_u32 s0, s10, s0
	v_ashrrev_i32_e32 v5, 31, v4
	s_addc_u32 s1, s11, 0
	v_lshlrev_b64 v[4:5], 11, v[4:5]
	v_lshlrev_b32_e32 v2, 4, v2
	v_lshl_add_u64 v[6:7], s[0:1], 0, v[4:5]
	v_and_b32_e32 v2, 0x70, v2
	s_waitcnt vmcnt(12)
	v_lshl_add_u64 v[106:107], v[6:7], 0, v[2:3]
	v_readlane_b32 s9, v252, 63
	s_ashr_i32 s7, s6, 31
	s_waitcnt vmcnt(10)
	v_add_co_u32_e32 v108, vcc, s33, v106
	s_lshl_b64 s[8:9], s[6:7], 11
	s_nop 0
	v_addc_co_u32_e32 v109, vcc, 0, v107, vcc
	s_add_u32 s8, s12, s8
	v_add_co_u32_e32 v110, vcc, s78, v106
	s_addc_u32 s9, s13, s9
	s_nop 0
	v_addc_co_u32_e32 v111, vcc, 0, v107, vcc
	v_lshl_add_u64 v[4:5], s[8:9], 0, v[4:5]
	s_waitcnt vmcnt(8)
	v_add_co_u32_e32 v112, vcc, s79, v106
	v_lshl_add_u64 v[104:105], v[4:5], 0, v[2:3]
	s_nop 0
	v_addc_co_u32_e32 v113, vcc, 0, v107, vcc
	v_add_co_u32_e32 v114, vcc, s33, v104
	s_nop 0
	v_addc_co_u32_e32 v115, vcc, 0, v105, vcc
	s_waitcnt vmcnt(7)
	v_add_co_u32_e32 v116, vcc, s78, v104
	s_nop 0
	v_addc_co_u32_e32 v117, vcc, 0, v105, vcc
	v_add_co_u32_e32 v118, vcc, s79, v104
	s_nop 0
	v_addc_co_u32_e32 v119, vcc, 0, v105, vcc
	v_lshrrev_b32_e32 v176, 3, v0
	v_lshlrev_b32_e32 v177, 4, v0
	v_mul_u32_u24_e32 v176, 0x90, v176
	v_and_b32_e32 v177, 0x70, v177
	v_add_u32_e32 v2, v176, v177
	v_add_u32_e32 v180, 0x9000, v2
	v_lshrrev_b32_e32 v176, 1, v0
	v_and_b32_e32 v177, 31, v0
	v_and_b32_e32 v178, 16, v176
	v_and_b32_e32 v176, 64, v176
	v_add_u32_e32 v176, v176, v177
	v_mul_u32_u24_e32 v176, 0x90, v176
	v_add_u32_e32 v181, v176, v178
	v_and_b32_e32 v176, 64, v0
	v_add_u32_e32 v176, v176, v177
	v_mul_u32_u24_e32 v176, 0x90, v176
	v_add_u32_e32 v182, v176, v178
	global_load_dwordx4 v[68:71], v[106:107], off
	global_load_dwordx4 v[72:75], v[108:109], off
	global_load_dwordx4 v[76:79], v[110:111], off
	global_load_dwordx4 v[80:83], v[112:113], off
	global_load_dwordx4 v[84:87], v[104:105], off
	global_load_dwordx4 v[88:91], v[114:115], off
	global_load_dwordx4 v[92:95], v[116:117], off
	global_load_dwordx4 v[96:99], v[118:119], off
	global_load_dwordx4 v[100:103], v[106:107], off offset:128
	global_load_dwordx4 v[120:123], v[108:109], off offset:128
	global_load_dwordx4 v[124:127], v[110:111], off offset:128
	global_load_dwordx4 v[128:131], v[112:113], off offset:128
	global_load_dwordx4 v[132:135], v[104:105], off offset:128
	global_load_dwordx4 v[136:139], v[114:115], off offset:128
	global_load_dwordx4 v[140:143], v[116:117], off offset:128
	global_load_dwordx4 v[144:147], v[118:119], off offset:128
	s_barrier
	s_waitcnt vmcnt(15)
	ds_write_b128 v2, v[68:71]
	s_waitcnt vmcnt(14)
	ds_write_b128 v2, v[72:75] offset:4608
	s_waitcnt vmcnt(13)
	ds_write_b128 v2, v[76:79] offset:9216
	s_waitcnt vmcnt(12)
	ds_write_b128 v2, v[80:83] offset:13824
	s_waitcnt vmcnt(11)
	ds_write_b128 v2, v[84:87] offset:18432
	s_waitcnt vmcnt(10)
	ds_write_b128 v2, v[88:91] offset:23040
	s_waitcnt vmcnt(9)
	ds_write_b128 v2, v[92:95] offset:27648
	s_waitcnt vmcnt(8)
	ds_write_b128 v2, v[96:99] offset:32256
	global_load_dwordx4 v[68:71], v[106:107], off offset:256
	global_load_dwordx4 v[72:75], v[108:109], off offset:256
	global_load_dwordx4 v[76:79], v[110:111], off offset:256
	global_load_dwordx4 v[80:83], v[112:113], off offset:256
	global_load_dwordx4 v[84:87], v[104:105], off offset:256
	global_load_dwordx4 v[88:91], v[114:115], off offset:256
	global_load_dwordx4 v[92:95], v[116:117], off offset:256
	global_load_dwordx4 v[96:99], v[118:119], off offset:256
	s_waitcnt lgkmcnt(0)
	s_barrier
	ds_read_b128 v[148:151], v181
	ds_read_b128 v[152:155], v182 offset:18432
	ds_read_b128 v[156:159], v182 offset:23040
	ds_read_b128 v[160:163], v181 offset:4608
	ds_read_b128 v[164:167], v181 offset:32
	ds_read_b128 v[168:171], v182 offset:18464
	ds_read_b128 v[172:175], v182 offset:23072
	ds_read_b128 v[176:179], v181 offset:4640
	s_setprio 1
	s_waitcnt lgkmcnt(6)
	v_mfma_f32_32x32x16_bf16 v[52:67], v[152:155], v[148:151], 0
	s_waitcnt vmcnt(15)
	ds_write_b128 v180, v[100:103]
	s_waitcnt lgkmcnt(6)
	v_mfma_f32_32x32x16_bf16 v[36:51], v[156:159], v[148:151], 0
	s_waitcnt vmcnt(14)
	ds_write_b128 v180, v[120:123] offset:4608
	s_waitcnt lgkmcnt(6)
	v_mfma_f32_32x32x16_bf16 v[20:35], v[152:155], v[160:163], 0
	s_waitcnt vmcnt(13)
	ds_write_b128 v180, v[124:127] offset:9216
	global_load_dwordx4 v[100:103], v[106:107], off offset:384
	v_mfma_f32_32x32x16_bf16 v[4:19], v[156:159], v[160:163], 0
	ds_read_b128 v[148:151], v181 offset:64
	ds_read_b128 v[152:155], v182 offset:18496
	s_waitcnt lgkmcnt(7)
	v_mfma_f32_32x32x16_bf16 v[52:67], v[168:171], v[164:167], v[52:67]
	ds_read_b128 v[156:159], v182 offset:23104
	ds_read_b128 v[160:163], v181 offset:4672
	s_waitcnt lgkmcnt(8)
	v_mfma_f32_32x32x16_bf16 v[36:51], v[172:175], v[164:167], v[36:51]
	s_waitcnt vmcnt(13)
	ds_write_b128 v180, v[128:131] offset:13824
	global_load_dwordx4 v[120:123], v[108:109], off offset:384
	s_waitcnt lgkmcnt(8)
	v_mfma_f32_32x32x16_bf16 v[20:35], v[168:171], v[176:179], v[20:35]
	s_waitcnt vmcnt(13)
	ds_write_b128 v180, v[132:135] offset:18432
	global_load_dwordx4 v[124:127], v[110:111], off offset:384
	v_mfma_f32_32x32x16_bf16 v[4:19], v[172:175], v[176:179], v[4:19]
	ds_read_b128 v[164:167], v181 offset:96
	ds_read_b128 v[168:171], v182 offset:18528
	s_waitcnt lgkmcnt(6)
	v_mfma_f32_32x32x16_bf16 v[52:67], v[152:155], v[148:151], v[52:67]
	ds_read_b128 v[172:175], v182 offset:23136
	ds_read_b128 v[176:179], v181 offset:4704
	s_waitcnt lgkmcnt(7)
	v_mfma_f32_32x32x16_bf16 v[36:51], v[156:159], v[148:151], v[36:51]
	s_waitcnt vmcnt(13)
	ds_write_b128 v180, v[136:139] offset:23040
	global_load_dwordx4 v[128:131], v[112:113], off offset:384
	s_waitcnt lgkmcnt(7)
	v_mfma_f32_32x32x16_bf16 v[20:35], v[152:155], v[160:163], v[20:35]
	s_waitcnt vmcnt(13)
	ds_write_b128 v180, v[140:143] offset:27648
	global_load_dwordx4 v[132:135], v[104:105], off offset:384
	v_mfma_f32_32x32x16_bf16 v[4:19], v[156:159], v[160:163], v[4:19]
	s_waitcnt vmcnt(13)
	ds_write_b128 v180, v[144:147] offset:32256
	global_load_dwordx4 v[136:139], v[114:115], off offset:384
	s_waitcnt lgkmcnt(5)
	v_mfma_f32_32x32x16_bf16 v[52:67], v[168:171], v[164:167], v[52:67]
	global_load_dwordx4 v[140:143], v[116:117], off offset:384
	s_waitcnt lgkmcnt(4)
	v_mfma_f32_32x32x16_bf16 v[36:51], v[172:175], v[164:167], v[36:51]
	global_load_dwordx4 v[144:147], v[118:119], off offset:384
	s_waitcnt lgkmcnt(3)
	v_mfma_f32_32x32x16_bf16 v[20:35], v[168:171], v[176:179], v[20:35]
	v_mfma_f32_32x32x16_bf16 v[4:19], v[172:175], v[176:179], v[4:19]
	s_setprio 0
	s_waitcnt lgkmcnt(0)
	s_barrier
	ds_read_b128 v[148:151], v181 offset:36864
	ds_read_b128 v[152:155], v182 offset:55296
	ds_read_b128 v[156:159], v182 offset:59904
	ds_read_b128 v[160:163], v181 offset:41472
	ds_read_b128 v[164:167], v181 offset:36896
	ds_read_b128 v[168:171], v182 offset:55328
	ds_read_b128 v[172:175], v182 offset:59936
	ds_read_b128 v[176:179], v181 offset:41504
	s_setprio 1
	s_waitcnt lgkmcnt(6)
	v_mfma_f32_32x32x16_bf16 v[52:67], v[152:155], v[148:151], v[52:67]
	s_waitcnt vmcnt(15)
	ds_write_b128 v2, v[68:71]
	s_waitcnt lgkmcnt(6)
	v_mfma_f32_32x32x16_bf16 v[36:51], v[156:159], v[148:151], v[36:51]
	s_waitcnt vmcnt(14)
	ds_write_b128 v2, v[72:75] offset:4608
	s_waitcnt lgkmcnt(6)
	v_mfma_f32_32x32x16_bf16 v[20:35], v[152:155], v[160:163], v[20:35]
	s_waitcnt vmcnt(13)
	ds_write_b128 v2, v[76:79] offset:9216
	global_load_dwordx4 v[68:71], v[106:107], off offset:512
	v_mfma_f32_32x32x16_bf16 v[4:19], v[156:159], v[160:163], v[4:19]
	ds_read_b128 v[148:151], v181 offset:36928
	ds_read_b128 v[152:155], v182 offset:55360
	s_waitcnt lgkmcnt(7)
	v_mfma_f32_32x32x16_bf16 v[52:67], v[168:171], v[164:167], v[52:67]
	ds_read_b128 v[156:159], v182 offset:59968
	ds_read_b128 v[160:163], v181 offset:41536
	s_waitcnt lgkmcnt(8)
	v_mfma_f32_32x32x16_bf16 v[36:51], v[172:175], v[164:167], v[36:51]
	s_waitcnt vmcnt(13)
	ds_write_b128 v2, v[80:83] offset:13824
	global_load_dwordx4 v[72:75], v[108:109], off offset:512
	s_waitcnt lgkmcnt(8)
	v_mfma_f32_32x32x16_bf16 v[20:35], v[168:171], v[176:179], v[20:35]
	s_waitcnt vmcnt(13)
	ds_write_b128 v2, v[84:87] offset:18432
	global_load_dwordx4 v[76:79], v[110:111], off offset:512
	v_mfma_f32_32x32x16_bf16 v[4:19], v[172:175], v[176:179], v[4:19]
	ds_read_b128 v[164:167], v181 offset:36960
	ds_read_b128 v[168:171], v182 offset:55392
	s_waitcnt lgkmcnt(6)
	v_mfma_f32_32x32x16_bf16 v[52:67], v[152:155], v[148:151], v[52:67]
	ds_read_b128 v[172:175], v182 offset:60000
	ds_read_b128 v[176:179], v181 offset:41568
	s_waitcnt lgkmcnt(7)
	v_mfma_f32_32x32x16_bf16 v[36:51], v[156:159], v[148:151], v[36:51]
	s_waitcnt vmcnt(13)
	ds_write_b128 v2, v[88:91] offset:23040
	global_load_dwordx4 v[80:83], v[112:113], off offset:512
	s_waitcnt lgkmcnt(7)
	v_mfma_f32_32x32x16_bf16 v[20:35], v[152:155], v[160:163], v[20:35]
	s_waitcnt vmcnt(13)
	ds_write_b128 v2, v[92:95] offset:27648
	global_load_dwordx4 v[84:87], v[104:105], off offset:512
	v_mfma_f32_32x32x16_bf16 v[4:19], v[156:159], v[160:163], v[4:19]
	s_waitcnt vmcnt(13)
	ds_write_b128 v2, v[96:99] offset:32256
	global_load_dwordx4 v[88:91], v[114:115], off offset:512
	s_waitcnt lgkmcnt(5)
	v_mfma_f32_32x32x16_bf16 v[52:67], v[168:171], v[164:167], v[52:67]
	global_load_dwordx4 v[92:95], v[116:117], off offset:512
	s_waitcnt lgkmcnt(4)
	v_mfma_f32_32x32x16_bf16 v[36:51], v[172:175], v[164:167], v[36:51]
	global_load_dwordx4 v[96:99], v[118:119], off offset:512
	s_waitcnt lgkmcnt(3)
	v_mfma_f32_32x32x16_bf16 v[20:35], v[168:171], v[176:179], v[20:35]
	v_mfma_f32_32x32x16_bf16 v[4:19], v[172:175], v[176:179], v[4:19]
	s_setprio 0
	s_waitcnt lgkmcnt(0)
	s_barrier
	ds_read_b128 v[148:151], v181
	ds_read_b128 v[152:155], v182 offset:18432
	ds_read_b128 v[156:159], v182 offset:23040
	ds_read_b128 v[160:163], v181 offset:4608
	ds_read_b128 v[164:167], v181 offset:32
	ds_read_b128 v[168:171], v182 offset:18464
	ds_read_b128 v[172:175], v182 offset:23072
	ds_read_b128 v[176:179], v181 offset:4640
	s_setprio 1
	s_waitcnt lgkmcnt(6)
	v_mfma_f32_32x32x16_bf16 v[52:67], v[152:155], v[148:151], v[52:67]
	s_waitcnt vmcnt(15)
	ds_write_b128 v180, v[100:103]
	s_waitcnt lgkmcnt(6)
	v_mfma_f32_32x32x16_bf16 v[36:51], v[156:159], v[148:151], v[36:51]
	s_waitcnt vmcnt(14)
	ds_write_b128 v180, v[120:123] offset:4608
	s_waitcnt lgkmcnt(6)
	v_mfma_f32_32x32x16_bf16 v[20:35], v[152:155], v[160:163], v[20:35]
	s_waitcnt vmcnt(13)
	ds_write_b128 v180, v[124:127] offset:9216
	global_load_dwordx4 v[100:103], v[106:107], off offset:640
	v_mfma_f32_32x32x16_bf16 v[4:19], v[156:159], v[160:163], v[4:19]
	ds_read_b128 v[148:151], v181 offset:64
	ds_read_b128 v[152:155], v182 offset:18496
	s_waitcnt lgkmcnt(7)
	v_mfma_f32_32x32x16_bf16 v[52:67], v[168:171], v[164:167], v[52:67]
	ds_read_b128 v[156:159], v182 offset:23104
	ds_read_b128 v[160:163], v181 offset:4672
	s_waitcnt lgkmcnt(8)
	v_mfma_f32_32x32x16_bf16 v[36:51], v[172:175], v[164:167], v[36:51]
	s_waitcnt vmcnt(13)
	ds_write_b128 v180, v[128:131] offset:13824
	global_load_dwordx4 v[120:123], v[108:109], off offset:640
	s_waitcnt lgkmcnt(8)
	v_mfma_f32_32x32x16_bf16 v[20:35], v[168:171], v[176:179], v[20:35]
	s_waitcnt vmcnt(13)
	ds_write_b128 v180, v[132:135] offset:18432
	global_load_dwordx4 v[124:127], v[110:111], off offset:640
	v_mfma_f32_32x32x16_bf16 v[4:19], v[172:175], v[176:179], v[4:19]
	ds_read_b128 v[164:167], v181 offset:96
	ds_read_b128 v[168:171], v182 offset:18528
	s_waitcnt lgkmcnt(6)
	v_mfma_f32_32x32x16_bf16 v[52:67], v[152:155], v[148:151], v[52:67]
	ds_read_b128 v[172:175], v182 offset:23136
	ds_read_b128 v[176:179], v181 offset:4704
	s_waitcnt lgkmcnt(7)
	v_mfma_f32_32x32x16_bf16 v[36:51], v[156:159], v[148:151], v[36:51]
	s_waitcnt vmcnt(13)
	ds_write_b128 v180, v[136:139] offset:23040
	global_load_dwordx4 v[128:131], v[112:113], off offset:640
	s_waitcnt lgkmcnt(7)
	v_mfma_f32_32x32x16_bf16 v[20:35], v[152:155], v[160:163], v[20:35]
	s_waitcnt vmcnt(13)
	ds_write_b128 v180, v[140:143] offset:27648
	global_load_dwordx4 v[132:135], v[104:105], off offset:640
	v_mfma_f32_32x32x16_bf16 v[4:19], v[156:159], v[160:163], v[4:19]
	s_waitcnt vmcnt(13)
	ds_write_b128 v180, v[144:147] offset:32256
	global_load_dwordx4 v[136:139], v[114:115], off offset:640
	s_waitcnt lgkmcnt(5)
	v_mfma_f32_32x32x16_bf16 v[52:67], v[168:171], v[164:167], v[52:67]
	global_load_dwordx4 v[140:143], v[116:117], off offset:640
	s_waitcnt lgkmcnt(4)
	v_mfma_f32_32x32x16_bf16 v[36:51], v[172:175], v[164:167], v[36:51]
	global_load_dwordx4 v[144:147], v[118:119], off offset:640
	s_waitcnt lgkmcnt(3)
	v_mfma_f32_32x32x16_bf16 v[20:35], v[168:171], v[176:179], v[20:35]
	v_mfma_f32_32x32x16_bf16 v[4:19], v[172:175], v[176:179], v[4:19]
	s_setprio 0
	s_waitcnt lgkmcnt(0)
	s_barrier
	ds_read_b128 v[148:151], v181 offset:36864
	ds_read_b128 v[152:155], v182 offset:55296
	ds_read_b128 v[156:159], v182 offset:59904
	ds_read_b128 v[160:163], v181 offset:41472
	ds_read_b128 v[164:167], v181 offset:36896
	ds_read_b128 v[168:171], v182 offset:55328
	ds_read_b128 v[172:175], v182 offset:59936
	ds_read_b128 v[176:179], v181 offset:41504
	s_setprio 1
	s_waitcnt lgkmcnt(6)
	v_mfma_f32_32x32x16_bf16 v[52:67], v[152:155], v[148:151], v[52:67]
	s_waitcnt vmcnt(15)
	ds_write_b128 v2, v[68:71]
	s_waitcnt lgkmcnt(6)
	v_mfma_f32_32x32x16_bf16 v[36:51], v[156:159], v[148:151], v[36:51]
	s_waitcnt vmcnt(14)
	ds_write_b128 v2, v[72:75] offset:4608
	s_waitcnt lgkmcnt(6)
	v_mfma_f32_32x32x16_bf16 v[20:35], v[152:155], v[160:163], v[20:35]
	s_waitcnt vmcnt(13)
	ds_write_b128 v2, v[76:79] offset:9216
	global_load_dwordx4 v[68:71], v[106:107], off offset:768
	v_mfma_f32_32x32x16_bf16 v[4:19], v[156:159], v[160:163], v[4:19]
	ds_read_b128 v[148:151], v181 offset:36928
	ds_read_b128 v[152:155], v182 offset:55360
	s_waitcnt lgkmcnt(7)
	v_mfma_f32_32x32x16_bf16 v[52:67], v[168:171], v[164:167], v[52:67]
	ds_read_b128 v[156:159], v182 offset:59968
	ds_read_b128 v[160:163], v181 offset:41536
	s_waitcnt lgkmcnt(8)
	v_mfma_f32_32x32x16_bf16 v[36:51], v[172:175], v[164:167], v[36:51]
	s_waitcnt vmcnt(13)
	ds_write_b128 v2, v[80:83] offset:13824
	global_load_dwordx4 v[72:75], v[108:109], off offset:768
	s_waitcnt lgkmcnt(8)
	v_mfma_f32_32x32x16_bf16 v[20:35], v[168:171], v[176:179], v[20:35]
	s_waitcnt vmcnt(13)
	ds_write_b128 v2, v[84:87] offset:18432
	global_load_dwordx4 v[76:79], v[110:111], off offset:768
	v_mfma_f32_32x32x16_bf16 v[4:19], v[172:175], v[176:179], v[4:19]
	ds_read_b128 v[164:167], v181 offset:36960
	ds_read_b128 v[168:171], v182 offset:55392
	s_waitcnt lgkmcnt(6)
	v_mfma_f32_32x32x16_bf16 v[52:67], v[152:155], v[148:151], v[52:67]
	ds_read_b128 v[172:175], v182 offset:60000
	ds_read_b128 v[176:179], v181 offset:41568
	s_waitcnt lgkmcnt(7)
	v_mfma_f32_32x32x16_bf16 v[36:51], v[156:159], v[148:151], v[36:51]
	s_waitcnt vmcnt(13)
	ds_write_b128 v2, v[88:91] offset:23040
	global_load_dwordx4 v[80:83], v[112:113], off offset:768
	s_waitcnt lgkmcnt(7)
	v_mfma_f32_32x32x16_bf16 v[20:35], v[152:155], v[160:163], v[20:35]
	s_waitcnt vmcnt(13)
	ds_write_b128 v2, v[92:95] offset:27648
	global_load_dwordx4 v[84:87], v[104:105], off offset:768
	v_mfma_f32_32x32x16_bf16 v[4:19], v[156:159], v[160:163], v[4:19]
	s_waitcnt vmcnt(13)
	ds_write_b128 v2, v[96:99] offset:32256
	global_load_dwordx4 v[88:91], v[114:115], off offset:768
	s_waitcnt lgkmcnt(5)
	v_mfma_f32_32x32x16_bf16 v[52:67], v[168:171], v[164:167], v[52:67]
	global_load_dwordx4 v[92:95], v[116:117], off offset:768
	s_waitcnt lgkmcnt(4)
	v_mfma_f32_32x32x16_bf16 v[36:51], v[172:175], v[164:167], v[36:51]
	global_load_dwordx4 v[96:99], v[118:119], off offset:768
	s_waitcnt lgkmcnt(3)
	v_mfma_f32_32x32x16_bf16 v[20:35], v[168:171], v[176:179], v[20:35]
	v_mfma_f32_32x32x16_bf16 v[4:19], v[172:175], v[176:179], v[4:19]
	s_setprio 0
	s_waitcnt lgkmcnt(0)
	s_barrier
	ds_read_b128 v[148:151], v181
	ds_read_b128 v[152:155], v182 offset:18432
	ds_read_b128 v[156:159], v182 offset:23040
	ds_read_b128 v[160:163], v181 offset:4608
	ds_read_b128 v[164:167], v181 offset:32
	ds_read_b128 v[168:171], v182 offset:18464
	ds_read_b128 v[172:175], v182 offset:23072
	ds_read_b128 v[176:179], v181 offset:4640
	s_setprio 1
	s_waitcnt lgkmcnt(6)
	v_mfma_f32_32x32x16_bf16 v[52:67], v[152:155], v[148:151], v[52:67]
	s_waitcnt vmcnt(15)
	ds_write_b128 v180, v[100:103]
	s_waitcnt lgkmcnt(6)
	v_mfma_f32_32x32x16_bf16 v[36:51], v[156:159], v[148:151], v[36:51]
	s_waitcnt vmcnt(14)
	ds_write_b128 v180, v[120:123] offset:4608
	s_waitcnt lgkmcnt(6)
	v_mfma_f32_32x32x16_bf16 v[20:35], v[152:155], v[160:163], v[20:35]
	s_waitcnt vmcnt(13)
	ds_write_b128 v180, v[124:127] offset:9216
	global_load_dwordx4 v[100:103], v[106:107], off offset:896
	v_mfma_f32_32x32x16_bf16 v[4:19], v[156:159], v[160:163], v[4:19]
	ds_read_b128 v[148:151], v181 offset:64
	ds_read_b128 v[152:155], v182 offset:18496
	s_waitcnt lgkmcnt(7)
	v_mfma_f32_32x32x16_bf16 v[52:67], v[168:171], v[164:167], v[52:67]
	ds_read_b128 v[156:159], v182 offset:23104
	ds_read_b128 v[160:163], v181 offset:4672
	s_waitcnt lgkmcnt(8)
	v_mfma_f32_32x32x16_bf16 v[36:51], v[172:175], v[164:167], v[36:51]
	s_waitcnt vmcnt(13)
	ds_write_b128 v180, v[128:131] offset:13824
	global_load_dwordx4 v[120:123], v[108:109], off offset:896
	s_waitcnt lgkmcnt(8)
	v_mfma_f32_32x32x16_bf16 v[20:35], v[168:171], v[176:179], v[20:35]
	s_waitcnt vmcnt(13)
	ds_write_b128 v180, v[132:135] offset:18432
	global_load_dwordx4 v[124:127], v[110:111], off offset:896
	v_mfma_f32_32x32x16_bf16 v[4:19], v[172:175], v[176:179], v[4:19]
	ds_read_b128 v[164:167], v181 offset:96
	ds_read_b128 v[168:171], v182 offset:18528
	s_waitcnt lgkmcnt(6)
	v_mfma_f32_32x32x16_bf16 v[52:67], v[152:155], v[148:151], v[52:67]
	ds_read_b128 v[172:175], v182 offset:23136
	ds_read_b128 v[176:179], v181 offset:4704
	s_waitcnt lgkmcnt(7)
	v_mfma_f32_32x32x16_bf16 v[36:51], v[156:159], v[148:151], v[36:51]
	s_waitcnt vmcnt(13)
	ds_write_b128 v180, v[136:139] offset:23040
	global_load_dwordx4 v[128:131], v[112:113], off offset:896
	s_waitcnt lgkmcnt(7)
	v_mfma_f32_32x32x16_bf16 v[20:35], v[152:155], v[160:163], v[20:35]
	s_waitcnt vmcnt(13)
	ds_write_b128 v180, v[140:143] offset:27648
	global_load_dwordx4 v[132:135], v[104:105], off offset:896
	v_mfma_f32_32x32x16_bf16 v[4:19], v[156:159], v[160:163], v[4:19]
	s_waitcnt vmcnt(13)
	ds_write_b128 v180, v[144:147] offset:32256
	global_load_dwordx4 v[136:139], v[114:115], off offset:896
	s_waitcnt lgkmcnt(5)
	v_mfma_f32_32x32x16_bf16 v[52:67], v[168:171], v[164:167], v[52:67]
	global_load_dwordx4 v[140:143], v[116:117], off offset:896
	s_waitcnt lgkmcnt(4)
	v_mfma_f32_32x32x16_bf16 v[36:51], v[172:175], v[164:167], v[36:51]
	global_load_dwordx4 v[144:147], v[118:119], off offset:896
	s_waitcnt lgkmcnt(3)
	v_mfma_f32_32x32x16_bf16 v[20:35], v[168:171], v[176:179], v[20:35]
	v_mfma_f32_32x32x16_bf16 v[4:19], v[172:175], v[176:179], v[4:19]
	s_setprio 0
	s_waitcnt lgkmcnt(0)
	s_barrier
	ds_read_b128 v[148:151], v181 offset:36864
	ds_read_b128 v[152:155], v182 offset:55296
	ds_read_b128 v[156:159], v182 offset:59904
	ds_read_b128 v[160:163], v181 offset:41472
	ds_read_b128 v[164:167], v181 offset:36896
	ds_read_b128 v[168:171], v182 offset:55328
	ds_read_b128 v[172:175], v182 offset:59936
	ds_read_b128 v[176:179], v181 offset:41504
	s_setprio 1
	s_waitcnt lgkmcnt(6)
	v_mfma_f32_32x32x16_bf16 v[52:67], v[152:155], v[148:151], v[52:67]
	s_waitcnt vmcnt(15)
	ds_write_b128 v2, v[68:71]
	s_waitcnt lgkmcnt(6)
	v_mfma_f32_32x32x16_bf16 v[36:51], v[156:159], v[148:151], v[36:51]
	s_waitcnt vmcnt(14)
	ds_write_b128 v2, v[72:75] offset:4608
	s_waitcnt lgkmcnt(6)
	v_mfma_f32_32x32x16_bf16 v[20:35], v[152:155], v[160:163], v[20:35]
	s_waitcnt vmcnt(13)
	ds_write_b128 v2, v[76:79] offset:9216
	global_load_dwordx4 v[68:71], v[106:107], off offset:1024
	v_mfma_f32_32x32x16_bf16 v[4:19], v[156:159], v[160:163], v[4:19]
	ds_read_b128 v[148:151], v181 offset:36928
	ds_read_b128 v[152:155], v182 offset:55360
	s_waitcnt lgkmcnt(7)
	v_mfma_f32_32x32x16_bf16 v[52:67], v[168:171], v[164:167], v[52:67]
	ds_read_b128 v[156:159], v182 offset:59968
	ds_read_b128 v[160:163], v181 offset:41536
	s_waitcnt lgkmcnt(8)
	v_mfma_f32_32x32x16_bf16 v[36:51], v[172:175], v[164:167], v[36:51]
	s_waitcnt vmcnt(13)
	ds_write_b128 v2, v[80:83] offset:13824
	global_load_dwordx4 v[72:75], v[108:109], off offset:1024
	s_waitcnt lgkmcnt(8)
	v_mfma_f32_32x32x16_bf16 v[20:35], v[168:171], v[176:179], v[20:35]
	s_waitcnt vmcnt(13)
	ds_write_b128 v2, v[84:87] offset:18432
	global_load_dwordx4 v[76:79], v[110:111], off offset:1024
	v_mfma_f32_32x32x16_bf16 v[4:19], v[172:175], v[176:179], v[4:19]
	ds_read_b128 v[164:167], v181 offset:36960
	ds_read_b128 v[168:171], v182 offset:55392
	s_waitcnt lgkmcnt(6)
	v_mfma_f32_32x32x16_bf16 v[52:67], v[152:155], v[148:151], v[52:67]
	ds_read_b128 v[172:175], v182 offset:60000
	ds_read_b128 v[176:179], v181 offset:41568
	s_waitcnt lgkmcnt(7)
	v_mfma_f32_32x32x16_bf16 v[36:51], v[156:159], v[148:151], v[36:51]
	s_waitcnt vmcnt(13)
	ds_write_b128 v2, v[88:91] offset:23040
	global_load_dwordx4 v[80:83], v[112:113], off offset:1024
	s_waitcnt lgkmcnt(7)
	v_mfma_f32_32x32x16_bf16 v[20:35], v[152:155], v[160:163], v[20:35]
	s_waitcnt vmcnt(13)
	ds_write_b128 v2, v[92:95] offset:27648
	global_load_dwordx4 v[84:87], v[104:105], off offset:1024
	v_mfma_f32_32x32x16_bf16 v[4:19], v[156:159], v[160:163], v[4:19]
	s_waitcnt vmcnt(13)
	ds_write_b128 v2, v[96:99] offset:32256
	global_load_dwordx4 v[88:91], v[114:115], off offset:1024
	s_waitcnt lgkmcnt(5)
	v_mfma_f32_32x32x16_bf16 v[52:67], v[168:171], v[164:167], v[52:67]
	global_load_dwordx4 v[92:95], v[116:117], off offset:1024
	s_waitcnt lgkmcnt(4)
	v_mfma_f32_32x32x16_bf16 v[36:51], v[172:175], v[164:167], v[36:51]
	global_load_dwordx4 v[96:99], v[118:119], off offset:1024
	s_waitcnt lgkmcnt(3)
	v_mfma_f32_32x32x16_bf16 v[20:35], v[168:171], v[176:179], v[20:35]
	v_mfma_f32_32x32x16_bf16 v[4:19], v[172:175], v[176:179], v[4:19]
	s_setprio 0
	s_waitcnt lgkmcnt(0)
	s_barrier
	ds_read_b128 v[148:151], v181
	ds_read_b128 v[152:155], v182 offset:18432
	ds_read_b128 v[156:159], v182 offset:23040
	ds_read_b128 v[160:163], v181 offset:4608
	ds_read_b128 v[164:167], v181 offset:32
	ds_read_b128 v[168:171], v182 offset:18464
	ds_read_b128 v[172:175], v182 offset:23072
	ds_read_b128 v[176:179], v181 offset:4640
	s_setprio 1
	s_waitcnt lgkmcnt(6)
	v_mfma_f32_32x32x16_bf16 v[52:67], v[152:155], v[148:151], v[52:67]
	s_waitcnt vmcnt(15)
	ds_write_b128 v180, v[100:103]
	s_waitcnt lgkmcnt(6)
	v_mfma_f32_32x32x16_bf16 v[36:51], v[156:159], v[148:151], v[36:51]
	s_waitcnt vmcnt(14)
	ds_write_b128 v180, v[120:123] offset:4608
	s_waitcnt lgkmcnt(6)
	v_mfma_f32_32x32x16_bf16 v[20:35], v[152:155], v[160:163], v[20:35]
	s_waitcnt vmcnt(13)
	ds_write_b128 v180, v[124:127] offset:9216
	global_load_dwordx4 v[100:103], v[106:107], off offset:1152
	v_mfma_f32_32x32x16_bf16 v[4:19], v[156:159], v[160:163], v[4:19]
	ds_read_b128 v[148:151], v181 offset:64
	ds_read_b128 v[152:155], v182 offset:18496
	s_waitcnt lgkmcnt(7)
	v_mfma_f32_32x32x16_bf16 v[52:67], v[168:171], v[164:167], v[52:67]
	ds_read_b128 v[156:159], v182 offset:23104
	ds_read_b128 v[160:163], v181 offset:4672
	s_waitcnt lgkmcnt(8)
	v_mfma_f32_32x32x16_bf16 v[36:51], v[172:175], v[164:167], v[36:51]
	s_waitcnt vmcnt(13)
	ds_write_b128 v180, v[128:131] offset:13824
	global_load_dwordx4 v[120:123], v[108:109], off offset:1152
	s_waitcnt lgkmcnt(8)
	v_mfma_f32_32x32x16_bf16 v[20:35], v[168:171], v[176:179], v[20:35]
	s_waitcnt vmcnt(13)
	ds_write_b128 v180, v[132:135] offset:18432
	global_load_dwordx4 v[124:127], v[110:111], off offset:1152
	v_mfma_f32_32x32x16_bf16 v[4:19], v[172:175], v[176:179], v[4:19]
	ds_read_b128 v[164:167], v181 offset:96
	ds_read_b128 v[168:171], v182 offset:18528
	s_waitcnt lgkmcnt(6)
	v_mfma_f32_32x32x16_bf16 v[52:67], v[152:155], v[148:151], v[52:67]
	ds_read_b128 v[172:175], v182 offset:23136
	ds_read_b128 v[176:179], v181 offset:4704
	s_waitcnt lgkmcnt(7)
	v_mfma_f32_32x32x16_bf16 v[36:51], v[156:159], v[148:151], v[36:51]
	s_waitcnt vmcnt(13)
	ds_write_b128 v180, v[136:139] offset:23040
	global_load_dwordx4 v[128:131], v[112:113], off offset:1152
	s_waitcnt lgkmcnt(7)
	v_mfma_f32_32x32x16_bf16 v[20:35], v[152:155], v[160:163], v[20:35]
	s_waitcnt vmcnt(13)
	ds_write_b128 v180, v[140:143] offset:27648
	global_load_dwordx4 v[132:135], v[104:105], off offset:1152
	v_mfma_f32_32x32x16_bf16 v[4:19], v[156:159], v[160:163], v[4:19]
	s_waitcnt vmcnt(13)
	ds_write_b128 v180, v[144:147] offset:32256
	global_load_dwordx4 v[136:139], v[114:115], off offset:1152
	s_waitcnt lgkmcnt(5)
	v_mfma_f32_32x32x16_bf16 v[52:67], v[168:171], v[164:167], v[52:67]
	global_load_dwordx4 v[140:143], v[116:117], off offset:1152
	s_waitcnt lgkmcnt(4)
	v_mfma_f32_32x32x16_bf16 v[36:51], v[172:175], v[164:167], v[36:51]
	global_load_dwordx4 v[144:147], v[118:119], off offset:1152
	s_waitcnt lgkmcnt(3)
	v_mfma_f32_32x32x16_bf16 v[20:35], v[168:171], v[176:179], v[20:35]
	v_mfma_f32_32x32x16_bf16 v[4:19], v[172:175], v[176:179], v[4:19]
	s_setprio 0
	s_waitcnt lgkmcnt(0)
	s_barrier
	ds_read_b128 v[148:151], v181 offset:36864
	ds_read_b128 v[152:155], v182 offset:55296
	ds_read_b128 v[156:159], v182 offset:59904
	ds_read_b128 v[160:163], v181 offset:41472
	ds_read_b128 v[164:167], v181 offset:36896
	ds_read_b128 v[168:171], v182 offset:55328
	ds_read_b128 v[172:175], v182 offset:59936
	ds_read_b128 v[176:179], v181 offset:41504
	s_setprio 1
	s_waitcnt lgkmcnt(6)
	v_mfma_f32_32x32x16_bf16 v[52:67], v[152:155], v[148:151], v[52:67]
	s_waitcnt vmcnt(15)
	ds_write_b128 v2, v[68:71]
	s_waitcnt lgkmcnt(6)
	v_mfma_f32_32x32x16_bf16 v[36:51], v[156:159], v[148:151], v[36:51]
	s_waitcnt vmcnt(14)
	ds_write_b128 v2, v[72:75] offset:4608
	s_waitcnt lgkmcnt(6)
	v_mfma_f32_32x32x16_bf16 v[20:35], v[152:155], v[160:163], v[20:35]
	s_waitcnt vmcnt(13)
	ds_write_b128 v2, v[76:79] offset:9216
	global_load_dwordx4 v[68:71], v[106:107], off offset:1280
	v_mfma_f32_32x32x16_bf16 v[4:19], v[156:159], v[160:163], v[4:19]
	ds_read_b128 v[148:151], v181 offset:36928
	ds_read_b128 v[152:155], v182 offset:55360
	s_waitcnt lgkmcnt(7)
	v_mfma_f32_32x32x16_bf16 v[52:67], v[168:171], v[164:167], v[52:67]
	ds_read_b128 v[156:159], v182 offset:59968
	ds_read_b128 v[160:163], v181 offset:41536
	s_waitcnt lgkmcnt(8)
	v_mfma_f32_32x32x16_bf16 v[36:51], v[172:175], v[164:167], v[36:51]
	s_waitcnt vmcnt(13)
	ds_write_b128 v2, v[80:83] offset:13824
	global_load_dwordx4 v[72:75], v[108:109], off offset:1280
	s_waitcnt lgkmcnt(8)
	v_mfma_f32_32x32x16_bf16 v[20:35], v[168:171], v[176:179], v[20:35]
	s_waitcnt vmcnt(13)
	ds_write_b128 v2, v[84:87] offset:18432
	global_load_dwordx4 v[76:79], v[110:111], off offset:1280
	v_mfma_f32_32x32x16_bf16 v[4:19], v[172:175], v[176:179], v[4:19]
	ds_read_b128 v[164:167], v181 offset:36960
	ds_read_b128 v[168:171], v182 offset:55392
	s_waitcnt lgkmcnt(6)
	v_mfma_f32_32x32x16_bf16 v[52:67], v[152:155], v[148:151], v[52:67]
	ds_read_b128 v[172:175], v182 offset:60000
	ds_read_b128 v[176:179], v181 offset:41568
	s_waitcnt lgkmcnt(7)
	v_mfma_f32_32x32x16_bf16 v[36:51], v[156:159], v[148:151], v[36:51]
	s_waitcnt vmcnt(13)
	ds_write_b128 v2, v[88:91] offset:23040
	global_load_dwordx4 v[80:83], v[112:113], off offset:1280
	s_waitcnt lgkmcnt(7)
	v_mfma_f32_32x32x16_bf16 v[20:35], v[152:155], v[160:163], v[20:35]
	s_waitcnt vmcnt(13)
	ds_write_b128 v2, v[92:95] offset:27648
	global_load_dwordx4 v[84:87], v[104:105], off offset:1280
	v_mfma_f32_32x32x16_bf16 v[4:19], v[156:159], v[160:163], v[4:19]
	s_waitcnt vmcnt(13)
	ds_write_b128 v2, v[96:99] offset:32256
	global_load_dwordx4 v[88:91], v[114:115], off offset:1280
	s_waitcnt lgkmcnt(5)
	v_mfma_f32_32x32x16_bf16 v[52:67], v[168:171], v[164:167], v[52:67]
	global_load_dwordx4 v[92:95], v[116:117], off offset:1280
	s_waitcnt lgkmcnt(4)
	v_mfma_f32_32x32x16_bf16 v[36:51], v[172:175], v[164:167], v[36:51]
	global_load_dwordx4 v[96:99], v[118:119], off offset:1280
	s_waitcnt lgkmcnt(3)
	v_mfma_f32_32x32x16_bf16 v[20:35], v[168:171], v[176:179], v[20:35]
	v_mfma_f32_32x32x16_bf16 v[4:19], v[172:175], v[176:179], v[4:19]
	s_setprio 0
	s_waitcnt lgkmcnt(0)
	s_barrier
	ds_read_b128 v[148:151], v181
	ds_read_b128 v[152:155], v182 offset:18432
	ds_read_b128 v[156:159], v182 offset:23040
	ds_read_b128 v[160:163], v181 offset:4608
	ds_read_b128 v[164:167], v181 offset:32
	ds_read_b128 v[168:171], v182 offset:18464
	ds_read_b128 v[172:175], v182 offset:23072
	ds_read_b128 v[176:179], v181 offset:4640
	s_setprio 1
	s_waitcnt lgkmcnt(6)
	v_mfma_f32_32x32x16_bf16 v[52:67], v[152:155], v[148:151], v[52:67]
	s_waitcnt vmcnt(15)
	ds_write_b128 v180, v[100:103]
	s_waitcnt lgkmcnt(6)
	v_mfma_f32_32x32x16_bf16 v[36:51], v[156:159], v[148:151], v[36:51]
	s_waitcnt vmcnt(14)
	ds_write_b128 v180, v[120:123] offset:4608
	s_waitcnt lgkmcnt(6)
	v_mfma_f32_32x32x16_bf16 v[20:35], v[152:155], v[160:163], v[20:35]
	s_waitcnt vmcnt(13)
	ds_write_b128 v180, v[124:127] offset:9216
	global_load_dwordx4 v[100:103], v[106:107], off offset:1408
	v_mfma_f32_32x32x16_bf16 v[4:19], v[156:159], v[160:163], v[4:19]
	ds_read_b128 v[148:151], v181 offset:64
	ds_read_b128 v[152:155], v182 offset:18496
	s_waitcnt lgkmcnt(7)
	v_mfma_f32_32x32x16_bf16 v[52:67], v[168:171], v[164:167], v[52:67]
	ds_read_b128 v[156:159], v182 offset:23104
	ds_read_b128 v[160:163], v181 offset:4672
	s_waitcnt lgkmcnt(8)
	v_mfma_f32_32x32x16_bf16 v[36:51], v[172:175], v[164:167], v[36:51]
	s_waitcnt vmcnt(13)
	ds_write_b128 v180, v[128:131] offset:13824
	global_load_dwordx4 v[120:123], v[108:109], off offset:1408
	s_waitcnt lgkmcnt(8)
	v_mfma_f32_32x32x16_bf16 v[20:35], v[168:171], v[176:179], v[20:35]
	s_waitcnt vmcnt(13)
	ds_write_b128 v180, v[132:135] offset:18432
	global_load_dwordx4 v[124:127], v[110:111], off offset:1408
	v_mfma_f32_32x32x16_bf16 v[4:19], v[172:175], v[176:179], v[4:19]
	ds_read_b128 v[164:167], v181 offset:96
	ds_read_b128 v[168:171], v182 offset:18528
	s_waitcnt lgkmcnt(6)
	v_mfma_f32_32x32x16_bf16 v[52:67], v[152:155], v[148:151], v[52:67]
	ds_read_b128 v[172:175], v182 offset:23136
	ds_read_b128 v[176:179], v181 offset:4704
	s_waitcnt lgkmcnt(7)
	v_mfma_f32_32x32x16_bf16 v[36:51], v[156:159], v[148:151], v[36:51]
	s_waitcnt vmcnt(13)
	ds_write_b128 v180, v[136:139] offset:23040
	global_load_dwordx4 v[128:131], v[112:113], off offset:1408
	s_waitcnt lgkmcnt(7)
	v_mfma_f32_32x32x16_bf16 v[20:35], v[152:155], v[160:163], v[20:35]
	s_waitcnt vmcnt(13)
	ds_write_b128 v180, v[140:143] offset:27648
	global_load_dwordx4 v[132:135], v[104:105], off offset:1408
	v_mfma_f32_32x32x16_bf16 v[4:19], v[156:159], v[160:163], v[4:19]
	s_waitcnt vmcnt(13)
	ds_write_b128 v180, v[144:147] offset:32256
	global_load_dwordx4 v[136:139], v[114:115], off offset:1408
	s_waitcnt lgkmcnt(5)
	v_mfma_f32_32x32x16_bf16 v[52:67], v[168:171], v[164:167], v[52:67]
	global_load_dwordx4 v[140:143], v[116:117], off offset:1408
	s_waitcnt lgkmcnt(4)
	v_mfma_f32_32x32x16_bf16 v[36:51], v[172:175], v[164:167], v[36:51]
	global_load_dwordx4 v[144:147], v[118:119], off offset:1408
	s_waitcnt lgkmcnt(3)
	v_mfma_f32_32x32x16_bf16 v[20:35], v[168:171], v[176:179], v[20:35]
	v_mfma_f32_32x32x16_bf16 v[4:19], v[172:175], v[176:179], v[4:19]
	s_setprio 0
	s_waitcnt lgkmcnt(0)
	s_barrier
	ds_read_b128 v[148:151], v181 offset:36864
	ds_read_b128 v[152:155], v182 offset:55296
	ds_read_b128 v[156:159], v182 offset:59904
	ds_read_b128 v[160:163], v181 offset:41472
	ds_read_b128 v[164:167], v181 offset:36896
	ds_read_b128 v[168:171], v182 offset:55328
	ds_read_b128 v[172:175], v182 offset:59936
	ds_read_b128 v[176:179], v181 offset:41504
	s_setprio 1
	s_waitcnt lgkmcnt(6)
	v_mfma_f32_32x32x16_bf16 v[52:67], v[152:155], v[148:151], v[52:67]
	s_waitcnt vmcnt(15)
	ds_write_b128 v2, v[68:71]
	s_waitcnt lgkmcnt(6)
	v_mfma_f32_32x32x16_bf16 v[36:51], v[156:159], v[148:151], v[36:51]
	s_waitcnt vmcnt(14)
	ds_write_b128 v2, v[72:75] offset:4608
	s_waitcnt lgkmcnt(6)
	v_mfma_f32_32x32x16_bf16 v[20:35], v[152:155], v[160:163], v[20:35]
	s_waitcnt vmcnt(13)
	ds_write_b128 v2, v[76:79] offset:9216
	global_load_dwordx4 v[68:71], v[106:107], off offset:1536
	v_mfma_f32_32x32x16_bf16 v[4:19], v[156:159], v[160:163], v[4:19]
	ds_read_b128 v[148:151], v181 offset:36928
	ds_read_b128 v[152:155], v182 offset:55360
	s_waitcnt lgkmcnt(7)
	v_mfma_f32_32x32x16_bf16 v[52:67], v[168:171], v[164:167], v[52:67]
	ds_read_b128 v[156:159], v182 offset:59968
	ds_read_b128 v[160:163], v181 offset:41536
	s_waitcnt lgkmcnt(8)
	v_mfma_f32_32x32x16_bf16 v[36:51], v[172:175], v[164:167], v[36:51]
	s_waitcnt vmcnt(13)
	ds_write_b128 v2, v[80:83] offset:13824
	global_load_dwordx4 v[72:75], v[108:109], off offset:1536
	s_waitcnt lgkmcnt(8)
	v_mfma_f32_32x32x16_bf16 v[20:35], v[168:171], v[176:179], v[20:35]
	s_waitcnt vmcnt(13)
	ds_write_b128 v2, v[84:87] offset:18432
	global_load_dwordx4 v[76:79], v[110:111], off offset:1536
	v_mfma_f32_32x32x16_bf16 v[4:19], v[172:175], v[176:179], v[4:19]
	ds_read_b128 v[164:167], v181 offset:36960
	ds_read_b128 v[168:171], v182 offset:55392
	s_waitcnt lgkmcnt(6)
	v_mfma_f32_32x32x16_bf16 v[52:67], v[152:155], v[148:151], v[52:67]
	ds_read_b128 v[172:175], v182 offset:60000
	ds_read_b128 v[176:179], v181 offset:41568
	s_waitcnt lgkmcnt(7)
	v_mfma_f32_32x32x16_bf16 v[36:51], v[156:159], v[148:151], v[36:51]
	s_waitcnt vmcnt(13)
	ds_write_b128 v2, v[88:91] offset:23040
	global_load_dwordx4 v[80:83], v[112:113], off offset:1536
	s_waitcnt lgkmcnt(7)
	v_mfma_f32_32x32x16_bf16 v[20:35], v[152:155], v[160:163], v[20:35]
	s_waitcnt vmcnt(13)
	ds_write_b128 v2, v[92:95] offset:27648
	global_load_dwordx4 v[84:87], v[104:105], off offset:1536
	v_mfma_f32_32x32x16_bf16 v[4:19], v[156:159], v[160:163], v[4:19]
	s_waitcnt vmcnt(13)
	ds_write_b128 v2, v[96:99] offset:32256
	global_load_dwordx4 v[88:91], v[114:115], off offset:1536
	s_waitcnt lgkmcnt(5)
	v_mfma_f32_32x32x16_bf16 v[52:67], v[168:171], v[164:167], v[52:67]
	global_load_dwordx4 v[92:95], v[116:117], off offset:1536
	s_waitcnt lgkmcnt(4)
	v_mfma_f32_32x32x16_bf16 v[36:51], v[172:175], v[164:167], v[36:51]
	global_load_dwordx4 v[96:99], v[118:119], off offset:1536
	s_waitcnt lgkmcnt(3)
	v_mfma_f32_32x32x16_bf16 v[20:35], v[168:171], v[176:179], v[20:35]
	v_mfma_f32_32x32x16_bf16 v[4:19], v[172:175], v[176:179], v[4:19]
	s_setprio 0
	s_waitcnt lgkmcnt(0)
	s_barrier
	ds_read_b128 v[148:151], v181
	ds_read_b128 v[152:155], v182 offset:18432
	ds_read_b128 v[156:159], v182 offset:23040
	ds_read_b128 v[160:163], v181 offset:4608
	ds_read_b128 v[164:167], v181 offset:32
	ds_read_b128 v[168:171], v182 offset:18464
	ds_read_b128 v[172:175], v182 offset:23072
	ds_read_b128 v[176:179], v181 offset:4640
	s_setprio 1
	s_waitcnt lgkmcnt(6)
	v_mfma_f32_32x32x16_bf16 v[52:67], v[152:155], v[148:151], v[52:67]
	s_waitcnt vmcnt(15)
	ds_write_b128 v180, v[100:103]
	s_waitcnt lgkmcnt(6)
	v_mfma_f32_32x32x16_bf16 v[36:51], v[156:159], v[148:151], v[36:51]
	s_waitcnt vmcnt(14)
	ds_write_b128 v180, v[120:123] offset:4608
	s_waitcnt lgkmcnt(6)
	v_mfma_f32_32x32x16_bf16 v[20:35], v[152:155], v[160:163], v[20:35]
	s_waitcnt vmcnt(13)
	ds_write_b128 v180, v[124:127] offset:9216
	global_load_dwordx4 v[100:103], v[106:107], off offset:1664
	v_mfma_f32_32x32x16_bf16 v[4:19], v[156:159], v[160:163], v[4:19]
	ds_read_b128 v[148:151], v181 offset:64
	ds_read_b128 v[152:155], v182 offset:18496
	s_waitcnt lgkmcnt(7)
	v_mfma_f32_32x32x16_bf16 v[52:67], v[168:171], v[164:167], v[52:67]
	ds_read_b128 v[156:159], v182 offset:23104
	ds_read_b128 v[160:163], v181 offset:4672
	s_waitcnt lgkmcnt(8)
	v_mfma_f32_32x32x16_bf16 v[36:51], v[172:175], v[164:167], v[36:51]
	s_waitcnt vmcnt(13)
	ds_write_b128 v180, v[128:131] offset:13824
	global_load_dwordx4 v[120:123], v[108:109], off offset:1664
	s_waitcnt lgkmcnt(8)
	v_mfma_f32_32x32x16_bf16 v[20:35], v[168:171], v[176:179], v[20:35]
	s_waitcnt vmcnt(13)
	ds_write_b128 v180, v[132:135] offset:18432
	global_load_dwordx4 v[124:127], v[110:111], off offset:1664
	v_mfma_f32_32x32x16_bf16 v[4:19], v[172:175], v[176:179], v[4:19]
	ds_read_b128 v[164:167], v181 offset:96
	ds_read_b128 v[168:171], v182 offset:18528
	s_waitcnt lgkmcnt(6)
	v_mfma_f32_32x32x16_bf16 v[52:67], v[152:155], v[148:151], v[52:67]
	ds_read_b128 v[172:175], v182 offset:23136
	ds_read_b128 v[176:179], v181 offset:4704
	s_waitcnt lgkmcnt(7)
	v_mfma_f32_32x32x16_bf16 v[36:51], v[156:159], v[148:151], v[36:51]
	s_waitcnt vmcnt(13)
	ds_write_b128 v180, v[136:139] offset:23040
	global_load_dwordx4 v[128:131], v[112:113], off offset:1664
	s_waitcnt lgkmcnt(7)
	v_mfma_f32_32x32x16_bf16 v[20:35], v[152:155], v[160:163], v[20:35]
	s_waitcnt vmcnt(13)
	ds_write_b128 v180, v[140:143] offset:27648
	global_load_dwordx4 v[132:135], v[104:105], off offset:1664
	v_mfma_f32_32x32x16_bf16 v[4:19], v[156:159], v[160:163], v[4:19]
	s_waitcnt vmcnt(13)
	ds_write_b128 v180, v[144:147] offset:32256
	global_load_dwordx4 v[136:139], v[114:115], off offset:1664
	s_waitcnt lgkmcnt(5)
	v_mfma_f32_32x32x16_bf16 v[52:67], v[168:171], v[164:167], v[52:67]
	global_load_dwordx4 v[140:143], v[116:117], off offset:1664
	s_waitcnt lgkmcnt(4)
	v_mfma_f32_32x32x16_bf16 v[36:51], v[172:175], v[164:167], v[36:51]
	global_load_dwordx4 v[144:147], v[118:119], off offset:1664
	s_waitcnt lgkmcnt(3)
	v_mfma_f32_32x32x16_bf16 v[20:35], v[168:171], v[176:179], v[20:35]
	v_mfma_f32_32x32x16_bf16 v[4:19], v[172:175], v[176:179], v[4:19]
	s_setprio 0
	s_waitcnt lgkmcnt(0)
	s_barrier
	ds_read_b128 v[148:151], v181 offset:36864
	ds_read_b128 v[152:155], v182 offset:55296
	ds_read_b128 v[156:159], v182 offset:59904
	ds_read_b128 v[160:163], v181 offset:41472
	ds_read_b128 v[164:167], v181 offset:36896
	ds_read_b128 v[168:171], v182 offset:55328
	ds_read_b128 v[172:175], v182 offset:59936
	ds_read_b128 v[176:179], v181 offset:41504
	s_setprio 1
	s_waitcnt lgkmcnt(6)
	v_mfma_f32_32x32x16_bf16 v[52:67], v[152:155], v[148:151], v[52:67]
	s_waitcnt vmcnt(15)
	ds_write_b128 v2, v[68:71]
	s_waitcnt lgkmcnt(6)
	v_mfma_f32_32x32x16_bf16 v[36:51], v[156:159], v[148:151], v[36:51]
	s_waitcnt vmcnt(14)
	ds_write_b128 v2, v[72:75] offset:4608
	s_waitcnt lgkmcnt(6)
	v_mfma_f32_32x32x16_bf16 v[20:35], v[152:155], v[160:163], v[20:35]
	s_waitcnt vmcnt(13)
	ds_write_b128 v2, v[76:79] offset:9216
	global_load_dwordx4 v[68:71], v[106:107], off offset:1792
	v_mfma_f32_32x32x16_bf16 v[4:19], v[156:159], v[160:163], v[4:19]
	ds_read_b128 v[148:151], v181 offset:36928
	ds_read_b128 v[152:155], v182 offset:55360
	s_waitcnt lgkmcnt(7)
	v_mfma_f32_32x32x16_bf16 v[52:67], v[168:171], v[164:167], v[52:67]
	ds_read_b128 v[156:159], v182 offset:59968
	ds_read_b128 v[160:163], v181 offset:41536
	s_waitcnt lgkmcnt(8)
	v_mfma_f32_32x32x16_bf16 v[36:51], v[172:175], v[164:167], v[36:51]
	s_waitcnt vmcnt(13)
	ds_write_b128 v2, v[80:83] offset:13824
	global_load_dwordx4 v[72:75], v[108:109], off offset:1792
	s_waitcnt lgkmcnt(8)
	v_mfma_f32_32x32x16_bf16 v[20:35], v[168:171], v[176:179], v[20:35]
	s_waitcnt vmcnt(13)
	ds_write_b128 v2, v[84:87] offset:18432
	global_load_dwordx4 v[76:79], v[110:111], off offset:1792
	v_mfma_f32_32x32x16_bf16 v[4:19], v[172:175], v[176:179], v[4:19]
	ds_read_b128 v[164:167], v181 offset:36960
	ds_read_b128 v[168:171], v182 offset:55392
	s_waitcnt lgkmcnt(6)
	v_mfma_f32_32x32x16_bf16 v[52:67], v[152:155], v[148:151], v[52:67]
	ds_read_b128 v[172:175], v182 offset:60000
	ds_read_b128 v[176:179], v181 offset:41568
	s_waitcnt lgkmcnt(7)
	v_mfma_f32_32x32x16_bf16 v[36:51], v[156:159], v[148:151], v[36:51]
	s_waitcnt vmcnt(13)
	ds_write_b128 v2, v[88:91] offset:23040
	global_load_dwordx4 v[80:83], v[112:113], off offset:1792
	s_waitcnt lgkmcnt(7)
	v_mfma_f32_32x32x16_bf16 v[20:35], v[152:155], v[160:163], v[20:35]
	s_waitcnt vmcnt(13)
	ds_write_b128 v2, v[92:95] offset:27648
	global_load_dwordx4 v[84:87], v[104:105], off offset:1792
	v_mfma_f32_32x32x16_bf16 v[4:19], v[156:159], v[160:163], v[4:19]
	s_waitcnt vmcnt(13)
	ds_write_b128 v2, v[96:99] offset:32256
	global_load_dwordx4 v[88:91], v[114:115], off offset:1792
	s_waitcnt lgkmcnt(5)
	v_mfma_f32_32x32x16_bf16 v[52:67], v[168:171], v[164:167], v[52:67]
	global_load_dwordx4 v[92:95], v[116:117], off offset:1792
	s_waitcnt lgkmcnt(4)
	v_mfma_f32_32x32x16_bf16 v[36:51], v[172:175], v[164:167], v[36:51]
	global_load_dwordx4 v[96:99], v[118:119], off offset:1792
	s_waitcnt lgkmcnt(3)
	v_mfma_f32_32x32x16_bf16 v[20:35], v[168:171], v[176:179], v[20:35]
	v_mfma_f32_32x32x16_bf16 v[4:19], v[172:175], v[176:179], v[4:19]
	s_setprio 0
	s_waitcnt lgkmcnt(0)
	s_barrier
	ds_read_b128 v[148:151], v181
	ds_read_b128 v[152:155], v182 offset:18432
	ds_read_b128 v[156:159], v182 offset:23040
	ds_read_b128 v[160:163], v181 offset:4608
	ds_read_b128 v[164:167], v181 offset:32
	ds_read_b128 v[168:171], v182 offset:18464
	ds_read_b128 v[172:175], v182 offset:23072
	ds_read_b128 v[176:179], v181 offset:4640
	s_setprio 1
	s_waitcnt lgkmcnt(6)
	v_mfma_f32_32x32x16_bf16 v[52:67], v[152:155], v[148:151], v[52:67]
	s_waitcnt vmcnt(15)
	ds_write_b128 v180, v[100:103]
	s_waitcnt lgkmcnt(6)
	v_mfma_f32_32x32x16_bf16 v[36:51], v[156:159], v[148:151], v[36:51]
	s_waitcnt vmcnt(14)
	ds_write_b128 v180, v[120:123] offset:4608
	s_waitcnt lgkmcnt(6)
	v_mfma_f32_32x32x16_bf16 v[20:35], v[152:155], v[160:163], v[20:35]
	s_waitcnt vmcnt(13)
	ds_write_b128 v180, v[124:127] offset:9216
	global_load_dwordx4 v[100:103], v[106:107], off offset:1920
	v_mfma_f32_32x32x16_bf16 v[4:19], v[156:159], v[160:163], v[4:19]
	ds_read_b128 v[148:151], v181 offset:64
	ds_read_b128 v[152:155], v182 offset:18496
	s_waitcnt lgkmcnt(7)
	v_mfma_f32_32x32x16_bf16 v[52:67], v[168:171], v[164:167], v[52:67]
	ds_read_b128 v[156:159], v182 offset:23104
	ds_read_b128 v[160:163], v181 offset:4672
	s_waitcnt lgkmcnt(8)
	v_mfma_f32_32x32x16_bf16 v[36:51], v[172:175], v[164:167], v[36:51]
	s_waitcnt vmcnt(13)
	ds_write_b128 v180, v[128:131] offset:13824
	global_load_dwordx4 v[120:123], v[108:109], off offset:1920
	s_waitcnt lgkmcnt(8)
	v_mfma_f32_32x32x16_bf16 v[20:35], v[168:171], v[176:179], v[20:35]
	s_waitcnt vmcnt(13)
	ds_write_b128 v180, v[132:135] offset:18432
	global_load_dwordx4 v[124:127], v[110:111], off offset:1920
	v_mfma_f32_32x32x16_bf16 v[4:19], v[172:175], v[176:179], v[4:19]
	ds_read_b128 v[164:167], v181 offset:96
	ds_read_b128 v[168:171], v182 offset:18528
	s_waitcnt lgkmcnt(6)
	v_mfma_f32_32x32x16_bf16 v[52:67], v[152:155], v[148:151], v[52:67]
	ds_read_b128 v[172:175], v182 offset:23136
	ds_read_b128 v[176:179], v181 offset:4704
	s_waitcnt lgkmcnt(7)
	v_mfma_f32_32x32x16_bf16 v[36:51], v[156:159], v[148:151], v[36:51]
	s_waitcnt vmcnt(13)
	ds_write_b128 v180, v[136:139] offset:23040
	global_load_dwordx4 v[128:131], v[112:113], off offset:1920
	s_waitcnt lgkmcnt(7)
	v_mfma_f32_32x32x16_bf16 v[20:35], v[152:155], v[160:163], v[20:35]
	s_waitcnt vmcnt(13)
	ds_write_b128 v180, v[140:143] offset:27648
	global_load_dwordx4 v[132:135], v[104:105], off offset:1920
	v_mfma_f32_32x32x16_bf16 v[4:19], v[156:159], v[160:163], v[4:19]
	s_waitcnt vmcnt(13)
	ds_write_b128 v180, v[144:147] offset:32256
	global_load_dwordx4 v[136:139], v[114:115], off offset:1920
	s_waitcnt lgkmcnt(5)
	v_mfma_f32_32x32x16_bf16 v[52:67], v[168:171], v[164:167], v[52:67]
	global_load_dwordx4 v[140:143], v[116:117], off offset:1920
	s_waitcnt lgkmcnt(4)
	v_mfma_f32_32x32x16_bf16 v[36:51], v[172:175], v[164:167], v[36:51]
	global_load_dwordx4 v[144:147], v[118:119], off offset:1920
	s_waitcnt lgkmcnt(3)
	v_mfma_f32_32x32x16_bf16 v[20:35], v[168:171], v[176:179], v[20:35]
	v_mfma_f32_32x32x16_bf16 v[4:19], v[172:175], v[176:179], v[4:19]
	s_setprio 0
	s_waitcnt lgkmcnt(0)
	s_barrier
	ds_read_b128 v[148:151], v181 offset:36864
	ds_read_b128 v[152:155], v182 offset:55296
	ds_read_b128 v[156:159], v182 offset:59904
	ds_read_b128 v[160:163], v181 offset:41472
	ds_read_b128 v[164:167], v181 offset:36896
	ds_read_b128 v[168:171], v182 offset:55328
	ds_read_b128 v[172:175], v182 offset:59936
	ds_read_b128 v[176:179], v181 offset:41504
	s_setprio 1
	s_waitcnt lgkmcnt(6)
	v_mfma_f32_32x32x16_bf16 v[52:67], v[152:155], v[148:151], v[52:67]
	s_waitcnt vmcnt(15)
	ds_write_b128 v2, v[68:71]
	s_waitcnt lgkmcnt(6)
	v_mfma_f32_32x32x16_bf16 v[36:51], v[156:159], v[148:151], v[36:51]
	s_waitcnt vmcnt(14)
	ds_write_b128 v2, v[72:75] offset:4608
	s_waitcnt lgkmcnt(6)
	v_mfma_f32_32x32x16_bf16 v[20:35], v[152:155], v[160:163], v[20:35]
	s_waitcnt vmcnt(13)
	ds_write_b128 v2, v[76:79] offset:9216
	v_mfma_f32_32x32x16_bf16 v[4:19], v[156:159], v[160:163], v[4:19]
	ds_read_b128 v[148:151], v181 offset:36928
	ds_read_b128 v[152:155], v182 offset:55360
	s_waitcnt lgkmcnt(7)
	v_mfma_f32_32x32x16_bf16 v[52:67], v[168:171], v[164:167], v[52:67]
	ds_read_b128 v[156:159], v182 offset:59968
	ds_read_b128 v[160:163], v181 offset:41536
	s_waitcnt lgkmcnt(8)
	v_mfma_f32_32x32x16_bf16 v[36:51], v[172:175], v[164:167], v[36:51]
	s_waitcnt vmcnt(12)
	ds_write_b128 v2, v[80:83] offset:13824
	s_waitcnt lgkmcnt(8)
	v_mfma_f32_32x32x16_bf16 v[20:35], v[168:171], v[176:179], v[20:35]
	s_waitcnt vmcnt(11)
	ds_write_b128 v2, v[84:87] offset:18432
	v_mfma_f32_32x32x16_bf16 v[4:19], v[172:175], v[176:179], v[4:19]
	ds_read_b128 v[164:167], v181 offset:36960
	ds_read_b128 v[168:171], v182 offset:55392
	s_waitcnt lgkmcnt(6)
	v_mfma_f32_32x32x16_bf16 v[52:67], v[152:155], v[148:151], v[52:67]
	ds_read_b128 v[172:175], v182 offset:60000
	ds_read_b128 v[176:179], v181 offset:41568
	s_waitcnt lgkmcnt(7)
	v_mfma_f32_32x32x16_bf16 v[36:51], v[156:159], v[148:151], v[36:51]
	s_waitcnt vmcnt(10)
	ds_write_b128 v2, v[88:91] offset:23040
	s_waitcnt lgkmcnt(7)
	v_mfma_f32_32x32x16_bf16 v[20:35], v[152:155], v[160:163], v[20:35]
	s_waitcnt vmcnt(9)
	ds_write_b128 v2, v[92:95] offset:27648
	v_mfma_f32_32x32x16_bf16 v[4:19], v[156:159], v[160:163], v[4:19]
	s_waitcnt vmcnt(8)
	ds_write_b128 v2, v[96:99] offset:32256
	s_waitcnt lgkmcnt(5)
	v_mfma_f32_32x32x16_bf16 v[52:67], v[168:171], v[164:167], v[52:67]
	s_waitcnt lgkmcnt(4)
	v_mfma_f32_32x32x16_bf16 v[36:51], v[172:175], v[164:167], v[36:51]
	s_waitcnt lgkmcnt(3)
	v_mfma_f32_32x32x16_bf16 v[20:35], v[168:171], v[176:179], v[20:35]
	v_mfma_f32_32x32x16_bf16 v[4:19], v[172:175], v[176:179], v[4:19]
	s_setprio 0
	s_waitcnt lgkmcnt(0)
	s_barrier
	ds_read_b128 v[148:151], v181
	ds_read_b128 v[152:155], v182 offset:18432
	ds_read_b128 v[156:159], v182 offset:23040
	ds_read_b128 v[160:163], v181 offset:4608
	ds_read_b128 v[164:167], v181 offset:32
	ds_read_b128 v[168:171], v182 offset:18464
	ds_read_b128 v[172:175], v182 offset:23072
	ds_read_b128 v[176:179], v181 offset:4640
	s_setprio 1
	s_waitcnt lgkmcnt(6)
	v_mfma_f32_32x32x16_bf16 v[52:67], v[152:155], v[148:151], v[52:67]
	s_waitcnt vmcnt(7)
	ds_write_b128 v180, v[100:103]
	s_waitcnt lgkmcnt(6)
	v_mfma_f32_32x32x16_bf16 v[36:51], v[156:159], v[148:151], v[36:51]
	s_waitcnt vmcnt(6)
	ds_write_b128 v180, v[120:123] offset:4608
	s_waitcnt lgkmcnt(6)
	v_mfma_f32_32x32x16_bf16 v[20:35], v[152:155], v[160:163], v[20:35]
	s_waitcnt vmcnt(5)
	ds_write_b128 v180, v[124:127] offset:9216
	v_mfma_f32_32x32x16_bf16 v[4:19], v[156:159], v[160:163], v[4:19]
	ds_read_b128 v[148:151], v181 offset:64
	ds_read_b128 v[152:155], v182 offset:18496
	s_waitcnt lgkmcnt(7)
	v_mfma_f32_32x32x16_bf16 v[52:67], v[168:171], v[164:167], v[52:67]
	ds_read_b128 v[156:159], v182 offset:23104
	ds_read_b128 v[160:163], v181 offset:4672
	s_waitcnt lgkmcnt(8)
	v_mfma_f32_32x32x16_bf16 v[36:51], v[172:175], v[164:167], v[36:51]
	s_waitcnt vmcnt(4)
	ds_write_b128 v180, v[128:131] offset:13824
	s_waitcnt lgkmcnt(8)
	v_mfma_f32_32x32x16_bf16 v[20:35], v[168:171], v[176:179], v[20:35]
	s_waitcnt vmcnt(3)
	ds_write_b128 v180, v[132:135] offset:18432
	v_mfma_f32_32x32x16_bf16 v[4:19], v[172:175], v[176:179], v[4:19]
	ds_read_b128 v[164:167], v181 offset:96
	ds_read_b128 v[168:171], v182 offset:18528
	s_waitcnt lgkmcnt(6)
	v_mfma_f32_32x32x16_bf16 v[52:67], v[152:155], v[148:151], v[52:67]
	ds_read_b128 v[172:175], v182 offset:23136
	ds_read_b128 v[176:179], v181 offset:4704
	s_waitcnt lgkmcnt(7)
	v_mfma_f32_32x32x16_bf16 v[36:51], v[156:159], v[148:151], v[36:51]
	s_waitcnt vmcnt(2)
	ds_write_b128 v180, v[136:139] offset:23040
	s_waitcnt lgkmcnt(7)
	v_mfma_f32_32x32x16_bf16 v[20:35], v[152:155], v[160:163], v[20:35]
	s_waitcnt vmcnt(1)
	ds_write_b128 v180, v[140:143] offset:27648
	v_mfma_f32_32x32x16_bf16 v[4:19], v[156:159], v[160:163], v[4:19]
	s_waitcnt vmcnt(0)
	ds_write_b128 v180, v[144:147] offset:32256
	s_waitcnt lgkmcnt(5)
	v_mfma_f32_32x32x16_bf16 v[52:67], v[168:171], v[164:167], v[52:67]
	s_waitcnt lgkmcnt(4)
	v_mfma_f32_32x32x16_bf16 v[36:51], v[172:175], v[164:167], v[36:51]
	s_waitcnt lgkmcnt(3)
	v_mfma_f32_32x32x16_bf16 v[20:35], v[168:171], v[176:179], v[20:35]
	v_mfma_f32_32x32x16_bf16 v[4:19], v[172:175], v[176:179], v[4:19]
	s_setprio 0
	s_waitcnt lgkmcnt(0)
	s_barrier
	ds_read_b128 v[148:151], v181 offset:36864
	ds_read_b128 v[152:155], v182 offset:55296
	ds_read_b128 v[156:159], v182 offset:59904
	ds_read_b128 v[160:163], v181 offset:41472
	ds_read_b128 v[164:167], v181 offset:36896
	ds_read_b128 v[168:171], v182 offset:55328
	ds_read_b128 v[172:175], v182 offset:59936
	ds_read_b128 v[176:179], v181 offset:41504
	s_setprio 1
	s_waitcnt lgkmcnt(6)
	v_mfma_f32_32x32x16_bf16 v[52:67], v[152:155], v[148:151], v[52:67]
	s_waitcnt lgkmcnt(5)
	v_mfma_f32_32x32x16_bf16 v[36:51], v[156:159], v[148:151], v[36:51]
	s_waitcnt lgkmcnt(4)
	v_mfma_f32_32x32x16_bf16 v[20:35], v[152:155], v[160:163], v[20:35]
	v_mfma_f32_32x32x16_bf16 v[4:19], v[156:159], v[160:163], v[4:19]
	ds_read_b128 v[148:151], v181 offset:36928
	ds_read_b128 v[152:155], v182 offset:55360
	s_waitcnt lgkmcnt(4)
	v_mfma_f32_32x32x16_bf16 v[52:67], v[168:171], v[164:167], v[52:67]
	ds_read_b128 v[156:159], v182 offset:59968
	ds_read_b128 v[160:163], v181 offset:41536
	s_waitcnt lgkmcnt(5)
	v_mfma_f32_32x32x16_bf16 v[36:51], v[172:175], v[164:167], v[36:51]
	s_waitcnt lgkmcnt(4)
	v_mfma_f32_32x32x16_bf16 v[20:35], v[168:171], v[176:179], v[20:35]
	v_mfma_f32_32x32x16_bf16 v[4:19], v[172:175], v[176:179], v[4:19]
	ds_read_b128 v[164:167], v181 offset:36960
	ds_read_b128 v[168:171], v182 offset:55392
	s_waitcnt lgkmcnt(4)
	v_mfma_f32_32x32x16_bf16 v[52:67], v[152:155], v[148:151], v[52:67]
	ds_read_b128 v[172:175], v182 offset:60000
	ds_read_b128 v[176:179], v181 offset:41568
	s_waitcnt lgkmcnt(5)
	v_mfma_f32_32x32x16_bf16 v[36:51], v[156:159], v[148:151], v[36:51]
	s_waitcnt lgkmcnt(4)
	v_mfma_f32_32x32x16_bf16 v[20:35], v[152:155], v[160:163], v[20:35]
	v_mfma_f32_32x32x16_bf16 v[4:19], v[156:159], v[160:163], v[4:19]
	s_waitcnt lgkmcnt(2)
	v_mfma_f32_32x32x16_bf16 v[52:67], v[168:171], v[164:167], v[52:67]
	s_waitcnt lgkmcnt(1)
	v_mfma_f32_32x32x16_bf16 v[36:51], v[172:175], v[164:167], v[36:51]
	s_waitcnt lgkmcnt(0)
	v_mfma_f32_32x32x16_bf16 v[20:35], v[168:171], v[176:179], v[20:35]
	v_mfma_f32_32x32x16_bf16 v[4:19], v[172:175], v[176:179], v[4:19]
	s_setprio 0
	s_nop 7
	s_nop 4
	v_sub_co_u32_e64 v2, s[0:1], s15, v184
	s_nop 0
	v_readfirstlane_b32 s42, v2
	s_mov_b64 s[10:11], -1
	s_and_b64 vcc, exec, s[4:5]
	s_barrier
	s_cbranch_vccz .LBB0_53
	s_lshl_b32 s7, s16, 2
	s_add_u32 s8, s70, s7
	s_addc_u32 s9, s71, 0
	s_mov_b64 s[10:11], 0

.LBB0_300:
	s_and_b32 s0, s76, 0xfffffe00
	s_cmpk_eq_i32 s0, 0xc00
	s_cselect_b64 s[0:1], -1, 0
	s_and_b64 s[0:1], s[26:27], s[0:1]
	s_cmpk_lt_i32 s76, 0xd00
	s_movk_i32 s2, 0xff00
	s_cselect_b32 s2, 0x100, s2
	s_and_b64 s[0:1], s[0:1], exec
	s_cselect_b32 s77, s2, 0
	s_add_i32 s77, s77, s76
	s_cmpk_lt_i32 s77, 0xd00
	s_mov_b64 s[0:1], -1
	s_cbranch_scc0 .LBB0_423
	s_mov_b32 s0, 0x10000
	s_mov_b32 s1, 0
	v_lshl_add_u64 v[134:135], s[0:1], 0, v[148:149]
	s_mov_b32 s0, 0x20000
	s_mov_b32 s1, 0
	v_lshl_add_u64 v[176:177], s[0:1], 0, v[148:149]
	s_mov_b32 s0, 0x30000
	s_mov_b32 s1, 0
	v_lshl_add_u64 v[178:179], s[0:1], 0, v[148:149]
	s_mov_b32 s0, 0x10000
	s_mov_b32 s1, 0
	v_lshl_add_u64 v[180:181], s[0:1], 0, v[150:151]
	s_mov_b32 s0, 0x20000
	s_mov_b32 s1, 0
	v_lshl_add_u64 v[182:183], s[0:1], 0, v[150:151]
	s_mov_b32 s0, 0x30000
	s_mov_b32 s1, 0
	v_lshl_add_u64 v[184:185], s[0:1], 0, v[150:151]
	v_lshrrev_b32_e32 v172, 3, v0
	v_lshlrev_b32_e32 v173, 4, v0
	v_mul_u32_u24_e32 v172, 0x90, v172
	v_and_b32_e32 v173, 0x70, v173
	v_add_u32_e32 v186, v172, v173
	v_add_u32_e32 v187, 0x9000, v186
	v_lshrrev_b32_e32 v172, 1, v0
	v_and_b32_e32 v173, 31, v0
	v_and_b32_e32 v174, 16, v172
	v_and_b32_e32 v172, 64, v172
	v_add_u32_e32 v172, v172, v173
	v_mul_u32_u24_e32 v172, 0x90, v172
	v_add_u32_e32 v194, v172, v174
	v_and_b32_e32 v172, 64, v0
	v_add_u32_e32 v172, v172, v173
	v_mul_u32_u24_e32 v172, 0x90, v172
	v_add_u32_e32 v195, v172, v174
	s_barrier
	s_waitcnt vmcnt(15)
	ds_write_b128 v186, v[68:71]
	s_waitcnt vmcnt(13)
	ds_write_b128 v186, v[72:75] offset:4608
	s_waitcnt vmcnt(11)
	ds_write_b128 v186, v[76:79] offset:9216
	s_waitcnt vmcnt(9)
	ds_write_b128 v186, v[80:83] offset:13824
	s_waitcnt vmcnt(7)
	ds_write_b128 v186, v[84:87] offset:18432
	s_waitcnt vmcnt(5)
	ds_write_b128 v186, v[88:91] offset:23040
	s_waitcnt vmcnt(3)
	ds_write_b128 v186, v[92:95] offset:27648
	s_waitcnt vmcnt(1)
	ds_write_b128 v186, v[96:99] offset:32256
	global_load_dwordx4 v[68:71], v[148:149], off offset:256
	global_load_dwordx4 v[72:75], v[134:135], off offset:256
	global_load_dwordx4 v[76:79], v[176:177], off offset:256
	global_load_dwordx4 v[80:83], v[178:179], off offset:256
	global_load_dwordx4 v[84:87], v[150:151], off offset:256
	global_load_dwordx4 v[88:91], v[180:181], off offset:256
	global_load_dwordx4 v[92:95], v[182:183], off offset:256
	global_load_dwordx4 v[96:99], v[184:185], off offset:256
	s_waitcnt lgkmcnt(0)
	s_barrier
	ds_read_b128 v[136:139], v194
	ds_read_b128 v[140:143], v195 offset:18432
	ds_read_b128 v[152:155], v195 offset:23040
	ds_read_b128 v[156:159], v194 offset:4608
	ds_read_b128 v[160:163], v194 offset:32
	ds_read_b128 v[164:167], v195 offset:18464
	ds_read_b128 v[168:171], v195 offset:23072
	ds_read_b128 v[172:175], v194 offset:4640
	s_setprio 1
	s_waitcnt lgkmcnt(6)
	v_mfma_f32_32x32x16_bf16 v[52:67], v[140:143], v[136:139], 0
	ds_write_b128 v187, v[100:103]
	s_waitcnt lgkmcnt(6)
	v_mfma_f32_32x32x16_bf16 v[36:51], v[152:155], v[136:139], 0
	ds_write_b128 v187, v[104:107] offset:4608
	s_waitcnt lgkmcnt(6)
	v_mfma_f32_32x32x16_bf16 v[20:35], v[140:143], v[156:159], 0
	ds_write_b128 v187, v[108:111] offset:9216
	global_load_dwordx4 v[100:103], v[148:149], off offset:384
	v_mfma_f32_32x32x16_bf16 v[4:19], v[152:155], v[156:159], 0
	ds_read_b128 v[136:139], v194 offset:64
	ds_read_b128 v[140:143], v195 offset:18496
	s_waitcnt lgkmcnt(7)
	v_mfma_f32_32x32x16_bf16 v[52:67], v[164:167], v[160:163], v[52:67]
	ds_read_b128 v[152:155], v195 offset:23104
	ds_read_b128 v[156:159], v194 offset:4672
	s_waitcnt lgkmcnt(8)
	v_mfma_f32_32x32x16_bf16 v[36:51], v[168:171], v[160:163], v[36:51]
	ds_write_b128 v187, v[112:115] offset:13824
	global_load_dwordx4 v[104:107], v[134:135], off offset:384
	s_waitcnt lgkmcnt(8)
	v_mfma_f32_32x32x16_bf16 v[20:35], v[164:167], v[172:175], v[20:35]
	ds_write_b128 v187, v[116:119] offset:18432
	global_load_dwordx4 v[108:111], v[176:177], off offset:384
	v_mfma_f32_32x32x16_bf16 v[4:19], v[168:171], v[172:175], v[4:19]
	ds_read_b128 v[160:163], v194 offset:96
	ds_read_b128 v[164:167], v195 offset:18528
	s_waitcnt lgkmcnt(6)
	v_mfma_f32_32x32x16_bf16 v[52:67], v[140:143], v[136:139], v[52:67]
	ds_read_b128 v[168:171], v195 offset:23136
	ds_read_b128 v[172:175], v194 offset:4704
	s_waitcnt lgkmcnt(7)
	v_mfma_f32_32x32x16_bf16 v[36:51], v[152:155], v[136:139], v[36:51]
	ds_write_b128 v187, v[120:123] offset:23040
	global_load_dwordx4 v[112:115], v[178:179], off offset:384
	s_waitcnt lgkmcnt(7)
	v_mfma_f32_32x32x16_bf16 v[20:35], v[140:143], v[156:159], v[20:35]
	ds_write_b128 v187, v[124:127] offset:27648
	global_load_dwordx4 v[116:119], v[150:151], off offset:384
	v_mfma_f32_32x32x16_bf16 v[4:19], v[152:155], v[156:159], v[4:19]
	s_waitcnt vmcnt(13)
	ds_write_b128 v187, v[128:131] offset:32256
	global_load_dwordx4 v[120:123], v[180:181], off offset:384
	s_waitcnt lgkmcnt(5)
	v_mfma_f32_32x32x16_bf16 v[52:67], v[164:167], v[160:163], v[52:67]
	global_load_dwordx4 v[124:127], v[182:183], off offset:384
	s_waitcnt lgkmcnt(4)
	v_mfma_f32_32x32x16_bf16 v[36:51], v[168:171], v[160:163], v[36:51]
	global_load_dwordx4 v[128:131], v[184:185], off offset:384
	s_waitcnt lgkmcnt(3)
	v_mfma_f32_32x32x16_bf16 v[20:35], v[164:167], v[172:175], v[20:35]
	v_mfma_f32_32x32x16_bf16 v[4:19], v[168:171], v[172:175], v[4:19]
	s_setprio 0
	s_waitcnt lgkmcnt(0)
	s_barrier
	ds_read_b128 v[136:139], v194 offset:36864
	ds_read_b128 v[140:143], v195 offset:55296
	ds_read_b128 v[152:155], v195 offset:59904
	ds_read_b128 v[156:159], v194 offset:41472
	ds_read_b128 v[160:163], v194 offset:36896
	ds_read_b128 v[164:167], v195 offset:55328
	ds_read_b128 v[168:171], v195 offset:59936
	ds_read_b128 v[172:175], v194 offset:41504
	s_setprio 1
	s_waitcnt lgkmcnt(6)
	v_mfma_f32_32x32x16_bf16 v[52:67], v[140:143], v[136:139], v[52:67]
	s_waitcnt vmcnt(15)
	ds_write_b128 v186, v[68:71]
	s_waitcnt lgkmcnt(6)
	v_mfma_f32_32x32x16_bf16 v[36:51], v[152:155], v[136:139], v[36:51]
	s_waitcnt vmcnt(14)
	ds_write_b128 v186, v[72:75] offset:4608
	s_waitcnt lgkmcnt(6)
	v_mfma_f32_32x32x16_bf16 v[20:35], v[140:143], v[156:159], v[20:35]
	s_waitcnt vmcnt(13)
	ds_write_b128 v186, v[76:79] offset:9216
	global_load_dwordx4 v[68:71], v[148:149], off offset:512
	v_mfma_f32_32x32x16_bf16 v[4:19], v[152:155], v[156:159], v[4:19]
	ds_read_b128 v[136:139], v194 offset:36928
	ds_read_b128 v[140:143], v195 offset:55360
	s_waitcnt lgkmcnt(7)
	v_mfma_f32_32x32x16_bf16 v[52:67], v[164:167], v[160:163], v[52:67]
	ds_read_b128 v[152:155], v195 offset:59968
	ds_read_b128 v[156:159], v194 offset:41536
	s_waitcnt lgkmcnt(8)
	v_mfma_f32_32x32x16_bf16 v[36:51], v[168:171], v[160:163], v[36:51]
	s_waitcnt vmcnt(13)
	ds_write_b128 v186, v[80:83] offset:13824
	global_load_dwordx4 v[72:75], v[134:135], off offset:512
	s_waitcnt lgkmcnt(8)
	v_mfma_f32_32x32x16_bf16 v[20:35], v[164:167], v[172:175], v[20:35]
	s_waitcnt vmcnt(13)
	ds_write_b128 v186, v[84:87] offset:18432
	global_load_dwordx4 v[76:79], v[176:177], off offset:512
	v_mfma_f32_32x32x16_bf16 v[4:19], v[168:171], v[172:175], v[4:19]
	ds_read_b128 v[160:163], v194 offset:36960
	ds_read_b128 v[164:167], v195 offset:55392
	s_waitcnt lgkmcnt(6)
	v_mfma_f32_32x32x16_bf16 v[52:67], v[140:143], v[136:139], v[52:67]
	ds_read_b128 v[168:171], v195 offset:60000
	ds_read_b128 v[172:175], v194 offset:41568
	s_waitcnt lgkmcnt(7)
	v_mfma_f32_32x32x16_bf16 v[36:51], v[152:155], v[136:139], v[36:51]
	s_waitcnt vmcnt(13)
	ds_write_b128 v186, v[88:91] offset:23040
	global_load_dwordx4 v[80:83], v[178:179], off offset:512
	s_waitcnt lgkmcnt(7)
	v_mfma_f32_32x32x16_bf16 v[20:35], v[140:143], v[156:159], v[20:35]
	s_waitcnt vmcnt(13)
	ds_write_b128 v186, v[92:95] offset:27648
	global_load_dwordx4 v[84:87], v[150:151], off offset:512
	v_mfma_f32_32x32x16_bf16 v[4:19], v[152:155], v[156:159], v[4:19]
	s_waitcnt vmcnt(13)
	ds_write_b128 v186, v[96:99] offset:32256
	global_load_dwordx4 v[88:91], v[180:181], off offset:512
	s_waitcnt lgkmcnt(5)
	v_mfma_f32_32x32x16_bf16 v[52:67], v[164:167], v[160:163], v[52:67]
	global_load_dwordx4 v[92:95], v[182:183], off offset:512
	s_waitcnt lgkmcnt(4)
	v_mfma_f32_32x32x16_bf16 v[36:51], v[168:171], v[160:163], v[36:51]
	global_load_dwordx4 v[96:99], v[184:185], off offset:512
	s_waitcnt lgkmcnt(3)
	v_mfma_f32_32x32x16_bf16 v[20:35], v[164:167], v[172:175], v[20:35]
	v_mfma_f32_32x32x16_bf16 v[4:19], v[168:171], v[172:175], v[4:19]
	s_setprio 0
	s_waitcnt lgkmcnt(0)
	s_barrier
	ds_read_b128 v[136:139], v194
	ds_read_b128 v[140:143], v195 offset:18432
	ds_read_b128 v[152:155], v195 offset:23040
	ds_read_b128 v[156:159], v194 offset:4608
	ds_read_b128 v[160:163], v194 offset:32
	ds_read_b128 v[164:167], v195 offset:18464
	ds_read_b128 v[168:171], v195 offset:23072
	ds_read_b128 v[172:175], v194 offset:4640
	s_setprio 1
	s_waitcnt lgkmcnt(6)
	v_mfma_f32_32x32x16_bf16 v[52:67], v[140:143], v[136:139], v[52:67]
	s_waitcnt vmcnt(15)
	ds_write_b128 v187, v[100:103]
	s_waitcnt lgkmcnt(6)
	v_mfma_f32_32x32x16_bf16 v[36:51], v[152:155], v[136:139], v[36:51]
	s_waitcnt vmcnt(14)
	ds_write_b128 v187, v[104:107] offset:4608
	s_waitcnt lgkmcnt(6)
	v_mfma_f32_32x32x16_bf16 v[20:35], v[140:143], v[156:159], v[20:35]
	s_waitcnt vmcnt(13)
	ds_write_b128 v187, v[108:111] offset:9216
	global_load_dwordx4 v[100:103], v[148:149], off offset:640
	v_mfma_f32_32x32x16_bf16 v[4:19], v[152:155], v[156:159], v[4:19]
	ds_read_b128 v[136:139], v194 offset:64
	ds_read_b128 v[140:143], v195 offset:18496
	s_waitcnt lgkmcnt(7)
	v_mfma_f32_32x32x16_bf16 v[52:67], v[164:167], v[160:163], v[52:67]
	ds_read_b128 v[152:155], v195 offset:23104
	ds_read_b128 v[156:159], v194 offset:4672
	s_waitcnt lgkmcnt(8)
	v_mfma_f32_32x32x16_bf16 v[36:51], v[168:171], v[160:163], v[36:51]
	s_waitcnt vmcnt(13)
	ds_write_b128 v187, v[112:115] offset:13824
	global_load_dwordx4 v[104:107], v[134:135], off offset:640
	s_waitcnt lgkmcnt(8)
	v_mfma_f32_32x32x16_bf16 v[20:35], v[164:167], v[172:175], v[20:35]
	s_waitcnt vmcnt(13)
	ds_write_b128 v187, v[116:119] offset:18432
	global_load_dwordx4 v[108:111], v[176:177], off offset:640
	v_mfma_f32_32x32x16_bf16 v[4:19], v[168:171], v[172:175], v[4:19]
	ds_read_b128 v[160:163], v194 offset:96
	ds_read_b128 v[164:167], v195 offset:18528
	s_waitcnt lgkmcnt(6)
	v_mfma_f32_32x32x16_bf16 v[52:67], v[140:143], v[136:139], v[52:67]
	ds_read_b128 v[168:171], v195 offset:23136
	ds_read_b128 v[172:175], v194 offset:4704
	s_waitcnt lgkmcnt(7)
	v_mfma_f32_32x32x16_bf16 v[36:51], v[152:155], v[136:139], v[36:51]
	s_waitcnt vmcnt(13)
	ds_write_b128 v187, v[120:123] offset:23040
	global_load_dwordx4 v[112:115], v[178:179], off offset:640
	s_waitcnt lgkmcnt(7)
	v_mfma_f32_32x32x16_bf16 v[20:35], v[140:143], v[156:159], v[20:35]
	s_waitcnt vmcnt(13)
	ds_write_b128 v187, v[124:127] offset:27648
	global_load_dwordx4 v[116:119], v[150:151], off offset:640
	v_mfma_f32_32x32x16_bf16 v[4:19], v[152:155], v[156:159], v[4:19]
	s_waitcnt vmcnt(13)
	ds_write_b128 v187, v[128:131] offset:32256
	global_load_dwordx4 v[120:123], v[180:181], off offset:640
	s_waitcnt lgkmcnt(5)
	v_mfma_f32_32x32x16_bf16 v[52:67], v[164:167], v[160:163], v[52:67]
	global_load_dwordx4 v[124:127], v[182:183], off offset:640
	s_waitcnt lgkmcnt(4)
	v_mfma_f32_32x32x16_bf16 v[36:51], v[168:171], v[160:163], v[36:51]
	global_load_dwordx4 v[128:131], v[184:185], off offset:640
	s_waitcnt lgkmcnt(3)
	v_mfma_f32_32x32x16_bf16 v[20:35], v[164:167], v[172:175], v[20:35]
	v_mfma_f32_32x32x16_bf16 v[4:19], v[168:171], v[172:175], v[4:19]
	s_setprio 0
	s_waitcnt lgkmcnt(0)
	s_barrier
	ds_read_b128 v[136:139], v194 offset:36864
	ds_read_b128 v[140:143], v195 offset:55296
	ds_read_b128 v[152:155], v195 offset:59904
	ds_read_b128 v[156:159], v194 offset:41472
	ds_read_b128 v[160:163], v194 offset:36896
	ds_read_b128 v[164:167], v195 offset:55328
	ds_read_b128 v[168:171], v195 offset:59936
	ds_read_b128 v[172:175], v194 offset:41504
	s_setprio 1
	s_waitcnt lgkmcnt(6)
	v_mfma_f32_32x32x16_bf16 v[52:67], v[140:143], v[136:139], v[52:67]
	s_waitcnt vmcnt(15)
	ds_write_b128 v186, v[68:71]
	s_waitcnt lgkmcnt(6)
	v_mfma_f32_32x32x16_bf16 v[36:51], v[152:155], v[136:139], v[36:51]
	s_waitcnt vmcnt(14)
	ds_write_b128 v186, v[72:75] offset:4608
	s_waitcnt lgkmcnt(6)
	v_mfma_f32_32x32x16_bf16 v[20:35], v[140:143], v[156:159], v[20:35]
	s_waitcnt vmcnt(13)
	ds_write_b128 v186, v[76:79] offset:9216
	global_load_dwordx4 v[68:71], v[148:149], off offset:768
	v_mfma_f32_32x32x16_bf16 v[4:19], v[152:155], v[156:159], v[4:19]
	ds_read_b128 v[136:139], v194 offset:36928
	ds_read_b128 v[140:143], v195 offset:55360
	s_waitcnt lgkmcnt(7)
	v_mfma_f32_32x32x16_bf16 v[52:67], v[164:167], v[160:163], v[52:67]
	ds_read_b128 v[152:155], v195 offset:59968
	ds_read_b128 v[156:159], v194 offset:41536
	s_waitcnt lgkmcnt(8)
	v_mfma_f32_32x32x16_bf16 v[36:51], v[168:171], v[160:163], v[36:51]
	s_waitcnt vmcnt(13)
	ds_write_b128 v186, v[80:83] offset:13824
	global_load_dwordx4 v[72:75], v[134:135], off offset:768
	s_waitcnt lgkmcnt(8)
	v_mfma_f32_32x32x16_bf16 v[20:35], v[164:167], v[172:175], v[20:35]
	s_waitcnt vmcnt(13)
	ds_write_b128 v186, v[84:87] offset:18432
	global_load_dwordx4 v[76:79], v[176:177], off offset:768
	v_mfma_f32_32x32x16_bf16 v[4:19], v[168:171], v[172:175], v[4:19]
	ds_read_b128 v[160:163], v194 offset:36960
	ds_read_b128 v[164:167], v195 offset:55392
	s_waitcnt lgkmcnt(6)
	v_mfma_f32_32x32x16_bf16 v[52:67], v[140:143], v[136:139], v[52:67]
	ds_read_b128 v[168:171], v195 offset:60000
	ds_read_b128 v[172:175], v194 offset:41568
	s_waitcnt lgkmcnt(7)
	v_mfma_f32_32x32x16_bf16 v[36:51], v[152:155], v[136:139], v[36:51]
	s_waitcnt vmcnt(13)
	ds_write_b128 v186, v[88:91] offset:23040
	global_load_dwordx4 v[80:83], v[178:179], off offset:768
	s_waitcnt lgkmcnt(7)
	v_mfma_f32_32x32x16_bf16 v[20:35], v[140:143], v[156:159], v[20:35]
	s_waitcnt vmcnt(13)
	ds_write_b128 v186, v[92:95] offset:27648
	global_load_dwordx4 v[84:87], v[150:151], off offset:768
	v_mfma_f32_32x32x16_bf16 v[4:19], v[152:155], v[156:159], v[4:19]
	s_waitcnt vmcnt(13)
	ds_write_b128 v186, v[96:99] offset:32256
	global_load_dwordx4 v[88:91], v[180:181], off offset:768
	s_waitcnt lgkmcnt(5)
	v_mfma_f32_32x32x16_bf16 v[52:67], v[164:167], v[160:163], v[52:67]
	global_load_dwordx4 v[92:95], v[182:183], off offset:768
	s_waitcnt lgkmcnt(4)
	v_mfma_f32_32x32x16_bf16 v[36:51], v[168:171], v[160:163], v[36:51]
	global_load_dwordx4 v[96:99], v[184:185], off offset:768
	s_waitcnt lgkmcnt(3)
	v_mfma_f32_32x32x16_bf16 v[20:35], v[164:167], v[172:175], v[20:35]
	v_mfma_f32_32x32x16_bf16 v[4:19], v[168:171], v[172:175], v[4:19]
	s_setprio 0
	s_waitcnt lgkmcnt(0)
	s_barrier
	ds_read_b128 v[136:139], v194
	ds_read_b128 v[140:143], v195 offset:18432
	ds_read_b128 v[152:155], v195 offset:23040
	ds_read_b128 v[156:159], v194 offset:4608
	ds_read_b128 v[160:163], v194 offset:32
	ds_read_b128 v[164:167], v195 offset:18464
	ds_read_b128 v[168:171], v195 offset:23072
	ds_read_b128 v[172:175], v194 offset:4640
	s_setprio 1
	s_waitcnt lgkmcnt(6)
	v_mfma_f32_32x32x16_bf16 v[52:67], v[140:143], v[136:139], v[52:67]
	s_waitcnt vmcnt(15)
	ds_write_b128 v187, v[100:103]
	s_waitcnt lgkmcnt(6)
	v_mfma_f32_32x32x16_bf16 v[36:51], v[152:155], v[136:139], v[36:51]
	s_waitcnt vmcnt(14)
	ds_write_b128 v187, v[104:107] offset:4608
	s_waitcnt lgkmcnt(6)
	v_mfma_f32_32x32x16_bf16 v[20:35], v[140:143], v[156:159], v[20:35]
	s_waitcnt vmcnt(13)
	ds_write_b128 v187, v[108:111] offset:9216
	global_load_dwordx4 v[100:103], v[148:149], off offset:896
	v_mfma_f32_32x32x16_bf16 v[4:19], v[152:155], v[156:159], v[4:19]
	ds_read_b128 v[136:139], v194 offset:64
	ds_read_b128 v[140:143], v195 offset:18496
	s_waitcnt lgkmcnt(7)
	v_mfma_f32_32x32x16_bf16 v[52:67], v[164:167], v[160:163], v[52:67]
	ds_read_b128 v[152:155], v195 offset:23104
	ds_read_b128 v[156:159], v194 offset:4672
	s_waitcnt lgkmcnt(8)
	v_mfma_f32_32x32x16_bf16 v[36:51], v[168:171], v[160:163], v[36:51]
	s_waitcnt vmcnt(13)
	ds_write_b128 v187, v[112:115] offset:13824
	global_load_dwordx4 v[104:107], v[134:135], off offset:896
	s_waitcnt lgkmcnt(8)
	v_mfma_f32_32x32x16_bf16 v[20:35], v[164:167], v[172:175], v[20:35]
	s_waitcnt vmcnt(13)
	ds_write_b128 v187, v[116:119] offset:18432
	global_load_dwordx4 v[108:111], v[176:177], off offset:896
	v_mfma_f32_32x32x16_bf16 v[4:19], v[168:171], v[172:175], v[4:19]
	ds_read_b128 v[160:163], v194 offset:96
	ds_read_b128 v[164:167], v195 offset:18528
	s_waitcnt lgkmcnt(6)
	v_mfma_f32_32x32x16_bf16 v[52:67], v[140:143], v[136:139], v[52:67]
	ds_read_b128 v[168:171], v195 offset:23136
	ds_read_b128 v[172:175], v194 offset:4704
	s_waitcnt lgkmcnt(7)
	v_mfma_f32_32x32x16_bf16 v[36:51], v[152:155], v[136:139], v[36:51]
	s_waitcnt vmcnt(13)
	ds_write_b128 v187, v[120:123] offset:23040
	global_load_dwordx4 v[112:115], v[178:179], off offset:896
	s_waitcnt lgkmcnt(7)
	v_mfma_f32_32x32x16_bf16 v[20:35], v[140:143], v[156:159], v[20:35]
	s_waitcnt vmcnt(13)
	ds_write_b128 v187, v[124:127] offset:27648
	global_load_dwordx4 v[116:119], v[150:151], off offset:896
	v_mfma_f32_32x32x16_bf16 v[4:19], v[152:155], v[156:159], v[4:19]
	s_waitcnt vmcnt(13)
	ds_write_b128 v187, v[128:131] offset:32256
	global_load_dwordx4 v[120:123], v[180:181], off offset:896
	s_waitcnt lgkmcnt(5)
	v_mfma_f32_32x32x16_bf16 v[52:67], v[164:167], v[160:163], v[52:67]
	global_load_dwordx4 v[124:127], v[182:183], off offset:896
	s_waitcnt lgkmcnt(4)
	v_mfma_f32_32x32x16_bf16 v[36:51], v[168:171], v[160:163], v[36:51]
	global_load_dwordx4 v[128:131], v[184:185], off offset:896
	s_waitcnt lgkmcnt(3)
	v_mfma_f32_32x32x16_bf16 v[20:35], v[164:167], v[172:175], v[20:35]
	v_mfma_f32_32x32x16_bf16 v[4:19], v[168:171], v[172:175], v[4:19]
	s_setprio 0
	s_waitcnt lgkmcnt(0)
	s_barrier
	ds_read_b128 v[136:139], v194 offset:36864
	ds_read_b128 v[140:143], v195 offset:55296
	ds_read_b128 v[152:155], v195 offset:59904
	ds_read_b128 v[156:159], v194 offset:41472
	ds_read_b128 v[160:163], v194 offset:36896
	ds_read_b128 v[164:167], v195 offset:55328
	ds_read_b128 v[168:171], v195 offset:59936
	ds_read_b128 v[172:175], v194 offset:41504
	s_setprio 1
	s_waitcnt lgkmcnt(6)
	v_mfma_f32_32x32x16_bf16 v[52:67], v[140:143], v[136:139], v[52:67]
	s_waitcnt vmcnt(15)
	ds_write_b128 v186, v[68:71]
	s_waitcnt lgkmcnt(6)
	v_mfma_f32_32x32x16_bf16 v[36:51], v[152:155], v[136:139], v[36:51]
	s_waitcnt vmcnt(14)
	ds_write_b128 v186, v[72:75] offset:4608
	s_waitcnt lgkmcnt(6)
	v_mfma_f32_32x32x16_bf16 v[20:35], v[140:143], v[156:159], v[20:35]
	s_waitcnt vmcnt(13)
	ds_write_b128 v186, v[76:79] offset:9216
	global_load_dwordx4 v[68:71], v[148:149], off offset:1024
	v_mfma_f32_32x32x16_bf16 v[4:19], v[152:155], v[156:159], v[4:19]
	ds_read_b128 v[136:139], v194 offset:36928
	ds_read_b128 v[140:143], v195 offset:55360
	s_waitcnt lgkmcnt(7)
	v_mfma_f32_32x32x16_bf16 v[52:67], v[164:167], v[160:163], v[52:67]
	ds_read_b128 v[152:155], v195 offset:59968
	ds_read_b128 v[156:159], v194 offset:41536
	s_waitcnt lgkmcnt(8)
	v_mfma_f32_32x32x16_bf16 v[36:51], v[168:171], v[160:163], v[36:51]
	s_waitcnt vmcnt(13)
	ds_write_b128 v186, v[80:83] offset:13824
	global_load_dwordx4 v[72:75], v[134:135], off offset:1024
	s_waitcnt lgkmcnt(8)
	v_mfma_f32_32x32x16_bf16 v[20:35], v[164:167], v[172:175], v[20:35]
	s_waitcnt vmcnt(13)
	ds_write_b128 v186, v[84:87] offset:18432
	global_load_dwordx4 v[76:79], v[176:177], off offset:1024
	v_mfma_f32_32x32x16_bf16 v[4:19], v[168:171], v[172:175], v[4:19]
	ds_read_b128 v[160:163], v194 offset:36960
	ds_read_b128 v[164:167], v195 offset:55392
	s_waitcnt lgkmcnt(6)
	v_mfma_f32_32x32x16_bf16 v[52:67], v[140:143], v[136:139], v[52:67]
	ds_read_b128 v[168:171], v195 offset:60000
	ds_read_b128 v[172:175], v194 offset:41568
	s_waitcnt lgkmcnt(7)
	v_mfma_f32_32x32x16_bf16 v[36:51], v[152:155], v[136:139], v[36:51]
	s_waitcnt vmcnt(13)
	ds_write_b128 v186, v[88:91] offset:23040
	global_load_dwordx4 v[80:83], v[178:179], off offset:1024
	s_waitcnt lgkmcnt(7)
	v_mfma_f32_32x32x16_bf16 v[20:35], v[140:143], v[156:159], v[20:35]
	s_waitcnt vmcnt(13)
	ds_write_b128 v186, v[92:95] offset:27648
	global_load_dwordx4 v[84:87], v[150:151], off offset:1024
	v_mfma_f32_32x32x16_bf16 v[4:19], v[152:155], v[156:159], v[4:19]
	s_waitcnt vmcnt(13)
	ds_write_b128 v186, v[96:99] offset:32256
	global_load_dwordx4 v[88:91], v[180:181], off offset:1024
	s_waitcnt lgkmcnt(5)
	v_mfma_f32_32x32x16_bf16 v[52:67], v[164:167], v[160:163], v[52:67]
	global_load_dwordx4 v[92:95], v[182:183], off offset:1024
	s_waitcnt lgkmcnt(4)
	v_mfma_f32_32x32x16_bf16 v[36:51], v[168:171], v[160:163], v[36:51]
	global_load_dwordx4 v[96:99], v[184:185], off offset:1024
	s_waitcnt lgkmcnt(3)
	v_mfma_f32_32x32x16_bf16 v[20:35], v[164:167], v[172:175], v[20:35]
	v_mfma_f32_32x32x16_bf16 v[4:19], v[168:171], v[172:175], v[4:19]
	s_setprio 0
	s_waitcnt lgkmcnt(0)
	s_barrier
	ds_read_b128 v[136:139], v194
	ds_read_b128 v[140:143], v195 offset:18432
	ds_read_b128 v[152:155], v195 offset:23040
	ds_read_b128 v[156:159], v194 offset:4608
	ds_read_b128 v[160:163], v194 offset:32
	ds_read_b128 v[164:167], v195 offset:18464
	ds_read_b128 v[168:171], v195 offset:23072
	ds_read_b128 v[172:175], v194 offset:4640
	s_setprio 1
	s_waitcnt lgkmcnt(6)
	v_mfma_f32_32x32x16_bf16 v[52:67], v[140:143], v[136:139], v[52:67]
	s_waitcnt vmcnt(15)
	ds_write_b128 v187, v[100:103]
	s_waitcnt lgkmcnt(6)
	v_mfma_f32_32x32x16_bf16 v[36:51], v[152:155], v[136:139], v[36:51]
	s_waitcnt vmcnt(14)
	ds_write_b128 v187, v[104:107] offset:4608
	s_waitcnt lgkmcnt(6)
	v_mfma_f32_32x32x16_bf16 v[20:35], v[140:143], v[156:159], v[20:35]
	s_waitcnt vmcnt(13)
	ds_write_b128 v187, v[108:111] offset:9216
	global_load_dwordx4 v[100:103], v[148:149], off offset:1152
	v_mfma_f32_32x32x16_bf16 v[4:19], v[152:155], v[156:159], v[4:19]
	ds_read_b128 v[136:139], v194 offset:64
	ds_read_b128 v[140:143], v195 offset:18496
	s_waitcnt lgkmcnt(7)
	v_mfma_f32_32x32x16_bf16 v[52:67], v[164:167], v[160:163], v[52:67]
	ds_read_b128 v[152:155], v195 offset:23104
	ds_read_b128 v[156:159], v194 offset:4672
	s_waitcnt lgkmcnt(8)
	v_mfma_f32_32x32x16_bf16 v[36:51], v[168:171], v[160:163], v[36:51]
	s_waitcnt vmcnt(13)
	ds_write_b128 v187, v[112:115] offset:13824
	global_load_dwordx4 v[104:107], v[134:135], off offset:1152
	s_waitcnt lgkmcnt(8)
	v_mfma_f32_32x32x16_bf16 v[20:35], v[164:167], v[172:175], v[20:35]
	s_waitcnt vmcnt(13)
	ds_write_b128 v187, v[116:119] offset:18432
	global_load_dwordx4 v[108:111], v[176:177], off offset:1152
	v_mfma_f32_32x32x16_bf16 v[4:19], v[168:171], v[172:175], v[4:19]
	ds_read_b128 v[160:163], v194 offset:96
	ds_read_b128 v[164:167], v195 offset:18528
	s_waitcnt lgkmcnt(6)
	v_mfma_f32_32x32x16_bf16 v[52:67], v[140:143], v[136:139], v[52:67]
	ds_read_b128 v[168:171], v195 offset:23136
	ds_read_b128 v[172:175], v194 offset:4704
	s_waitcnt lgkmcnt(7)
	v_mfma_f32_32x32x16_bf16 v[36:51], v[152:155], v[136:139], v[36:51]
	s_waitcnt vmcnt(13)
	ds_write_b128 v187, v[120:123] offset:23040
	global_load_dwordx4 v[112:115], v[178:179], off offset:1152
	s_waitcnt lgkmcnt(7)
	v_mfma_f32_32x32x16_bf16 v[20:35], v[140:143], v[156:159], v[20:35]
	s_waitcnt vmcnt(13)
	ds_write_b128 v187, v[124:127] offset:27648
	global_load_dwordx4 v[116:119], v[150:151], off offset:1152
	v_mfma_f32_32x32x16_bf16 v[4:19], v[152:155], v[156:159], v[4:19]
	s_waitcnt vmcnt(13)
	ds_write_b128 v187, v[128:131] offset:32256
	global_load_dwordx4 v[120:123], v[180:181], off offset:1152
	s_waitcnt lgkmcnt(5)
	v_mfma_f32_32x32x16_bf16 v[52:67], v[164:167], v[160:163], v[52:67]
	global_load_dwordx4 v[124:127], v[182:183], off offset:1152
	s_waitcnt lgkmcnt(4)
	v_mfma_f32_32x32x16_bf16 v[36:51], v[168:171], v[160:163], v[36:51]
	global_load_dwordx4 v[128:131], v[184:185], off offset:1152
	s_waitcnt lgkmcnt(3)
	v_mfma_f32_32x32x16_bf16 v[20:35], v[164:167], v[172:175], v[20:35]
	v_mfma_f32_32x32x16_bf16 v[4:19], v[168:171], v[172:175], v[4:19]
	s_setprio 0
	s_waitcnt lgkmcnt(0)
	s_barrier
	ds_read_b128 v[136:139], v194 offset:36864
	ds_read_b128 v[140:143], v195 offset:55296
	ds_read_b128 v[152:155], v195 offset:59904
	ds_read_b128 v[156:159], v194 offset:41472
	ds_read_b128 v[160:163], v194 offset:36896
	ds_read_b128 v[164:167], v195 offset:55328
	ds_read_b128 v[168:171], v195 offset:59936
	ds_read_b128 v[172:175], v194 offset:41504
	s_setprio 1
	s_waitcnt lgkmcnt(6)
	v_mfma_f32_32x32x16_bf16 v[52:67], v[140:143], v[136:139], v[52:67]
	s_waitcnt vmcnt(15)
	ds_write_b128 v186, v[68:71]
	s_waitcnt lgkmcnt(6)
	v_mfma_f32_32x32x16_bf16 v[36:51], v[152:155], v[136:139], v[36:51]
	s_waitcnt vmcnt(14)
	ds_write_b128 v186, v[72:75] offset:4608
	s_waitcnt lgkmcnt(6)
	v_mfma_f32_32x32x16_bf16 v[20:35], v[140:143], v[156:159], v[20:35]
	s_waitcnt vmcnt(13)
	ds_write_b128 v186, v[76:79] offset:9216
	global_load_dwordx4 v[68:71], v[148:149], off offset:1280
	v_mfma_f32_32x32x16_bf16 v[4:19], v[152:155], v[156:159], v[4:19]
	ds_read_b128 v[136:139], v194 offset:36928
	ds_read_b128 v[140:143], v195 offset:55360
	s_waitcnt lgkmcnt(7)
	v_mfma_f32_32x32x16_bf16 v[52:67], v[164:167], v[160:163], v[52:67]
	ds_read_b128 v[152:155], v195 offset:59968
	ds_read_b128 v[156:159], v194 offset:41536
	s_waitcnt lgkmcnt(8)
	v_mfma_f32_32x32x16_bf16 v[36:51], v[168:171], v[160:163], v[36:51]
	s_waitcnt vmcnt(13)
	ds_write_b128 v186, v[80:83] offset:13824
	global_load_dwordx4 v[72:75], v[134:135], off offset:1280
	s_waitcnt lgkmcnt(8)
	v_mfma_f32_32x32x16_bf16 v[20:35], v[164:167], v[172:175], v[20:35]
	s_waitcnt vmcnt(13)
	ds_write_b128 v186, v[84:87] offset:18432
	global_load_dwordx4 v[76:79], v[176:177], off offset:1280
	v_mfma_f32_32x32x16_bf16 v[4:19], v[168:171], v[172:175], v[4:19]
	ds_read_b128 v[160:163], v194 offset:36960
	ds_read_b128 v[164:167], v195 offset:55392
	s_waitcnt lgkmcnt(6)
	v_mfma_f32_32x32x16_bf16 v[52:67], v[140:143], v[136:139], v[52:67]
	ds_read_b128 v[168:171], v195 offset:60000
	ds_read_b128 v[172:175], v194 offset:41568
	s_waitcnt lgkmcnt(7)
	v_mfma_f32_32x32x16_bf16 v[36:51], v[152:155], v[136:139], v[36:51]
	s_waitcnt vmcnt(13)
	ds_write_b128 v186, v[88:91] offset:23040
	global_load_dwordx4 v[80:83], v[178:179], off offset:1280
	s_waitcnt lgkmcnt(7)
	v_mfma_f32_32x32x16_bf16 v[20:35], v[140:143], v[156:159], v[20:35]
	s_waitcnt vmcnt(13)
	ds_write_b128 v186, v[92:95] offset:27648
	global_load_dwordx4 v[84:87], v[150:151], off offset:1280
	v_mfma_f32_32x32x16_bf16 v[4:19], v[152:155], v[156:159], v[4:19]
	s_waitcnt vmcnt(13)
	ds_write_b128 v186, v[96:99] offset:32256
	global_load_dwordx4 v[88:91], v[180:181], off offset:1280
	s_waitcnt lgkmcnt(5)
	v_mfma_f32_32x32x16_bf16 v[52:67], v[164:167], v[160:163], v[52:67]
	global_load_dwordx4 v[92:95], v[182:183], off offset:1280
	s_waitcnt lgkmcnt(4)
	v_mfma_f32_32x32x16_bf16 v[36:51], v[168:171], v[160:163], v[36:51]
	global_load_dwordx4 v[96:99], v[184:185], off offset:1280
	s_waitcnt lgkmcnt(3)
	v_mfma_f32_32x32x16_bf16 v[20:35], v[164:167], v[172:175], v[20:35]
	v_mfma_f32_32x32x16_bf16 v[4:19], v[168:171], v[172:175], v[4:19]
	s_setprio 0
	s_waitcnt lgkmcnt(0)
	s_barrier
	ds_read_b128 v[136:139], v194
	ds_read_b128 v[140:143], v195 offset:18432
	ds_read_b128 v[152:155], v195 offset:23040
	ds_read_b128 v[156:159], v194 offset:4608
	ds_read_b128 v[160:163], v194 offset:32
	ds_read_b128 v[164:167], v195 offset:18464
	ds_read_b128 v[168:171], v195 offset:23072
	ds_read_b128 v[172:175], v194 offset:4640
	s_setprio 1
	s_waitcnt lgkmcnt(6)
	v_mfma_f32_32x32x16_bf16 v[52:67], v[140:143], v[136:139], v[52:67]
	s_waitcnt vmcnt(15)
	ds_write_b128 v187, v[100:103]
	s_waitcnt lgkmcnt(6)
	v_mfma_f32_32x32x16_bf16 v[36:51], v[152:155], v[136:139], v[36:51]
	s_waitcnt vmcnt(14)
	ds_write_b128 v187, v[104:107] offset:4608
	s_waitcnt lgkmcnt(6)
	v_mfma_f32_32x32x16_bf16 v[20:35], v[140:143], v[156:159], v[20:35]
	s_waitcnt vmcnt(13)
	ds_write_b128 v187, v[108:111] offset:9216
	global_load_dwordx4 v[100:103], v[148:149], off offset:1408
	v_mfma_f32_32x32x16_bf16 v[4:19], v[152:155], v[156:159], v[4:19]
	ds_read_b128 v[136:139], v194 offset:64
	ds_read_b128 v[140:143], v195 offset:18496
	s_waitcnt lgkmcnt(7)
	v_mfma_f32_32x32x16_bf16 v[52:67], v[164:167], v[160:163], v[52:67]
	ds_read_b128 v[152:155], v195 offset:23104
	ds_read_b128 v[156:159], v194 offset:4672
	s_waitcnt lgkmcnt(8)
	v_mfma_f32_32x32x16_bf16 v[36:51], v[168:171], v[160:163], v[36:51]
	s_waitcnt vmcnt(13)
	ds_write_b128 v187, v[112:115] offset:13824
	global_load_dwordx4 v[104:107], v[134:135], off offset:1408
	s_waitcnt lgkmcnt(8)
	v_mfma_f32_32x32x16_bf16 v[20:35], v[164:167], v[172:175], v[20:35]
	s_waitcnt vmcnt(13)
	ds_write_b128 v187, v[116:119] offset:18432
	global_load_dwordx4 v[108:111], v[176:177], off offset:1408
	v_mfma_f32_32x32x16_bf16 v[4:19], v[168:171], v[172:175], v[4:19]
	ds_read_b128 v[160:163], v194 offset:96
	ds_read_b128 v[164:167], v195 offset:18528
	s_waitcnt lgkmcnt(6)
	v_mfma_f32_32x32x16_bf16 v[52:67], v[140:143], v[136:139], v[52:67]
	ds_read_b128 v[168:171], v195 offset:23136
	ds_read_b128 v[172:175], v194 offset:4704
	s_waitcnt lgkmcnt(7)
	v_mfma_f32_32x32x16_bf16 v[36:51], v[152:155], v[136:139], v[36:51]
	s_waitcnt vmcnt(13)
	ds_write_b128 v187, v[120:123] offset:23040
	global_load_dwordx4 v[112:115], v[178:179], off offset:1408
	s_waitcnt lgkmcnt(7)
	v_mfma_f32_32x32x16_bf16 v[20:35], v[140:143], v[156:159], v[20:35]
	s_waitcnt vmcnt(13)
	ds_write_b128 v187, v[124:127] offset:27648
	global_load_dwordx4 v[116:119], v[150:151], off offset:1408
	v_mfma_f32_32x32x16_bf16 v[4:19], v[152:155], v[156:159], v[4:19]
	s_waitcnt vmcnt(13)
	ds_write_b128 v187, v[128:131] offset:32256
	global_load_dwordx4 v[120:123], v[180:181], off offset:1408
	s_waitcnt lgkmcnt(5)
	v_mfma_f32_32x32x16_bf16 v[52:67], v[164:167], v[160:163], v[52:67]
	global_load_dwordx4 v[124:127], v[182:183], off offset:1408
	s_waitcnt lgkmcnt(4)
	v_mfma_f32_32x32x16_bf16 v[36:51], v[168:171], v[160:163], v[36:51]
	global_load_dwordx4 v[128:131], v[184:185], off offset:1408
	s_waitcnt lgkmcnt(3)
	v_mfma_f32_32x32x16_bf16 v[20:35], v[164:167], v[172:175], v[20:35]
	v_mfma_f32_32x32x16_bf16 v[4:19], v[168:171], v[172:175], v[4:19]
	s_setprio 0
	s_waitcnt lgkmcnt(0)
	s_barrier
	ds_read_b128 v[136:139], v194 offset:36864
	ds_read_b128 v[140:143], v195 offset:55296
	ds_read_b128 v[152:155], v195 offset:59904
	ds_read_b128 v[156:159], v194 offset:41472
	ds_read_b128 v[160:163], v194 offset:36896
	ds_read_b128 v[164:167], v195 offset:55328
	ds_read_b128 v[168:171], v195 offset:59936
	ds_read_b128 v[172:175], v194 offset:41504
	s_setprio 1
	s_waitcnt lgkmcnt(6)
	v_mfma_f32_32x32x16_bf16 v[52:67], v[140:143], v[136:139], v[52:67]
	s_waitcnt vmcnt(15)
	ds_write_b128 v186, v[68:71]
	s_waitcnt lgkmcnt(6)
	v_mfma_f32_32x32x16_bf16 v[36:51], v[152:155], v[136:139], v[36:51]
	s_waitcnt vmcnt(14)
	ds_write_b128 v186, v[72:75] offset:4608
	s_waitcnt lgkmcnt(6)
	v_mfma_f32_32x32x16_bf16 v[20:35], v[140:143], v[156:159], v[20:35]
	s_waitcnt vmcnt(13)
	ds_write_b128 v186, v[76:79] offset:9216
	global_load_dwordx4 v[68:71], v[148:149], off offset:1536
	v_mfma_f32_32x32x16_bf16 v[4:19], v[152:155], v[156:159], v[4:19]
	ds_read_b128 v[136:139], v194 offset:36928
	ds_read_b128 v[140:143], v195 offset:55360
	s_waitcnt lgkmcnt(7)
	v_mfma_f32_32x32x16_bf16 v[52:67], v[164:167], v[160:163], v[52:67]
	ds_read_b128 v[152:155], v195 offset:59968
	ds_read_b128 v[156:159], v194 offset:41536
	s_waitcnt lgkmcnt(8)
	v_mfma_f32_32x32x16_bf16 v[36:51], v[168:171], v[160:163], v[36:51]
	s_waitcnt vmcnt(13)
	ds_write_b128 v186, v[80:83] offset:13824
	global_load_dwordx4 v[72:75], v[134:135], off offset:1536
	s_waitcnt lgkmcnt(8)
	v_mfma_f32_32x32x16_bf16 v[20:35], v[164:167], v[172:175], v[20:35]
	s_waitcnt vmcnt(13)
	ds_write_b128 v186, v[84:87] offset:18432
	global_load_dwordx4 v[76:79], v[176:177], off offset:1536
	v_mfma_f32_32x32x16_bf16 v[4:19], v[168:171], v[172:175], v[4:19]
	ds_read_b128 v[160:163], v194 offset:36960
	ds_read_b128 v[164:167], v195 offset:55392
	s_waitcnt lgkmcnt(6)
	v_mfma_f32_32x32x16_bf16 v[52:67], v[140:143], v[136:139], v[52:67]
	ds_read_b128 v[168:171], v195 offset:60000
	ds_read_b128 v[172:175], v194 offset:41568
	s_waitcnt lgkmcnt(7)
	v_mfma_f32_32x32x16_bf16 v[36:51], v[152:155], v[136:139], v[36:51]
	s_waitcnt vmcnt(13)
	ds_write_b128 v186, v[88:91] offset:23040
	global_load_dwordx4 v[80:83], v[178:179], off offset:1536
	s_waitcnt lgkmcnt(7)
	v_mfma_f32_32x32x16_bf16 v[20:35], v[140:143], v[156:159], v[20:35]
	s_waitcnt vmcnt(13)
	ds_write_b128 v186, v[92:95] offset:27648
	global_load_dwordx4 v[84:87], v[150:151], off offset:1536
	v_mfma_f32_32x32x16_bf16 v[4:19], v[152:155], v[156:159], v[4:19]
	s_waitcnt vmcnt(13)
	ds_write_b128 v186, v[96:99] offset:32256
	global_load_dwordx4 v[88:91], v[180:181], off offset:1536
	s_waitcnt lgkmcnt(5)
	v_mfma_f32_32x32x16_bf16 v[52:67], v[164:167], v[160:163], v[52:67]
	global_load_dwordx4 v[92:95], v[182:183], off offset:1536
	s_waitcnt lgkmcnt(4)
	v_mfma_f32_32x32x16_bf16 v[36:51], v[168:171], v[160:163], v[36:51]
	global_load_dwordx4 v[96:99], v[184:185], off offset:1536
	s_waitcnt lgkmcnt(3)
	v_mfma_f32_32x32x16_bf16 v[20:35], v[164:167], v[172:175], v[20:35]
	v_mfma_f32_32x32x16_bf16 v[4:19], v[168:171], v[172:175], v[4:19]
	s_setprio 0
	s_waitcnt lgkmcnt(0)
	s_barrier
	ds_read_b128 v[136:139], v194
	ds_read_b128 v[140:143], v195 offset:18432
	ds_read_b128 v[152:155], v195 offset:23040
	ds_read_b128 v[156:159], v194 offset:4608
	ds_read_b128 v[160:163], v194 offset:32
	ds_read_b128 v[164:167], v195 offset:18464
	ds_read_b128 v[168:171], v195 offset:23072
	ds_read_b128 v[172:175], v194 offset:4640
	s_setprio 1
	s_waitcnt lgkmcnt(6)
	v_mfma_f32_32x32x16_bf16 v[52:67], v[140:143], v[136:139], v[52:67]
	s_waitcnt vmcnt(15)
	ds_write_b128 v187, v[100:103]
	s_waitcnt lgkmcnt(6)
	v_mfma_f32_32x32x16_bf16 v[36:51], v[152:155], v[136:139], v[36:51]
	s_waitcnt vmcnt(14)
	ds_write_b128 v187, v[104:107] offset:4608
	s_waitcnt lgkmcnt(6)
	v_mfma_f32_32x32x16_bf16 v[20:35], v[140:143], v[156:159], v[20:35]
	s_waitcnt vmcnt(13)
	ds_write_b128 v187, v[108:111] offset:9216
	global_load_dwordx4 v[100:103], v[148:149], off offset:1664
	v_mfma_f32_32x32x16_bf16 v[4:19], v[152:155], v[156:159], v[4:19]
	ds_read_b128 v[136:139], v194 offset:64
	ds_read_b128 v[140:143], v195 offset:18496
	s_waitcnt lgkmcnt(7)
	v_mfma_f32_32x32x16_bf16 v[52:67], v[164:167], v[160:163], v[52:67]
	ds_read_b128 v[152:155], v195 offset:23104
	ds_read_b128 v[156:159], v194 offset:4672
	s_waitcnt lgkmcnt(8)
	v_mfma_f32_32x32x16_bf16 v[36:51], v[168:171], v[160:163], v[36:51]
	s_waitcnt vmcnt(13)
	ds_write_b128 v187, v[112:115] offset:13824
	global_load_dwordx4 v[104:107], v[134:135], off offset:1664
	s_waitcnt lgkmcnt(8)
	v_mfma_f32_32x32x16_bf16 v[20:35], v[164:167], v[172:175], v[20:35]
	s_waitcnt vmcnt(13)
	ds_write_b128 v187, v[116:119] offset:18432
	global_load_dwordx4 v[108:111], v[176:177], off offset:1664
	v_mfma_f32_32x32x16_bf16 v[4:19], v[168:171], v[172:175], v[4:19]
	ds_read_b128 v[160:163], v194 offset:96
	ds_read_b128 v[164:167], v195 offset:18528
	s_waitcnt lgkmcnt(6)
	v_mfma_f32_32x32x16_bf16 v[52:67], v[140:143], v[136:139], v[52:67]
	ds_read_b128 v[168:171], v195 offset:23136
	ds_read_b128 v[172:175], v194 offset:4704
	s_waitcnt lgkmcnt(7)
	v_mfma_f32_32x32x16_bf16 v[36:51], v[152:155], v[136:139], v[36:51]
	s_waitcnt vmcnt(13)
	ds_write_b128 v187, v[120:123] offset:23040
	global_load_dwordx4 v[112:115], v[178:179], off offset:1664
	s_waitcnt lgkmcnt(7)
	v_mfma_f32_32x32x16_bf16 v[20:35], v[140:143], v[156:159], v[20:35]
	s_waitcnt vmcnt(13)
	ds_write_b128 v187, v[124:127] offset:27648
	global_load_dwordx4 v[116:119], v[150:151], off offset:1664
	v_mfma_f32_32x32x16_bf16 v[4:19], v[152:155], v[156:159], v[4:19]
	s_waitcnt vmcnt(13)
	ds_write_b128 v187, v[128:131] offset:32256
	global_load_dwordx4 v[120:123], v[180:181], off offset:1664
	s_waitcnt lgkmcnt(5)
	v_mfma_f32_32x32x16_bf16 v[52:67], v[164:167], v[160:163], v[52:67]
	global_load_dwordx4 v[124:127], v[182:183], off offset:1664
	s_waitcnt lgkmcnt(4)
	v_mfma_f32_32x32x16_bf16 v[36:51], v[168:171], v[160:163], v[36:51]
	global_load_dwordx4 v[128:131], v[184:185], off offset:1664
	s_waitcnt lgkmcnt(3)
	v_mfma_f32_32x32x16_bf16 v[20:35], v[164:167], v[172:175], v[20:35]
	v_mfma_f32_32x32x16_bf16 v[4:19], v[168:171], v[172:175], v[4:19]
	s_setprio 0
	s_waitcnt lgkmcnt(0)
	s_barrier
	ds_read_b128 v[136:139], v194 offset:36864
	ds_read_b128 v[140:143], v195 offset:55296
	ds_read_b128 v[152:155], v195 offset:59904
	ds_read_b128 v[156:159], v194 offset:41472
	ds_read_b128 v[160:163], v194 offset:36896
	ds_read_b128 v[164:167], v195 offset:55328
	ds_read_b128 v[168:171], v195 offset:59936
	ds_read_b128 v[172:175], v194 offset:41504
	s_setprio 1
	s_waitcnt lgkmcnt(6)
	v_mfma_f32_32x32x16_bf16 v[52:67], v[140:143], v[136:139], v[52:67]
	s_waitcnt vmcnt(15)
	ds_write_b128 v186, v[68:71]
	s_waitcnt lgkmcnt(6)
	v_mfma_f32_32x32x16_bf16 v[36:51], v[152:155], v[136:139], v[36:51]
	s_waitcnt vmcnt(14)
	ds_write_b128 v186, v[72:75] offset:4608
	s_waitcnt lgkmcnt(6)
	v_mfma_f32_32x32x16_bf16 v[20:35], v[140:143], v[156:159], v[20:35]
	s_waitcnt vmcnt(13)
	ds_write_b128 v186, v[76:79] offset:9216
	global_load_dwordx4 v[68:71], v[148:149], off offset:1792
	v_mfma_f32_32x32x16_bf16 v[4:19], v[152:155], v[156:159], v[4:19]
	ds_read_b128 v[136:139], v194 offset:36928
	ds_read_b128 v[140:143], v195 offset:55360
	s_waitcnt lgkmcnt(7)
	v_mfma_f32_32x32x16_bf16 v[52:67], v[164:167], v[160:163], v[52:67]
	ds_read_b128 v[152:155], v195 offset:59968
	ds_read_b128 v[156:159], v194 offset:41536
	s_waitcnt lgkmcnt(8)
	v_mfma_f32_32x32x16_bf16 v[36:51], v[168:171], v[160:163], v[36:51]
	s_waitcnt vmcnt(13)
	ds_write_b128 v186, v[80:83] offset:13824
	global_load_dwordx4 v[72:75], v[134:135], off offset:1792
	s_waitcnt lgkmcnt(8)
	v_mfma_f32_32x32x16_bf16 v[20:35], v[164:167], v[172:175], v[20:35]
	s_waitcnt vmcnt(13)
	ds_write_b128 v186, v[84:87] offset:18432
	global_load_dwordx4 v[76:79], v[176:177], off offset:1792
	v_mfma_f32_32x32x16_bf16 v[4:19], v[168:171], v[172:175], v[4:19]
	ds_read_b128 v[160:163], v194 offset:36960
	ds_read_b128 v[164:167], v195 offset:55392
	s_waitcnt lgkmcnt(6)
	v_mfma_f32_32x32x16_bf16 v[52:67], v[140:143], v[136:139], v[52:67]
	ds_read_b128 v[168:171], v195 offset:60000
	ds_read_b128 v[172:175], v194 offset:41568
	s_waitcnt lgkmcnt(7)
	v_mfma_f32_32x32x16_bf16 v[36:51], v[152:155], v[136:139], v[36:51]
	s_waitcnt vmcnt(13)
	ds_write_b128 v186, v[88:91] offset:23040
	global_load_dwordx4 v[80:83], v[178:179], off offset:1792
	s_waitcnt lgkmcnt(7)
	v_mfma_f32_32x32x16_bf16 v[20:35], v[140:143], v[156:159], v[20:35]
	s_waitcnt vmcnt(13)
	ds_write_b128 v186, v[92:95] offset:27648
	global_load_dwordx4 v[84:87], v[150:151], off offset:1792
	v_mfma_f32_32x32x16_bf16 v[4:19], v[152:155], v[156:159], v[4:19]
	s_waitcnt vmcnt(13)
	ds_write_b128 v186, v[96:99] offset:32256
	global_load_dwordx4 v[88:91], v[180:181], off offset:1792
	s_waitcnt lgkmcnt(5)
	v_mfma_f32_32x32x16_bf16 v[52:67], v[164:167], v[160:163], v[52:67]
	global_load_dwordx4 v[92:95], v[182:183], off offset:1792
	s_waitcnt lgkmcnt(4)
	v_mfma_f32_32x32x16_bf16 v[36:51], v[168:171], v[160:163], v[36:51]
	global_load_dwordx4 v[96:99], v[184:185], off offset:1792
	s_waitcnt lgkmcnt(3)
	v_mfma_f32_32x32x16_bf16 v[20:35], v[164:167], v[172:175], v[20:35]
	v_mfma_f32_32x32x16_bf16 v[4:19], v[168:171], v[172:175], v[4:19]
	s_setprio 0
	s_waitcnt lgkmcnt(0)
	s_barrier
	ds_read_b128 v[136:139], v194
	ds_read_b128 v[140:143], v195 offset:18432
	ds_read_b128 v[152:155], v195 offset:23040
	ds_read_b128 v[156:159], v194 offset:4608
	ds_read_b128 v[160:163], v194 offset:32
	ds_read_b128 v[164:167], v195 offset:18464
	ds_read_b128 v[168:171], v195 offset:23072
	ds_read_b128 v[172:175], v194 offset:4640
	s_setprio 1
	s_waitcnt lgkmcnt(6)
	v_mfma_f32_32x32x16_bf16 v[52:67], v[140:143], v[136:139], v[52:67]
	s_waitcnt vmcnt(15)
	ds_write_b128 v187, v[100:103]
	s_waitcnt lgkmcnt(6)
	v_mfma_f32_32x32x16_bf16 v[36:51], v[152:155], v[136:139], v[36:51]
	s_waitcnt vmcnt(14)
	ds_write_b128 v187, v[104:107] offset:4608
	s_waitcnt lgkmcnt(6)
	v_mfma_f32_32x32x16_bf16 v[20:35], v[140:143], v[156:159], v[20:35]
	s_waitcnt vmcnt(13)
	ds_write_b128 v187, v[108:111] offset:9216
	global_load_dwordx4 v[100:103], v[148:149], off offset:1920
	v_mfma_f32_32x32x16_bf16 v[4:19], v[152:155], v[156:159], v[4:19]
	ds_read_b128 v[136:139], v194 offset:64
	ds_read_b128 v[140:143], v195 offset:18496
	s_waitcnt lgkmcnt(7)
	v_mfma_f32_32x32x16_bf16 v[52:67], v[164:167], v[160:163], v[52:67]
	ds_read_b128 v[152:155], v195 offset:23104
	ds_read_b128 v[156:159], v194 offset:4672
	s_waitcnt lgkmcnt(8)
	v_mfma_f32_32x32x16_bf16 v[36:51], v[168:171], v[160:163], v[36:51]
	s_waitcnt vmcnt(13)
	ds_write_b128 v187, v[112:115] offset:13824
	global_load_dwordx4 v[104:107], v[134:135], off offset:1920
	s_waitcnt lgkmcnt(8)
	v_mfma_f32_32x32x16_bf16 v[20:35], v[164:167], v[172:175], v[20:35]
	s_waitcnt vmcnt(13)
	ds_write_b128 v187, v[116:119] offset:18432
	global_load_dwordx4 v[108:111], v[176:177], off offset:1920
	v_mfma_f32_32x32x16_bf16 v[4:19], v[168:171], v[172:175], v[4:19]
	ds_read_b128 v[160:163], v194 offset:96
	ds_read_b128 v[164:167], v195 offset:18528
	s_waitcnt lgkmcnt(6)
	v_mfma_f32_32x32x16_bf16 v[52:67], v[140:143], v[136:139], v[52:67]
	ds_read_b128 v[168:171], v195 offset:23136
	ds_read_b128 v[172:175], v194 offset:4704
	s_waitcnt lgkmcnt(7)
	v_mfma_f32_32x32x16_bf16 v[36:51], v[152:155], v[136:139], v[36:51]
	s_waitcnt vmcnt(13)
	ds_write_b128 v187, v[120:123] offset:23040
	global_load_dwordx4 v[112:115], v[178:179], off offset:1920
	s_waitcnt lgkmcnt(7)
	v_mfma_f32_32x32x16_bf16 v[20:35], v[140:143], v[156:159], v[20:35]
	s_waitcnt vmcnt(13)
	ds_write_b128 v187, v[124:127] offset:27648
	global_load_dwordx4 v[116:119], v[150:151], off offset:1920
	v_mfma_f32_32x32x16_bf16 v[4:19], v[152:155], v[156:159], v[4:19]
	s_waitcnt vmcnt(13)
	ds_write_b128 v187, v[128:131] offset:32256
	global_load_dwordx4 v[120:123], v[180:181], off offset:1920
	s_waitcnt lgkmcnt(5)
	v_mfma_f32_32x32x16_bf16 v[52:67], v[164:167], v[160:163], v[52:67]
	global_load_dwordx4 v[124:127], v[182:183], off offset:1920
	s_waitcnt lgkmcnt(4)
	v_mfma_f32_32x32x16_bf16 v[36:51], v[168:171], v[160:163], v[36:51]
	global_load_dwordx4 v[128:131], v[184:185], off offset:1920
	s_waitcnt lgkmcnt(3)
	v_mfma_f32_32x32x16_bf16 v[20:35], v[164:167], v[172:175], v[20:35]
	v_mfma_f32_32x32x16_bf16 v[4:19], v[168:171], v[172:175], v[4:19]
	s_setprio 0
	s_waitcnt lgkmcnt(0)
	s_barrier
	ds_read_b128 v[136:139], v194 offset:36864
	ds_read_b128 v[140:143], v195 offset:55296
	ds_read_b128 v[152:155], v195 offset:59904
	ds_read_b128 v[156:159], v194 offset:41472
	ds_read_b128 v[160:163], v194 offset:36896
	ds_read_b128 v[164:167], v195 offset:55328
	ds_read_b128 v[168:171], v195 offset:59936
	ds_read_b128 v[172:175], v194 offset:41504
	s_setprio 1
	s_waitcnt lgkmcnt(6)
	v_mfma_f32_32x32x16_bf16 v[52:67], v[140:143], v[136:139], v[52:67]
	s_waitcnt vmcnt(15)
	ds_write_b128 v186, v[68:71]
	s_waitcnt lgkmcnt(6)
	v_mfma_f32_32x32x16_bf16 v[36:51], v[152:155], v[136:139], v[36:51]
	s_waitcnt vmcnt(14)
	ds_write_b128 v186, v[72:75] offset:4608
	s_waitcnt lgkmcnt(6)
	v_mfma_f32_32x32x16_bf16 v[20:35], v[140:143], v[156:159], v[20:35]
	s_waitcnt vmcnt(13)
	ds_write_b128 v186, v[76:79] offset:9216
	v_mfma_f32_32x32x16_bf16 v[4:19], v[152:155], v[156:159], v[4:19]
	ds_read_b128 v[136:139], v194 offset:36928
	ds_read_b128 v[140:143], v195 offset:55360
	s_waitcnt lgkmcnt(7)
	v_mfma_f32_32x32x16_bf16 v[52:67], v[164:167], v[160:163], v[52:67]
	ds_read_b128 v[152:155], v195 offset:59968
	ds_read_b128 v[156:159], v194 offset:41536
	s_waitcnt lgkmcnt(8)
	v_mfma_f32_32x32x16_bf16 v[36:51], v[168:171], v[160:163], v[36:51]
	s_waitcnt vmcnt(12)
	ds_write_b128 v186, v[80:83] offset:13824
	s_waitcnt lgkmcnt(8)
	v_mfma_f32_32x32x16_bf16 v[20:35], v[164:167], v[172:175], v[20:35]
	s_waitcnt vmcnt(11)
	ds_write_b128 v186, v[84:87] offset:18432
	v_mfma_f32_32x32x16_bf16 v[4:19], v[168:171], v[172:175], v[4:19]
	ds_read_b128 v[160:163], v194 offset:36960
	ds_read_b128 v[164:167], v195 offset:55392
	s_waitcnt lgkmcnt(6)
	v_mfma_f32_32x32x16_bf16 v[52:67], v[140:143], v[136:139], v[52:67]
	ds_read_b128 v[168:171], v195 offset:60000
	ds_read_b128 v[172:175], v194 offset:41568
	s_waitcnt lgkmcnt(7)
	v_mfma_f32_32x32x16_bf16 v[36:51], v[152:155], v[136:139], v[36:51]
	s_waitcnt vmcnt(10)
	ds_write_b128 v186, v[88:91] offset:23040
	s_waitcnt lgkmcnt(7)
	v_mfma_f32_32x32x16_bf16 v[20:35], v[140:143], v[156:159], v[20:35]
	s_waitcnt vmcnt(9)
	ds_write_b128 v186, v[92:95] offset:27648
	v_mfma_f32_32x32x16_bf16 v[4:19], v[152:155], v[156:159], v[4:19]
	s_waitcnt vmcnt(8)
	ds_write_b128 v186, v[96:99] offset:32256
	s_waitcnt lgkmcnt(5)
	v_mfma_f32_32x32x16_bf16 v[52:67], v[164:167], v[160:163], v[52:67]
	s_waitcnt lgkmcnt(4)
	v_mfma_f32_32x32x16_bf16 v[36:51], v[168:171], v[160:163], v[36:51]
	s_waitcnt lgkmcnt(3)
	v_mfma_f32_32x32x16_bf16 v[20:35], v[164:167], v[172:175], v[20:35]
	v_mfma_f32_32x32x16_bf16 v[4:19], v[168:171], v[172:175], v[4:19]
	s_setprio 0
	s_waitcnt lgkmcnt(0)
	s_barrier
	ds_read_b128 v[136:139], v194
	ds_read_b128 v[140:143], v195 offset:18432
	ds_read_b128 v[152:155], v195 offset:23040
	ds_read_b128 v[156:159], v194 offset:4608
	ds_read_b128 v[160:163], v194 offset:32
	ds_read_b128 v[164:167], v195 offset:18464
	ds_read_b128 v[168:171], v195 offset:23072
	ds_read_b128 v[172:175], v194 offset:4640
	s_setprio 1
	s_waitcnt lgkmcnt(6)
	v_mfma_f32_32x32x16_bf16 v[52:67], v[140:143], v[136:139], v[52:67]
	s_waitcnt vmcnt(7)
	ds_write_b128 v187, v[100:103]
	s_waitcnt lgkmcnt(6)
	v_mfma_f32_32x32x16_bf16 v[36:51], v[152:155], v[136:139], v[36:51]
	s_waitcnt vmcnt(6)
	ds_write_b128 v187, v[104:107] offset:4608
	s_waitcnt lgkmcnt(6)
	v_mfma_f32_32x32x16_bf16 v[20:35], v[140:143], v[156:159], v[20:35]
	s_waitcnt vmcnt(5)
	ds_write_b128 v187, v[108:111] offset:9216
	v_mfma_f32_32x32x16_bf16 v[4:19], v[152:155], v[156:159], v[4:19]
	ds_read_b128 v[136:139], v194 offset:64
	ds_read_b128 v[140:143], v195 offset:18496
	s_waitcnt lgkmcnt(7)
	v_mfma_f32_32x32x16_bf16 v[52:67], v[164:167], v[160:163], v[52:67]
	ds_read_b128 v[152:155], v195 offset:23104
	ds_read_b128 v[156:159], v194 offset:4672
	s_waitcnt lgkmcnt(8)
	v_mfma_f32_32x32x16_bf16 v[36:51], v[168:171], v[160:163], v[36:51]
	s_waitcnt vmcnt(4)
	ds_write_b128 v187, v[112:115] offset:13824
	s_waitcnt lgkmcnt(8)
	v_mfma_f32_32x32x16_bf16 v[20:35], v[164:167], v[172:175], v[20:35]
	s_waitcnt vmcnt(3)
	ds_write_b128 v187, v[116:119] offset:18432
	v_mfma_f32_32x32x16_bf16 v[4:19], v[168:171], v[172:175], v[4:19]
	ds_read_b128 v[160:163], v194 offset:96
	ds_read_b128 v[164:167], v195 offset:18528
	s_waitcnt lgkmcnt(6)
	v_mfma_f32_32x32x16_bf16 v[52:67], v[140:143], v[136:139], v[52:67]
	ds_read_b128 v[168:171], v195 offset:23136
	ds_read_b128 v[172:175], v194 offset:4704
	s_waitcnt lgkmcnt(7)
	v_mfma_f32_32x32x16_bf16 v[36:51], v[152:155], v[136:139], v[36:51]
	s_waitcnt vmcnt(2)
	ds_write_b128 v187, v[120:123] offset:23040
	s_waitcnt lgkmcnt(7)
	v_mfma_f32_32x32x16_bf16 v[20:35], v[140:143], v[156:159], v[20:35]
	s_waitcnt vmcnt(1)
	ds_write_b128 v187, v[124:127] offset:27648
	v_mfma_f32_32x32x16_bf16 v[4:19], v[152:155], v[156:159], v[4:19]
	s_waitcnt vmcnt(0)
	ds_write_b128 v187, v[128:131] offset:32256
	s_waitcnt lgkmcnt(5)
	v_mfma_f32_32x32x16_bf16 v[52:67], v[164:167], v[160:163], v[52:67]
	s_waitcnt lgkmcnt(4)
	v_mfma_f32_32x32x16_bf16 v[36:51], v[168:171], v[160:163], v[36:51]
	s_waitcnt lgkmcnt(3)
	v_mfma_f32_32x32x16_bf16 v[20:35], v[164:167], v[172:175], v[20:35]
	v_mfma_f32_32x32x16_bf16 v[4:19], v[168:171], v[172:175], v[4:19]
	s_setprio 0
	s_waitcnt lgkmcnt(0)
	s_barrier
	ds_read_b128 v[136:139], v194 offset:36864
	ds_read_b128 v[140:143], v195 offset:55296
	ds_read_b128 v[152:155], v195 offset:59904
	ds_read_b128 v[156:159], v194 offset:41472
	ds_read_b128 v[160:163], v194 offset:36896
	ds_read_b128 v[164:167], v195 offset:55328
	ds_read_b128 v[168:171], v195 offset:59936
	ds_read_b128 v[172:175], v194 offset:41504
	s_setprio 1
	s_waitcnt lgkmcnt(6)
	v_mfma_f32_32x32x16_bf16 v[52:67], v[140:143], v[136:139], v[52:67]
	s_waitcnt lgkmcnt(5)
	v_mfma_f32_32x32x16_bf16 v[36:51], v[152:155], v[136:139], v[36:51]
	s_waitcnt lgkmcnt(4)
	v_mfma_f32_32x32x16_bf16 v[20:35], v[140:143], v[156:159], v[20:35]
	v_mfma_f32_32x32x16_bf16 v[4:19], v[152:155], v[156:159], v[4:19]
	ds_read_b128 v[136:139], v194 offset:36928
	ds_read_b128 v[140:143], v195 offset:55360
	s_waitcnt lgkmcnt(4)
	v_mfma_f32_32x32x16_bf16 v[52:67], v[164:167], v[160:163], v[52:67]
	ds_read_b128 v[152:155], v195 offset:59968
	ds_read_b128 v[156:159], v194 offset:41536
	s_waitcnt lgkmcnt(5)
	v_mfma_f32_32x32x16_bf16 v[36:51], v[168:171], v[160:163], v[36:51]
	s_waitcnt lgkmcnt(4)
	v_mfma_f32_32x32x16_bf16 v[20:35], v[164:167], v[172:175], v[20:35]
	v_mfma_f32_32x32x16_bf16 v[4:19], v[168:171], v[172:175], v[4:19]
	ds_read_b128 v[160:163], v194 offset:36960
	ds_read_b128 v[164:167], v195 offset:55392
	s_waitcnt lgkmcnt(4)
	v_mfma_f32_32x32x16_bf16 v[52:67], v[140:143], v[136:139], v[52:67]
	ds_read_b128 v[168:171], v195 offset:60000
	ds_read_b128 v[172:175], v194 offset:41568
	s_waitcnt lgkmcnt(5)
	v_mfma_f32_32x32x16_bf16 v[36:51], v[152:155], v[136:139], v[36:51]
	s_waitcnt lgkmcnt(4)
	v_mfma_f32_32x32x16_bf16 v[20:35], v[140:143], v[156:159], v[20:35]
	v_mfma_f32_32x32x16_bf16 v[4:19], v[152:155], v[156:159], v[4:19]
	s_waitcnt lgkmcnt(2)
	v_mfma_f32_32x32x16_bf16 v[52:67], v[164:167], v[160:163], v[52:67]
	s_waitcnt lgkmcnt(1)
	v_mfma_f32_32x32x16_bf16 v[36:51], v[168:171], v[160:163], v[36:51]
	s_waitcnt lgkmcnt(0)
	v_mfma_f32_32x32x16_bf16 v[20:35], v[164:167], v[172:175], v[20:35]
	v_mfma_f32_32x32x16_bf16 v[4:19], v[168:171], v[172:175], v[4:19]
	s_setprio 0
	s_nop 7
	s_nop 4
	v_mov_b32_e32 v188, 0x12010
	s_add_i32 s2, s76, s70
	s_and_b32 s0, s2, 0xfffffe00
	s_cmpk_eq_i32 s0, 0xc00
	s_cselect_b64 s[0:1], -1, 0
	s_and_b64 s[0:1], s[26:27], s[0:1]
	s_cmpk_lt_i32 s2, 0xd00
	s_movk_i32 s3, 0xff00
	s_cselect_b32 s3, 0x100, s3
	s_and_b64 s[0:1], s[0:1], exec
	s_cselect_b32 s0, s3, 0
	s_add_i32 s0, s0, s2
	s_cmpk_lt_i32 s2, 0xe10
	s_cselect_b32 s0, s0, 0xd00
	s_cmpk_gt_i32 s0, 0xcff
	v_mov_b64_e32 v[146:147], v[150:151]
	v_mov_b64_e32 v[144:145], v[148:149]
	s_barrier
	s_cbranch_scc1 .LBB0_303
	s_lshl_b32 s1, s0, 18
	v_readlane_b32 s12, v252, 47
	v_mov_b32_e32 v2, v0
	s_and_b32 s1, s1, 0xfc0000
	v_readlane_b32 s18, v252, 53
	v_readlane_b32 s19, v252, 54
	v_ashrrev_i32_e32 v68, 3, v2
	s_add_u32 s2, s18, s1
	v_ashrrev_i32_e32 v69, 31, v68
	s_addc_u32 s3, s19, 0
	v_lshlrev_b64 v[68:69], 11, v[68:69]
	v_lshlrev_b32_e32 v2, 4, v2
	v_lshl_add_u64 v[70:71], s[2:3], 0, v[68:69]
	v_and_b32_e32 v2, 0x70, v2
	s_ashr_i32 s0, s0, 6
	v_lshl_add_u64 v[144:145], v[70:71], 0, v[2:3]
	s_ashr_i32 s1, s0, 31
	v_add_co_u32_e32 v76, vcc, s33, v144
	s_lshl_b64 s[0:1], s[0:1], 18
	s_nop 0
	v_addc_co_u32_e32 v77, vcc, 0, v145, vcc
	s_add_u32 s0, s68, s0
	v_add_co_u32_e32 v80, vcc, s78, v144
	s_addc_u32 s1, s69, s1
	s_nop 0
	v_addc_co_u32_e32 v81, vcc, 0, v145, vcc
	v_lshl_add_u64 v[68:69], s[0:1], 0, v[68:69]
	v_add_co_u32_e32 v84, vcc, s79, v144
	v_lshl_add_u64 v[146:147], v[68:69], 0, v[2:3]
	s_nop 0
	v_addc_co_u32_e32 v85, vcc, 0, v145, vcc
	v_add_co_u32_e32 v92, vcc, s33, v146
	v_readlane_b32 s13, v252, 48
	s_nop 0
	v_addc_co_u32_e32 v93, vcc, 0, v147, vcc
	v_add_co_u32_e32 v96, vcc, s78, v146
	v_readlane_b32 s14, v252, 49
	s_nop 0
	v_addc_co_u32_e32 v97, vcc, 0, v147, vcc
	v_add_co_u32_e32 v128, vcc, 0x30000, v146
	v_readlane_b32 s15, v252, 50
	s_nop 0
	v_addc_co_u32_e32 v129, vcc, 0, v147, vcc
	global_load_dwordx4 v[68:71], v[144:145], off
	global_load_dwordx4 v[100:103], v[144:145], off offset:128
	global_load_dwordx4 v[72:75], v[76:77], off
	global_load_dwordx4 v[104:107], v[76:77], off offset:128
	s_nop 0
	global_load_dwordx4 v[76:79], v[80:81], off
	global_load_dwordx4 v[108:111], v[80:81], off offset:128
	s_nop 0
	global_load_dwordx4 v[80:83], v[84:85], off
	global_load_dwordx4 v[112:115], v[84:85], off offset:128
	s_nop 0
	global_load_dwordx4 v[84:87], v[146:147], off
	global_load_dwordx4 v[116:119], v[146:147], off offset:128
	global_load_dwordx4 v[88:91], v[92:93], off
	global_load_dwordx4 v[120:123], v[92:93], off offset:128
	s_nop 0
	global_load_dwordx4 v[92:95], v[96:97], off
	global_load_dwordx4 v[124:127], v[96:97], off offset:128
	s_nop 0
	global_load_dwordx4 v[96:99], v[128:129], off
	s_nop 0
	global_load_dwordx4 v[128:131], v[128:129], off offset:128
	v_readlane_b32 s16, v252, 51
	v_readlane_b32 s17, v252, 52

.LBB0_574:
	s_add_i32 s0, s37, 0xfffff000
	s_lshr_b32 s0, s0, 11
	s_add_i32 s21, s0, 1
	s_and_b64 s[0:1], s[18:19], exec
	s_cselect_b32 s0, 0, s21
	s_mul_i32 s1, s94, 3
	s_add_u32 s0, s1, s0
	s_mul_hi_i32 s1, s94, 3
	s_addc_u32 s1, s1, 0
	s_mulk_i32 s1, 0x6000
	s_mul_hi_u32 s18, s0, 0x6000
	v_readlane_b32 s24, v251, 7
	v_mov_b32_e32 v2, v0
	s_add_i32 s18, s18, s1
	s_mulk_i32 s0, 0x6000
	v_readlane_b32 s26, v251, 9
	v_readlane_b32 s27, v251, 10
	s_waitcnt vmcnt(7)
	v_lshrrev_b32_e32 v70, 3, v2
	s_add_u32 s19, s26, s0
	v_and_b32_e32 v68, 31, v2
	v_and_b32_e32 v69, 64, v2
	v_and_b32_e32 v70, 4, v70
	v_ashrrev_i32_e32 v2, 1, v2
	s_addc_u32 s21, s27, s18
	s_lshl_b32 s0, s37, 12
	s_waitcnt vmcnt(5)
	v_or3_b32 v88, v69, v70, s20
	v_and_b32_e32 v2, 0xffffffc0, v2
	v_or_b32_e32 v69, s37, v68
	s_add_u32 s0, s70, s0
	v_add_u32_e32 v74, v69, v2
	v_or_b32_e32 v70, v2, v68
	s_addc_u32 s1, s71, 0
	v_ashrrev_i32_e32 v75, 31, v74
	v_ashrrev_i32_e32 v71, 31, v70
	s_add_u32 s18, s19, 0x5000
	v_lshlrev_b64 v[68:69], 12, v[74:75]
	v_lshlrev_b64 v[72:73], 12, v[70:71]
	v_ashrrev_i32_e32 v89, 31, v88
	s_addc_u32 s19, s21, 0
	v_lshl_add_u64 v[68:69], s[70:71], 0, v[68:69]
	v_lshl_add_u64 v[78:79], s[0:1], 0, v[72:73]
	v_lshlrev_b64 v[72:73], 2, v[88:89]
	v_lshl_add_u64 v[76:77], v[68:69], 0, v[72:73]
	v_lshl_add_u64 v[68:69], s[18:19], 0, v[72:73]
	v_lshl_add_u64 v[78:79], v[78:79], 0, v[72:73]
	v_readlane_b32 s25, v251, 8
	v_add_co_u32_e32 v142, vcc, 0x20000, v78
	s_nop 1
	v_addc_co_u32_e32 v143, vcc, 0, v79, vcc
	v_add_co_u32_e32 v172, vcc, 0x20000, v76
	s_nop 1
	v_addc_co_u32_e32 v173, vcc, 0, v77, vcc
	global_load_dwordx4 v[112:115], v[78:79], off
	global_load_dwordx4 v[116:119], v[78:79], off offset:32
	global_load_dwordx4 v[120:123], v[78:79], off offset:64
	global_load_dwordx4 v[124:127], v[78:79], off offset:96
	global_load_dwordx4 v[128:131], v[78:79], off offset:128
	global_load_dwordx4 v[144:147], v[78:79], off offset:160
	global_load_dwordx4 v[148:151], v[78:79], off offset:192
	global_load_dwordx4 v[152:155], v[78:79], off offset:224
	global_load_dwordx4 v[80:83], v[68:69], off
	global_load_dwordx4 v[84:87], v[68:69], off offset:32
	global_load_dwordx4 v[88:91], v[68:69], off offset:64
	global_load_dwordx4 v[92:95], v[68:69], off offset:96
	global_load_dwordx4 v[96:99], v[68:69], off offset:128
	global_load_dwordx4 v[100:103], v[68:69], off offset:160
	global_load_dwordx4 v[104:107], v[68:69], off offset:192
	global_load_dwordx4 v[108:111], v[68:69], off offset:224
	global_load_dwordx4 v[156:159], v[142:143], off
	global_load_dwordx4 v[160:163], v[142:143], off offset:32
	global_load_dwordx4 v[164:167], v[142:143], off offset:64
	global_load_dwordx4 v[168:171], v[142:143], off offset:96
	s_waitcnt vmcnt(11)
	v_pk_fma_f32 v[112:113], v[52:53], v[80:81], v[112:113]
	v_pk_fma_f32 v[114:115], v[54:55], v[82:83], v[114:115]
	global_store_dwordx4 v[76:77], v[112:115], off
	s_waitcnt vmcnt(11)
	v_pk_fma_f32 v[116:117], v[56:57], v[84:85], v[116:117]
	v_pk_fma_f32 v[118:119], v[58:59], v[86:87], v[118:119]
	global_store_dwordx4 v[76:77], v[116:119], off offset:32
	s_waitcnt vmcnt(11)
	v_pk_fma_f32 v[120:121], v[60:61], v[88:89], v[120:121]
	v_pk_fma_f32 v[122:123], v[62:63], v[90:91], v[122:123]
	global_store_dwordx4 v[76:77], v[120:123], off offset:64
	s_waitcnt vmcnt(11)
	v_pk_fma_f32 v[124:125], v[64:65], v[92:93], v[124:125]
	v_pk_fma_f32 v[126:127], v[66:67], v[94:95], v[126:127]
	global_store_dwordx4 v[76:77], v[124:127], off offset:96
	s_nop 1
	global_load_dwordx4 v[112:115], v[142:143], off offset:128
	global_load_dwordx4 v[116:119], v[142:143], off offset:160
	global_load_dwordx4 v[120:123], v[142:143], off offset:192
	global_load_dwordx4 v[124:127], v[142:143], off offset:224
	s_waitcnt vmcnt(15)
	v_pk_fma_f32 v[128:129], v[36:37], v[96:97], v[128:129]
	v_pk_fma_f32 v[130:131], v[38:39], v[98:99], v[130:131]
	global_store_dwordx4 v[76:77], v[128:131], off offset:128
	s_waitcnt vmcnt(15)
	v_pk_fma_f32 v[144:145], v[40:41], v[100:101], v[144:145]
	v_pk_fma_f32 v[146:147], v[42:43], v[102:103], v[146:147]
	global_store_dwordx4 v[76:77], v[144:147], off offset:160
	s_waitcnt vmcnt(15)
	v_pk_fma_f32 v[148:149], v[44:45], v[104:105], v[148:149]
	v_pk_fma_f32 v[150:151], v[46:47], v[106:107], v[150:151]
	global_store_dwordx4 v[76:77], v[148:151], off offset:192
	s_waitcnt vmcnt(15)
	v_pk_fma_f32 v[152:153], v[48:49], v[108:109], v[152:153]
	v_pk_fma_f32 v[154:155], v[50:51], v[110:111], v[154:155]
	global_store_dwordx4 v[76:77], v[152:155], off offset:224
	s_waitcnt vmcnt(15)
	v_pk_fma_f32 v[156:157], v[20:21], v[80:81], v[156:157]
	v_pk_fma_f32 v[158:159], v[22:23], v[82:83], v[158:159]
	global_store_dwordx4 v[172:173], v[156:159], off
	s_waitcnt vmcnt(15)
	v_pk_fma_f32 v[160:161], v[24:25], v[84:85], v[160:161]
	v_pk_fma_f32 v[162:163], v[26:27], v[86:87], v[162:163]
	global_store_dwordx4 v[172:173], v[160:163], off offset:32
	s_waitcnt vmcnt(15)
	v_pk_fma_f32 v[164:165], v[28:29], v[88:89], v[164:165]
	v_pk_fma_f32 v[166:167], v[30:31], v[90:91], v[166:167]
	global_store_dwordx4 v[172:173], v[164:167], off offset:64
	s_waitcnt vmcnt(15)
	v_pk_fma_f32 v[168:169], v[32:33], v[92:93], v[168:169]
	v_pk_fma_f32 v[170:171], v[34:35], v[94:95], v[170:171]
	global_store_dwordx4 v[172:173], v[168:171], off offset:96
	s_waitcnt vmcnt(11)
	v_pk_fma_f32 v[112:113], v[4:5], v[96:97], v[112:113]
	v_pk_fma_f32 v[114:115], v[6:7], v[98:99], v[114:115]
	global_store_dwordx4 v[172:173], v[112:115], off offset:128
	s_waitcnt vmcnt(11)
	v_pk_fma_f32 v[116:117], v[8:9], v[100:101], v[116:117]
	v_pk_fma_f32 v[118:119], v[10:11], v[102:103], v[118:119]
	global_store_dwordx4 v[172:173], v[116:119], off offset:160
	s_waitcnt vmcnt(11)
	v_pk_fma_f32 v[120:121], v[12:13], v[104:105], v[120:121]
	v_pk_fma_f32 v[122:123], v[14:15], v[106:107], v[122:123]
	global_store_dwordx4 v[172:173], v[120:123], off offset:192
	s_waitcnt vmcnt(11)
	v_pk_fma_f32 v[124:125], v[16:17], v[108:109], v[124:125]
	v_pk_fma_f32 v[126:127], v[18:19], v[110:111], v[126:127]
	global_store_dwordx4 v[172:173], v[124:127], off offset:224
	s_load_dword s0, s[62:63], 0x0
	s_waitcnt lgkmcnt(0)
	s_add_i32 s36, s0, s36
	s_cmpk_gt_i32 s36, 0x1ff
	s_cbranch_scc1 .LBB0_589
